# MLA: the next tile's first K-fragment reads (and tile loads) are issued in front of the max-chain tail of the current tile
# speedup vs baseline: 1.0011x; 1.0011x over previous
; __device__ __forceinline__ void finishSM9(f32x16& p0, f32x16& p1, float alpha, float& l_reg, v8i32& p8) {
; #pragma unroll
;   for (int r = 0; r < 16; ++r) { p0[r] = __builtin_amdgcn_exp2f(p0[r]); p1[r] = __builtin_amdgcn_exp2f(p1[r]); }
;   float ps = 0;
; #pragma unroll
;   for (int r = 0; r < 16; ++r) ps += p0[r];
; #pragma unroll
;   for (int r = 0; r < 16; ++r) ps += p1[r];
;   { auto rr = __builtin_amdgcn_permlane32_swap(__float_as_uint(ps), __float_as_uint(ps), false, false);
;     ps = __uint_as_float(rr[0]) + __uint_as_float(rr[1]); }
;   l_reg = l_reg * alpha + ps;
; #pragma unroll
;   for (int g = 0; g < 4; ++g) {
;     int w = __builtin_amdgcn_cvt_pk_fp8_f32(p0[4 * g], p0[4 * g + 1], 0, false); p8[g] = __builtin_amdgcn_cvt_pk_fp8_f32(p0[4 * g + 2], p0[4 * g + 3], w, true);
;     int u = __builtin_amdgcn_cvt_pk_fp8_f32(p1[4 * g], p1[4 * g + 1], 0, false); p8[4 + g] = __builtin_amdgcn_cvt_pk_fp8_f32(p1[4 * g + 2], p1[4 * g + 3], u, true); }
; }
; __device__ __forceinline__ void pv8(f32x16* o, const char* Vt, const v8i32 p8, int r32, int hi) {
; __device__ __forceinline__ void attn_unit7(const unsigned char* __restrict__ Q8, int ldq, const unsigned char* __restrict__ Kn8, int ldk, const unsigned char* __restrict__ Kr8, ...
;     ...
;   float m_reg = 0.f, l_reg = 0; f32x16 o[4] = {}; v8i32 qf[3];
;   { const unsigned char* Qw = Q8 + (unsigned)((wid * 32 + r32) * ldq + hi * 32);
; #pragma unroll
;     for (int s = 0; s < 3; ++s) qf[s] = cat8(*reinterpret_cast<const v4i32*>(Qw + s * 64), *reinterpret_cast<const v4i32*>(Qw + s * 64 + 16)); }
;   const int vtr = tid >> 2, vtc = tid & 3, vtst = vtr * 64 + ((vtc ^ ((vtr >> 2) & 3)) << 4);
;   const int knr = tid >> 3, knc = tid & 7, knst = KN8SW(knr, knc);
;   const int krr = (tid >> 2) & 63, krc = tid & 3, krst = KR8SW(krr, krc);
;   const bool krw = tid < 256;
;   unsigned vtoff = (unsigned)(tid * 16), knoff = (unsigned)(knr * ldk + knc * 16), kroff = (unsigned)(krr * 64 + krc * 16);
;   v4i32 vt, kn, kr;
;     ...
;   f32x16 pA0, pA1, pB0, pB1; float alA, alB; v8i32 p8;
;   SLOAD(); SWRITE(0); __syncthreads();
;   SLOAD();
;   qkt9(pA0, pA1, Kn_lds, Kr_lds, qf, 7.0f - m_reg, r32, hi); partialSM9(pA0, pA1, m_reg, alA, thr_raw);
;   SWRITE(1); __syncthreads();
;   for (int j = 1; j + 1 < NT; j += 2) {
;     SLOAD();
;     qkt9(pB0, pB1, Kn_lds + 8192, Kr_lds + 4096, qf, 7.0f - m_reg, r32, hi);
.LBB0_1320:
	s_or_b64 exec, exec, s[20:21]
	v_and_b32_e32 v0, 0x3fffffc0, v12
	s_mov_b32 s20, 0x60000
	v_lshl_add_u32 v187, v0, 2, 0
	v_add3_u32 v178, v13, v14, s20
	v_add_u32_e32 v0, v15, v16
	v_mov_b32_e32 v14, v1
	v_mov_b32_e32 v15, v1
	v_and_b32_e32 v184, 63, v12
	v_lshl_add_u64 v[180:181], s[12:13], 0, v[0:1]
	v_mov_b32_e32 v0, v1
	v_mov_b32_e32 v2, v1
	v_mov_b32_e32 v3, v1
	v_mov_b32_e32 v4, v1
	v_mov_b32_e32 v5, v1
	v_mov_b32_e32 v6, v1
	v_mov_b32_e32 v7, v1
	v_mov_b32_e32 v8, v1
	v_mov_b32_e32 v9, v1
	v_mov_b32_e32 v10, v1
	v_mov_b32_e32 v11, v1
	v_mov_b32_e32 v12, v1
	v_mov_b32_e32 v13, v1
	v_mov_b64_e32 v[64:65], v[14:15]
	v_mov_b64_e32 v[48:49], v[14:15]
	v_mov_b64_e32 v[32:33], v[14:15]
	v_mov_b64_e32 v[62:63], v[12:13]
	v_mov_b64_e32 v[60:61], v[10:11]
	v_mov_b64_e32 v[58:59], v[8:9]
	v_mov_b64_e32 v[56:57], v[6:7]
	v_mov_b64_e32 v[54:55], v[4:5]
	v_mov_b64_e32 v[52:53], v[2:3]
	v_mov_b64_e32 v[50:51], v[0:1]
	v_mov_b64_e32 v[46:47], v[12:13]
	v_mov_b64_e32 v[44:45], v[10:11]
	v_mov_b64_e32 v[42:43], v[8:9]
	v_mov_b64_e32 v[40:41], v[6:7]
	v_mov_b64_e32 v[38:39], v[4:5]
	v_mov_b64_e32 v[36:37], v[2:3]
	v_mov_b64_e32 v[34:35], v[0:1]
	v_mov_b64_e32 v[30:31], v[12:13]
	v_mov_b64_e32 v[28:29], v[10:11]
	v_mov_b64_e32 v[26:27], v[8:9]
	v_mov_b64_e32 v[24:25], v[6:7]
	v_mov_b64_e32 v[22:23], v[4:5]
	v_mov_b64_e32 v[20:21], v[2:3]
	v_mov_b64_e32 v[18:19], v[0:1]
	v_mov_b64_e32 v[16:17], v[14:15]
	s_lshl_b32 s29, s29, 8
	v_cmp_gt_u32_e64 s[40:41], 32, v184
	v_lshl_add_u32 v208, v183, 2, v187
	v_lshlrev_b32_e32 v207, 4, v175
	v_add_u32_e32 v176, 0x6000, v174
	v_mov_b32_e32 v209, 0
	s_mov_b32 s30, -1
	v_mov_b64_e32 v[14:15], v[12:13]
	v_mov_b64_e32 v[12:13], v[10:11]
	v_mov_b64_e32 v[10:11], v[8:9]
	v_mov_b64_e32 v[8:9], v[6:7]
	v_mov_b64_e32 v[6:7], v[4:5]
	v_mov_b64_e32 v[4:5], v[2:3]
	v_mov_b64_e32 v[2:3], v[0:1]
	v_add_u32_e32 v176, 0xffffe000, v176
	v_add_u32_e32 v178, 0xfffe0000, v178
	v_sub_f32_e32 v230, 0x40e00000, v217
	v_mov_b32_e32 v231, v230
	v_mov_b32_e32 v232, v230
	v_mov_b32_e32 v233, v230
	v_mov_b32_e32 v234, v230
	v_mov_b32_e32 v235, v230
	v_mov_b32_e32 v236, v230
	v_mov_b32_e32 v237, v230
	v_mov_b32_e32 v238, v230
	v_mov_b32_e32 v239, v230
	v_mov_b32_e32 v240, v230
	v_mov_b32_e32 v241, v230
	v_mov_b32_e32 v242, v230
	v_mov_b32_e32 v243, v230
	v_mov_b32_e32 v244, v230
	v_mov_b32_e32 v245, v230
	s_mov_b32 s30, 0
	s_waitcnt lgkmcnt(0)
	s_barrier
	s_cmp_eq_u64 s[42:43], 0
	s_cbranch_scc1 .Lmla_stag_entry
	global_load_dwordx4 v[158:161], v176, s[18:19]
	global_load_dwordx4 v[162:165], v178, s[16:17]
	global_load_dwordx4 v[154:157], v[180:181], off
	ds_read_b128 v[114:117], v215 offset:24576
	ds_read_b128 v[118:121], v216 offset:24576
	ds_read_b128 v[222:225], v215 offset:28672
	ds_read_b128 v[226:229], v216 offset:28672
	v_add_u32_e32 v176, 0x2000, v176
	v_add_u32_e32 v178, 0x20000, v178
	s_mov_b64 s[20:21], 0x1000
	v_lshl_add_u64 v[180:181], v[180:181], 0, s[20:21]
.LBB0_1321:
	v_exp_f32_e32 v0, v82
	v_exp_f32_e32 v177, v83
	v_exp_f32_e32 v179, v84
	v_exp_f32_e32 v254, v85
	v_add_f32_e32 v219, v0, v177
	v_cvt_pk_fp8_f32 v246, v0, v177
	v_add_f32_e32 v219, v179, v219
	v_add_f32_e32 v219, v254, v219
	v_cvt_pk_fp8_f32 v246, v179, v254 op_sel:[0,0,1]
	s_waitcnt lgkmcnt(2)
	v_mfma_scale_f32_32x32x64_f8f6f4 v[114:129], v[114:121], v[146:153], v[230:245], v194, v193 op_sel_hi:[0,0,0]
	v_exp_f32_e32 v0, v86
	v_exp_f32_e32 v177, v87
	v_exp_f32_e32 v179, v88
	v_exp_f32_e32 v254, v89
	v_add_f32_e32 v219, v0, v219
	v_add_f32_e32 v219, v177, v219
	v_cvt_pk_fp8_f32 v247, v0, v177
	v_add_f32_e32 v219, v179, v219
	v_add_f32_e32 v219, v254, v219
	v_cvt_pk_fp8_f32 v247, v179, v254 op_sel:[0,0,1]
	ds_read_b128 v[82:85], v213 offset:24576
	ds_read_b128 v[86:89], v214 offset:24576
	s_waitcnt lgkmcnt(2)
	v_mfma_scale_f32_32x32x64_f8f6f4 v[98:113], v[222:229], v[146:153], v[230:245], v194, v193 op_sel_hi:[0,0,0]
	ds_read_b128 v[222:225], v213 offset:28672
	ds_read_b128 v[226:229], v214 offset:28672
	v_exp_f32_e32 v0, v90
	v_exp_f32_e32 v177, v91
	v_exp_f32_e32 v179, v92
	v_exp_f32_e32 v254, v93
	v_add_f32_e32 v219, v0, v219
	v_add_f32_e32 v219, v177, v219
	v_cvt_pk_fp8_f32 v248, v0, v177
	v_add_f32_e32 v219, v179, v219
	v_add_f32_e32 v219, v254, v219
	v_cvt_pk_fp8_f32 v248, v179, v254 op_sel:[0,0,1]
	v_exp_f32_e32 v0, v94
	v_exp_f32_e32 v177, v95
	v_exp_f32_e32 v179, v96
	v_exp_f32_e32 v254, v97
	v_add_f32_e32 v219, v0, v219
	v_add_f32_e32 v219, v177, v219
	v_cvt_pk_fp8_f32 v249, v0, v177
	v_add_f32_e32 v219, v179, v219
	v_add_f32_e32 v219, v254, v219
	v_cvt_pk_fp8_f32 v249, v179, v254 op_sel:[0,0,1]
	ds_read_b128 v[90:93], v185 offset:36864
	ds_read_b128 v[94:97], v186 offset:36864
	s_waitcnt lgkmcnt(4)
	v_mfma_scale_f32_32x32x64_f8f6f4 v[114:129], v[82:89], v[138:145], v[114:129], v194, v193 op_sel_hi:[0,0,0]
	v_exp_f32_e32 v0, v66
	v_exp_f32_e32 v177, v67
	v_exp_f32_e32 v179, v68
	v_exp_f32_e32 v254, v69
	v_add_f32_e32 v219, v0, v219
	v_add_f32_e32 v219, v177, v219
	v_cvt_pk_fp8_f32 v250, v0, v177
	v_add_f32_e32 v219, v179, v219
	v_add_f32_e32 v219, v254, v219
	v_cvt_pk_fp8_f32 v250, v179, v254 op_sel:[0,0,1]
	s_waitcnt lgkmcnt(2)
	v_mfma_scale_f32_32x32x64_f8f6f4 v[98:113], v[222:229], v[138:145], v[98:113], v194, v193 op_sel_hi:[0,0,0]
	ds_read_b128 v[222:225], v185 offset:38912
	ds_read_b128 v[226:229], v186 offset:38912
	v_exp_f32_e32 v0, v70
	v_exp_f32_e32 v177, v71
	v_exp_f32_e32 v179, v72
	v_exp_f32_e32 v254, v73
	v_add_f32_e32 v219, v0, v219
	v_add_f32_e32 v219, v177, v219
	v_cvt_pk_fp8_f32 v251, v0, v177
	v_add_f32_e32 v219, v179, v219
	v_add_f32_e32 v219, v254, v219
	v_cvt_pk_fp8_f32 v251, v179, v254 op_sel:[0,0,1]
	v_exp_f32_e32 v0, v74
	v_exp_f32_e32 v177, v75
	v_exp_f32_e32 v179, v76
	v_exp_f32_e32 v254, v77
	v_add_f32_e32 v219, v0, v219
	v_add_f32_e32 v219, v177, v219
	v_cvt_pk_fp8_f32 v252, v0, v177
	v_add_f32_e32 v219, v179, v219
	v_add_f32_e32 v219, v254, v219
	v_cvt_pk_fp8_f32 v252, v179, v254 op_sel:[0,0,1]
	s_waitcnt lgkmcnt(2)
; __device__ __forceinline__ void finishSM9(f32x16& p0, f32x16& p1, float alpha, float& l_reg, v8i32& p8) {
; #pragma unroll
;   for (int r = 0; r < 16; ++r) { p0[r] = __builtin_amdgcn_exp2f(p0[r]); p1[r] = __builtin_amdgcn_exp2f(p1[r]); }
;   float ps = 0;
; #pragma unroll
;   for (int r = 0; r < 16; ++r) ps += p0[r];
; #pragma unroll
;   for (int r = 0; r < 16; ++r) ps += p1[r];
;   { auto rr = __builtin_amdgcn_permlane32_swap(__float_as_uint(ps), __float_as_uint(ps), false, false);
;     ps = __uint_as_float(rr[0]) + __uint_as_float(rr[1]); }
;   l_reg = l_reg * alpha + ps;
; #pragma unroll
;   for (int g = 0; g < 4; ++g) {
;     int w = __builtin_amdgcn_cvt_pk_fp8_f32(p0[4 * g], p0[4 * g + 1], 0, false); p8[g] = __builtin_amdgcn_cvt_pk_fp8_f32(p0[4 * g + 2], p0[4 * g + 3], w, true);
;     int u = __builtin_amdgcn_cvt_pk_fp8_f32(p1[4 * g], p1[4 * g + 1], 0, false); p8[4 + g] = __builtin_amdgcn_cvt_pk_fp8_f32(p1[4 * g + 2], p1[4 * g + 3], u, true); }
; }
; __device__ __forceinline__ void pv8(f32x16* o, const char* Vt, const v8i32 p8, int r32, int hi) {
;   const int sw = (r32 >> 2) & 3, a0 = r32 * 64 + (((hi * 2) ^ sw) << 4), a1 = r32 * 64 + (((hi * 2 + 1) ^ sw) << 4);
; #pragma unroll
;   for (int d0 = 0; d0 < 4; ++d0) {
;     const v8i32 vf = cat8(*reinterpret_cast<const v4i32*>(Vt + d0 * 2048 + a0), *reinterpret_cast<const v4i32*>(Vt + d0 * 2048 + a1));
;     o[d0] = __builtin_amdgcn_mfma_scale_f32_32x32x64_f8f6f4(p8, vf, o[d0], 0, 0, 0, 127, 0, 127); }
; }
; __device__ __forceinline__ void qkt9(f32x16& p0, f32x16& p1, const char* Kn, const char* Kr, const v8i32* qf, const float init, int r32, int hi) {
; #pragma unroll
;   for (int r = 0; r < 16; ++r) { p0[r] = init; p1[r] = init; }
; #pragma unroll
;   for (int s = 0; s < 2; ++s) { const int c0 = s * 4 + hi * 2;
;     const v8i32 a0 = cat8(*reinterpret_cast<const v4i32*>(Kn + KN8SW(r32, c0)), *reinterpret_cast<const v4i32*>(Kn + KN8SW(r32, c0 + 1)));
;     const v8i32 a1 = cat8(*reinterpret_cast<const v4i32*>(Kn + 4096 + KN8SW(r32, c0)), *reinterpret_cast<const v4i32*>(Kn + 4096 + KN8SW(r32, c0 + 1)));
;     p0 = __builtin_amdgcn_mfma_scale_f32_32x32x64_f8f6f4(a0, qf[s], p0, 0, 0, 0, 127, 0, 124);
;     p1 = __builtin_amdgcn_mfma_scale_f32_32x32x64_f8f6f4(a1, qf[s], p1, 0, 0, 0, 127, 0, 124); }
;   { const int c0 = hi * 2;
	v_mfma_scale_f32_32x32x64_f8f6f4 v[114:129], v[90:97], v[130:137], v[114:129], v194, v193 op_sel_hi:[0,0,0]
	v_exp_f32_e32 v0, v78
	v_exp_f32_e32 v177, v79
	v_exp_f32_e32 v179, v80
	v_exp_f32_e32 v254, v81
	v_add_f32_e32 v219, v0, v219
	v_add_f32_e32 v219, v177, v219
	v_cvt_pk_fp8_f32 v253, v0, v177
	v_add_f32_e32 v219, v179, v219
	v_add_f32_e32 v219, v254, v219
	v_cvt_pk_fp8_f32 v253, v179, v254 op_sel:[0,0,1]
	ds_read_b128 v[90:93], v185 offset:0
	ds_read_b128 v[94:97], v186 offset:0
	ds_read_b128 v[82:85], v185 offset:2048
	ds_read_b128 v[86:89], v186 offset:2048
	ds_read_b128 v[74:77], v185 offset:4096
	ds_read_b128 v[78:81], v186 offset:4096
	ds_read_b128 v[66:69], v185 offset:6144
	ds_read_b128 v[70:73], v186 offset:6144
	s_waitcnt lgkmcnt(8)
	v_mfma_scale_f32_32x32x64_f8f6f4 v[98:113], v[222:229], v[130:137], v[98:113], v194, v193 op_sel_hi:[0,0,0]
	v_mov_b32_e32 v0, v219
	s_nop 1
	v_permlane32_swap_b32_e32 v219, v0
	v_add_f32_e32 v219, v219, v0
	v_fma_f32 v209, v209, v218, v219
	v_max_f32_e32 v177, v114, v115
	v_max3_f32 v177, v177, v116, v117
	v_max3_f32 v177, v177, v118, v119
	v_max3_f32 v177, v177, v120, v121
	v_max3_f32 v177, v177, v122, v123
	v_max3_f32 v177, v177, v124, v125
	v_max3_f32 v177, v177, v126, v127
	v_max3_f32 v177, v177, v128, v129
	s_waitcnt lgkmcnt(6)
	v_mfma_scale_f32_32x32x64_f8f6f4 v[50:65], v[246:253], v[90:97], v[50:65], v194, v194 op_sel_hi:[0,0,0]
	s_waitcnt lgkmcnt(4)
	v_mfma_scale_f32_32x32x64_f8f6f4 v[34:49], v[246:253], v[82:89], v[34:49], v194, v194 op_sel_hi:[0,0,0]
	s_waitcnt lgkmcnt(2)
	v_mfma_scale_f32_32x32x64_f8f6f4 v[18:33], v[246:253], v[74:81], v[18:33], v194, v194 op_sel_hi:[0,0,0]
	s_waitcnt vmcnt(0)
	ds_write_b128 v210, v[158:161] offset:43008
	ds_write_b128 v211, v[162:165] offset:51200
	ds_write_b128 v212, v[154:157] offset:59392
	s_waitcnt lgkmcnt(3)
	v_mfma_scale_f32_32x32x64_f8f6f4 v[2:17], v[246:253], v[66:73], v[2:17], v194, v194 op_sel_hi:[0,0,0]
	s_waitcnt lgkmcnt(0)
	s_barrier
	global_load_dwordx4 v[158:161], v176, s[18:19]
	global_load_dwordx4 v[162:165], v178, s[16:17]
	global_load_dwordx4 v[154:157], v[180:181], off
	ds_read_b128 v[82:85], v215 offset:51200
	ds_read_b128 v[86:89], v216 offset:51200
	ds_read_b128 v[222:225], v215 offset:55296
	ds_read_b128 v[226:229], v216 offset:55296
	v_add_u32_e32 v176, 0x2000, v176
	v_add_u32_e32 v178, 0x20000, v178
	s_mov_b64 s[20:21], 0x1000
	v_lshl_add_u64 v[180:181], v[180:181], 0, s[20:21]
	v_max_f32_e32 v0, v98, v99
	v_max3_f32 v0, v0, v100, v101
	v_max3_f32 v0, v0, v102, v103
	v_max3_f32 v0, v0, v104, v105
	v_max3_f32 v0, v0, v106, v107
	v_max3_f32 v0, v0, v108, v109
	v_max3_f32 v0, v0, v110, v111
	v_max3_f32 v0, v0, v112, v113
	v_max_f32_e32 v177, v177, v0
	v_mov_b32_e32 v0, v177
	v_mov_b32_e32 v221, 1.0
	s_nop 0
	v_permlane32_swap_b32_e32 v177, v0
	v_max_f32_e32 v177, v177, v0
	v_cmp_ge_f32_e32 vcc, s90, v177
	s_cmp_eq_u64 vcc, exec
	s_cbranch_scc0 .Lmla_h0_newmax
.Lmla_h0_cont:
	v_exp_f32_e32 v0, v114
	v_exp_f32_e32 v177, v115
	v_exp_f32_e32 v179, v116
	v_exp_f32_e32 v254, v117
	v_add_f32_e32 v219, v0, v177
	v_cvt_pk_fp8_f32 v246, v0, v177
	v_add_f32_e32 v219, v179, v219
	v_add_f32_e32 v219, v254, v219
	v_cvt_pk_fp8_f32 v246, v179, v254 op_sel:[0,0,1]
	s_waitcnt lgkmcnt(2)
	v_mfma_scale_f32_32x32x64_f8f6f4 v[82:97], v[82:89], v[146:153], v[230:245], v194, v193 op_sel_hi:[0,0,0]
	v_exp_f32_e32 v0, v118
	v_exp_f32_e32 v177, v119
	v_exp_f32_e32 v179, v120
	v_exp_f32_e32 v254, v121
	v_add_f32_e32 v219, v0, v219
	v_add_f32_e32 v219, v177, v219
	v_cvt_pk_fp8_f32 v247, v0, v177
	v_add_f32_e32 v219, v179, v219
	v_add_f32_e32 v219, v254, v219
	v_cvt_pk_fp8_f32 v247, v179, v254 op_sel:[0,0,1]
	ds_read_b128 v[114:117], v213 offset:51200
	ds_read_b128 v[118:121], v214 offset:51200
	s_waitcnt lgkmcnt(2)
	v_mfma_scale_f32_32x32x64_f8f6f4 v[66:81], v[222:229], v[146:153], v[230:245], v194, v193 op_sel_hi:[0,0,0]
	ds_read_b128 v[222:225], v213 offset:55296
	ds_read_b128 v[226:229], v214 offset:55296
	v_exp_f32_e32 v0, v122
	v_exp_f32_e32 v177, v123
	v_exp_f32_e32 v179, v124
	v_exp_f32_e32 v254, v125
	v_add_f32_e32 v219, v0, v219
	v_add_f32_e32 v219, v177, v219
	v_cvt_pk_fp8_f32 v248, v0, v177
	v_add_f32_e32 v219, v179, v219
	v_add_f32_e32 v219, v254, v219
	v_cvt_pk_fp8_f32 v248, v179, v254 op_sel:[0,0,1]
	v_exp_f32_e32 v0, v126
	v_exp_f32_e32 v177, v127
	v_exp_f32_e32 v179, v128
	v_exp_f32_e32 v254, v129
	v_add_f32_e32 v219, v0, v219
	v_add_f32_e32 v219, v177, v219
	v_cvt_pk_fp8_f32 v249, v0, v177
	v_add_f32_e32 v219, v179, v219
	v_add_f32_e32 v219, v254, v219
	v_cvt_pk_fp8_f32 v249, v179, v254 op_sel:[0,0,1]
	ds_read_b128 v[122:125], v185 offset:59392
	ds_read_b128 v[126:129], v186 offset:59392
	s_waitcnt lgkmcnt(4)
	v_mfma_scale_f32_32x32x64_f8f6f4 v[82:97], v[114:121], v[138:145], v[82:97], v194, v193 op_sel_hi:[0,0,0]
	v_exp_f32_e32 v0, v98
	v_exp_f32_e32 v177, v99
	v_exp_f32_e32 v179, v100
	v_exp_f32_e32 v254, v101
	v_add_f32_e32 v219, v0, v219
	v_add_f32_e32 v219, v177, v219
	v_cvt_pk_fp8_f32 v250, v0, v177
	v_add_f32_e32 v219, v179, v219
	v_add_f32_e32 v219, v254, v219
	v_cvt_pk_fp8_f32 v250, v179, v254 op_sel:[0,0,1]
	s_waitcnt lgkmcnt(2)
	v_mfma_scale_f32_32x32x64_f8f6f4 v[66:81], v[222:229], v[138:145], v[66:81], v194, v193 op_sel_hi:[0,0,0]
	ds_read_b128 v[222:225], v185 offset:61440
	ds_read_b128 v[226:229], v186 offset:61440
	v_exp_f32_e32 v0, v102
	v_exp_f32_e32 v177, v103
	v_exp_f32_e32 v179, v104
	v_exp_f32_e32 v254, v105
	v_add_f32_e32 v219, v0, v219
	v_add_f32_e32 v219, v177, v219
	v_cvt_pk_fp8_f32 v251, v0, v177
	v_add_f32_e32 v219, v179, v219
	v_add_f32_e32 v219, v254, v219
	v_cvt_pk_fp8_f32 v251, v179, v254 op_sel:[0,0,1]
	v_exp_f32_e32 v0, v106
	v_exp_f32_e32 v177, v107
	v_exp_f32_e32 v179, v108
	v_exp_f32_e32 v254, v109
	v_add_f32_e32 v219, v0, v219
	v_add_f32_e32 v219, v177, v219
	v_cvt_pk_fp8_f32 v252, v0, v177
	v_add_f32_e32 v219, v179, v219
	v_add_f32_e32 v219, v254, v219
	v_cvt_pk_fp8_f32 v252, v179, v254 op_sel:[0,0,1]
	s_waitcnt lgkmcnt(2)
; __device__ __forceinline__ void finishSM9(f32x16& p0, f32x16& p1, float alpha, float& l_reg, v8i32& p8) {
; #pragma unroll
;   for (int r = 0; r < 16; ++r) { p0[r] = __builtin_amdgcn_exp2f(p0[r]); p1[r] = __builtin_amdgcn_exp2f(p1[r]); }
;   float ps = 0;
; #pragma unroll
;   for (int r = 0; r < 16; ++r) ps += p0[r];
; #pragma unroll
;   for (int r = 0; r < 16; ++r) ps += p1[r];
;   { auto rr = __builtin_amdgcn_permlane32_swap(__float_as_uint(ps), __float_as_uint(ps), false, false);
;     ps = __uint_as_float(rr[0]) + __uint_as_float(rr[1]); }
;   l_reg = l_reg * alpha + ps;
; #pragma unroll
;   for (int g = 0; g < 4; ++g) {
;     int w = __builtin_amdgcn_cvt_pk_fp8_f32(p0[4 * g], p0[4 * g + 1], 0, false); p8[g] = __builtin_amdgcn_cvt_pk_fp8_f32(p0[4 * g + 2], p0[4 * g + 3], w, true);
;     int u = __builtin_amdgcn_cvt_pk_fp8_f32(p1[4 * g], p1[4 * g + 1], 0, false); p8[4 + g] = __builtin_amdgcn_cvt_pk_fp8_f32(p1[4 * g + 2], p1[4 * g + 3], u, true); }
; }
; __device__ __forceinline__ void pv8(f32x16* o, const char* Vt, const v8i32 p8, int r32, int hi) {
;   const int sw = (r32 >> 2) & 3, a0 = r32 * 64 + (((hi * 2) ^ sw) << 4), a1 = r32 * 64 + (((hi * 2 + 1) ^ sw) << 4);
; #pragma unroll
;   for (int d0 = 0; d0 < 4; ++d0) {
;     const v8i32 vf = cat8(*reinterpret_cast<const v4i32*>(Vt + d0 * 2048 + a0), *reinterpret_cast<const v4i32*>(Vt + d0 * 2048 + a1));
;     o[d0] = __builtin_amdgcn_mfma_scale_f32_32x32x64_f8f6f4(p8, vf, o[d0], 0, 0, 0, 127, 0, 127); }
; }
; __device__ __forceinline__ void qkt9(f32x16& p0, f32x16& p1, const char* Kn, const char* Kr, const v8i32* qf, const float init, int r32, int hi) {
; #pragma unroll
;   for (int r = 0; r < 16; ++r) { p0[r] = init; p1[r] = init; }
; #pragma unroll
;   for (int s = 0; s < 2; ++s) { const int c0 = s * 4 + hi * 2;
;     const v8i32 a0 = cat8(*reinterpret_cast<const v4i32*>(Kn + KN8SW(r32, c0)), *reinterpret_cast<const v4i32*>(Kn + KN8SW(r32, c0 + 1)));
;     const v8i32 a1 = cat8(*reinterpret_cast<const v4i32*>(Kn + 4096 + KN8SW(r32, c0)), *reinterpret_cast<const v4i32*>(Kn + 4096 + KN8SW(r32, c0 + 1)));
;     p0 = __builtin_amdgcn_mfma_scale_f32_32x32x64_f8f6f4(a0, qf[s], p0, 0, 0, 0, 127, 0, 124);
;     p1 = __builtin_amdgcn_mfma_scale_f32_32x32x64_f8f6f4(a1, qf[s], p1, 0, 0, 0, 127, 0, 124); }
;   { const int c0 = hi * 2;
	v_mfma_scale_f32_32x32x64_f8f6f4 v[82:97], v[122:129], v[130:137], v[82:97], v194, v193 op_sel_hi:[0,0,0]
	v_exp_f32_e32 v0, v110
	v_exp_f32_e32 v177, v111
	v_exp_f32_e32 v179, v112
	v_exp_f32_e32 v254, v113
	v_add_f32_e32 v219, v0, v219
	v_add_f32_e32 v219, v177, v219
	v_cvt_pk_fp8_f32 v253, v0, v177
	v_add_f32_e32 v219, v179, v219
	v_add_f32_e32 v219, v254, v219
	v_cvt_pk_fp8_f32 v253, v179, v254 op_sel:[0,0,1]
	ds_read_b128 v[122:125], v185 offset:8192
	ds_read_b128 v[126:129], v186 offset:8192
	ds_read_b128 v[114:117], v185 offset:10240
	ds_read_b128 v[118:121], v186 offset:10240
	ds_read_b128 v[106:109], v185 offset:12288
	ds_read_b128 v[110:113], v186 offset:12288
	ds_read_b128 v[98:101], v185 offset:14336
	ds_read_b128 v[102:105], v186 offset:14336
	s_waitcnt lgkmcnt(8)
	v_mfma_scale_f32_32x32x64_f8f6f4 v[66:81], v[222:229], v[130:137], v[66:81], v194, v193 op_sel_hi:[0,0,0]
	v_mov_b32_e32 v0, v219
	s_nop 1
	v_permlane32_swap_b32_e32 v219, v0
	v_add_f32_e32 v219, v219, v0
	v_fma_f32 v209, v209, v221, v219
	v_max_f32_e32 v177, v82, v83
	v_max3_f32 v177, v177, v84, v85
	v_max3_f32 v177, v177, v86, v87
	v_max3_f32 v177, v177, v88, v89
	v_max3_f32 v177, v177, v90, v91
	v_max3_f32 v177, v177, v92, v93
	v_max3_f32 v177, v177, v94, v95
	v_max3_f32 v177, v177, v96, v97
	s_waitcnt lgkmcnt(6)
	v_mfma_scale_f32_32x32x64_f8f6f4 v[50:65], v[246:253], v[122:129], v[50:65], v194, v194 op_sel_hi:[0,0,0]
	s_waitcnt lgkmcnt(4)
	v_mfma_scale_f32_32x32x64_f8f6f4 v[34:49], v[246:253], v[114:121], v[34:49], v194, v194 op_sel_hi:[0,0,0]
	s_waitcnt lgkmcnt(2)
	v_mfma_scale_f32_32x32x64_f8f6f4 v[18:33], v[246:253], v[106:113], v[18:33], v194, v194 op_sel_hi:[0,0,0]
	s_waitcnt vmcnt(0)
	ds_write_b128 v210, v[158:161]
	ds_write_b128 v211, v[162:165] offset:16384
	ds_write_b128 v212, v[154:157] offset:32768
	s_waitcnt lgkmcnt(3)
	v_mfma_scale_f32_32x32x64_f8f6f4 v[2:17], v[246:253], v[98:105], v[2:17], v194, v194 op_sel_hi:[0,0,0]
	s_waitcnt lgkmcnt(0)
	s_barrier
	global_load_dwordx4 v[158:161], v176, s[18:19]
	global_load_dwordx4 v[162:165], v178, s[16:17]
	global_load_dwordx4 v[154:157], v[180:181], off
	ds_read_b128 v[114:117], v215 offset:16384
	ds_read_b128 v[118:121], v216 offset:16384
	ds_read_b128 v[222:225], v215 offset:20480
	ds_read_b128 v[226:229], v216 offset:20480
	v_add_u32_e32 v176, 0x2000, v176
	v_add_u32_e32 v178, 0x20000, v178
	s_mov_b64 s[20:21], 0x1000
	v_lshl_add_u64 v[180:181], v[180:181], 0, s[20:21]
	v_max_f32_e32 v0, v66, v67
	v_max3_f32 v0, v0, v68, v69
	v_max3_f32 v0, v0, v70, v71
	v_max3_f32 v0, v0, v72, v73
	v_max3_f32 v0, v0, v74, v75
	v_max3_f32 v0, v0, v76, v77
	v_max3_f32 v0, v0, v78, v79
	v_max3_f32 v0, v0, v80, v81
	v_max_f32_e32 v177, v177, v0
	v_mov_b32_e32 v0, v177
	v_mov_b32_e32 v218, 1.0
	s_nop 0
	v_permlane32_swap_b32_e32 v177, v0
	v_max_f32_e32 v177, v177, v0
	v_cmp_ge_f32_e32 vcc, s90, v177
	s_cmp_eq_u64 vcc, exec
	s_cbranch_scc0 .Lmla_h1_newmax
.Lmla_h1_cont:
	v_exp_f32_e32 v0, v82
	v_exp_f32_e32 v177, v83
	v_exp_f32_e32 v179, v84
	v_exp_f32_e32 v254, v85
	v_add_f32_e32 v219, v0, v177
	v_cvt_pk_fp8_f32 v246, v0, v177
	v_add_f32_e32 v219, v179, v219
	v_add_f32_e32 v219, v254, v219
	v_cvt_pk_fp8_f32 v246, v179, v254 op_sel:[0,0,1]
	s_waitcnt lgkmcnt(2)
	v_mfma_scale_f32_32x32x64_f8f6f4 v[114:129], v[114:121], v[146:153], v[230:245], v194, v193 op_sel_hi:[0,0,0]
	v_exp_f32_e32 v0, v86
	v_exp_f32_e32 v177, v87
	v_exp_f32_e32 v179, v88
	v_exp_f32_e32 v254, v89
	v_add_f32_e32 v219, v0, v219
	v_add_f32_e32 v219, v177, v219
	v_cvt_pk_fp8_f32 v247, v0, v177
	v_add_f32_e32 v219, v179, v219
	v_add_f32_e32 v219, v254, v219
	v_cvt_pk_fp8_f32 v247, v179, v254 op_sel:[0,0,1]
	ds_read_b128 v[82:85], v213 offset:16384
	ds_read_b128 v[86:89], v214 offset:16384
	s_waitcnt lgkmcnt(2)
	v_mfma_scale_f32_32x32x64_f8f6f4 v[98:113], v[222:229], v[146:153], v[230:245], v194, v193 op_sel_hi:[0,0,0]
	ds_read_b128 v[222:225], v213 offset:20480
	ds_read_b128 v[226:229], v214 offset:20480
	v_exp_f32_e32 v0, v90
	v_exp_f32_e32 v177, v91
	v_exp_f32_e32 v179, v92
	v_exp_f32_e32 v254, v93
	v_add_f32_e32 v219, v0, v219
	v_add_f32_e32 v219, v177, v219
	v_cvt_pk_fp8_f32 v248, v0, v177
	v_add_f32_e32 v219, v179, v219
	v_add_f32_e32 v219, v254, v219
	v_cvt_pk_fp8_f32 v248, v179, v254 op_sel:[0,0,1]
	v_exp_f32_e32 v0, v94
	v_exp_f32_e32 v177, v95
	v_exp_f32_e32 v179, v96
	v_exp_f32_e32 v254, v97
	v_add_f32_e32 v219, v0, v219
	v_add_f32_e32 v219, v177, v219
	v_cvt_pk_fp8_f32 v249, v0, v177
	v_add_f32_e32 v219, v179, v219
	v_add_f32_e32 v219, v254, v219
	v_cvt_pk_fp8_f32 v249, v179, v254 op_sel:[0,0,1]
	ds_read_b128 v[90:93], v185 offset:32768
	ds_read_b128 v[94:97], v186 offset:32768
	s_waitcnt lgkmcnt(4)
	v_mfma_scale_f32_32x32x64_f8f6f4 v[114:129], v[82:89], v[138:145], v[114:129], v194, v193 op_sel_hi:[0,0,0]
	v_exp_f32_e32 v0, v66
	v_exp_f32_e32 v177, v67
	v_exp_f32_e32 v179, v68
	v_exp_f32_e32 v254, v69
	v_add_f32_e32 v219, v0, v219
	v_add_f32_e32 v219, v177, v219
	v_cvt_pk_fp8_f32 v250, v0, v177
	v_add_f32_e32 v219, v179, v219
	v_add_f32_e32 v219, v254, v219
	v_cvt_pk_fp8_f32 v250, v179, v254 op_sel:[0,0,1]
	s_waitcnt lgkmcnt(2)
	v_mfma_scale_f32_32x32x64_f8f6f4 v[98:113], v[222:229], v[138:145], v[98:113], v194, v193 op_sel_hi:[0,0,0]
	ds_read_b128 v[222:225], v185 offset:34816
	ds_read_b128 v[226:229], v186 offset:34816
	v_exp_f32_e32 v0, v70
	v_exp_f32_e32 v177, v71
	v_exp_f32_e32 v179, v72
	v_exp_f32_e32 v254, v73
	v_add_f32_e32 v219, v0, v219
	v_add_f32_e32 v219, v177, v219
	v_cvt_pk_fp8_f32 v251, v0, v177
	v_add_f32_e32 v219, v179, v219
	v_add_f32_e32 v219, v254, v219
	v_cvt_pk_fp8_f32 v251, v179, v254 op_sel:[0,0,1]
	v_exp_f32_e32 v0, v74
	v_exp_f32_e32 v177, v75
	v_exp_f32_e32 v179, v76
	v_exp_f32_e32 v254, v77
	v_add_f32_e32 v219, v0, v219
	v_add_f32_e32 v219, v177, v219
	v_cvt_pk_fp8_f32 v252, v0, v177
	v_add_f32_e32 v219, v179, v219
	v_add_f32_e32 v219, v254, v219
	v_cvt_pk_fp8_f32 v252, v179, v254 op_sel:[0,0,1]
	s_waitcnt lgkmcnt(2)
; __device__ __forceinline__ void finishSM9(f32x16& p0, f32x16& p1, float alpha, float& l_reg, v8i32& p8) {
; #pragma unroll
;   for (int r = 0; r < 16; ++r) { p0[r] = __builtin_amdgcn_exp2f(p0[r]); p1[r] = __builtin_amdgcn_exp2f(p1[r]); }
;   float ps = 0;
; #pragma unroll
;   for (int r = 0; r < 16; ++r) ps += p0[r];
; #pragma unroll
;   for (int r = 0; r < 16; ++r) ps += p1[r];
;   { auto rr = __builtin_amdgcn_permlane32_swap(__float_as_uint(ps), __float_as_uint(ps), false, false);
;     ps = __uint_as_float(rr[0]) + __uint_as_float(rr[1]); }
;   l_reg = l_reg * alpha + ps;
; #pragma unroll
;   for (int g = 0; g < 4; ++g) {
;     int w = __builtin_amdgcn_cvt_pk_fp8_f32(p0[4 * g], p0[4 * g + 1], 0, false); p8[g] = __builtin_amdgcn_cvt_pk_fp8_f32(p0[4 * g + 2], p0[4 * g + 3], w, true);
;     int u = __builtin_amdgcn_cvt_pk_fp8_f32(p1[4 * g], p1[4 * g + 1], 0, false); p8[4 + g] = __builtin_amdgcn_cvt_pk_fp8_f32(p1[4 * g + 2], p1[4 * g + 3], u, true); }
; }
; __device__ __forceinline__ void pv8(f32x16* o, const char* Vt, const v8i32 p8, int r32, int hi) {
;   const int sw = (r32 >> 2) & 3, a0 = r32 * 64 + (((hi * 2) ^ sw) << 4), a1 = r32 * 64 + (((hi * 2 + 1) ^ sw) << 4);
; #pragma unroll
;   for (int d0 = 0; d0 < 4; ++d0) {
;     const v8i32 vf = cat8(*reinterpret_cast<const v4i32*>(Vt + d0 * 2048 + a0), *reinterpret_cast<const v4i32*>(Vt + d0 * 2048 + a1));
;     o[d0] = __builtin_amdgcn_mfma_scale_f32_32x32x64_f8f6f4(p8, vf, o[d0], 0, 0, 0, 127, 0, 127); }
; }
; __device__ __forceinline__ void qkt9(f32x16& p0, f32x16& p1, const char* Kn, const char* Kr, const v8i32* qf, const float init, int r32, int hi) {
; #pragma unroll
;   for (int r = 0; r < 16; ++r) { p0[r] = init; p1[r] = init; }
; #pragma unroll
;   for (int s = 0; s < 2; ++s) { const int c0 = s * 4 + hi * 2;
;     const v8i32 a0 = cat8(*reinterpret_cast<const v4i32*>(Kn + KN8SW(r32, c0)), *reinterpret_cast<const v4i32*>(Kn + KN8SW(r32, c0 + 1)));
;     const v8i32 a1 = cat8(*reinterpret_cast<const v4i32*>(Kn + 4096 + KN8SW(r32, c0)), *reinterpret_cast<const v4i32*>(Kn + 4096 + KN8SW(r32, c0 + 1)));
;     p0 = __builtin_amdgcn_mfma_scale_f32_32x32x64_f8f6f4(a0, qf[s], p0, 0, 0, 0, 127, 0, 124);
;     p1 = __builtin_amdgcn_mfma_scale_f32_32x32x64_f8f6f4(a1, qf[s], p1, 0, 0, 0, 127, 0, 124); }
;   { const int c0 = hi * 2;
	v_mfma_scale_f32_32x32x64_f8f6f4 v[114:129], v[90:97], v[130:137], v[114:129], v194, v193 op_sel_hi:[0,0,0]
	v_exp_f32_e32 v0, v78
	v_exp_f32_e32 v177, v79
	v_exp_f32_e32 v179, v80
	v_exp_f32_e32 v254, v81
	v_add_f32_e32 v219, v0, v219
	v_add_f32_e32 v219, v177, v219
	v_cvt_pk_fp8_f32 v253, v0, v177
	v_add_f32_e32 v219, v179, v219
	v_add_f32_e32 v219, v254, v219
	v_cvt_pk_fp8_f32 v253, v179, v254 op_sel:[0,0,1]
	ds_read_b128 v[90:93], v185 offset:43008
	ds_read_b128 v[94:97], v186 offset:43008
	ds_read_b128 v[82:85], v185 offset:45056
	ds_read_b128 v[86:89], v186 offset:45056
	ds_read_b128 v[74:77], v185 offset:47104
	ds_read_b128 v[78:81], v186 offset:47104
	ds_read_b128 v[66:69], v185 offset:49152
	ds_read_b128 v[70:73], v186 offset:49152
	s_waitcnt lgkmcnt(8)
	v_mfma_scale_f32_32x32x64_f8f6f4 v[98:113], v[222:229], v[130:137], v[98:113], v194, v193 op_sel_hi:[0,0,0]
	v_mov_b32_e32 v0, v219
	s_nop 1
	v_permlane32_swap_b32_e32 v219, v0
	v_add_f32_e32 v219, v219, v0
	v_fma_f32 v209, v209, v218, v219
	v_max_f32_e32 v177, v114, v115
	v_max3_f32 v177, v177, v116, v117
	v_max3_f32 v177, v177, v118, v119
	v_max3_f32 v177, v177, v120, v121
	v_max3_f32 v177, v177, v122, v123
	v_max3_f32 v177, v177, v124, v125
	v_max3_f32 v177, v177, v126, v127
	v_max3_f32 v177, v177, v128, v129
	s_waitcnt lgkmcnt(6)
	v_mfma_scale_f32_32x32x64_f8f6f4 v[50:65], v[246:253], v[90:97], v[50:65], v194, v194 op_sel_hi:[0,0,0]
	s_waitcnt lgkmcnt(4)
	v_mfma_scale_f32_32x32x64_f8f6f4 v[34:49], v[246:253], v[82:89], v[34:49], v194, v194 op_sel_hi:[0,0,0]
	s_waitcnt lgkmcnt(2)
	v_mfma_scale_f32_32x32x64_f8f6f4 v[18:33], v[246:253], v[74:81], v[18:33], v194, v194 op_sel_hi:[0,0,0]
	s_waitcnt vmcnt(0)
	ds_write_b128 v210, v[158:161] offset:8192
	ds_write_b128 v211, v[162:165] offset:24576
	ds_write_b128 v212, v[154:157] offset:36864
	s_waitcnt lgkmcnt(3)
	v_mfma_scale_f32_32x32x64_f8f6f4 v[2:17], v[246:253], v[66:73], v[2:17], v194, v194 op_sel_hi:[0,0,0]
	s_waitcnt lgkmcnt(0)
	s_barrier
	global_load_dwordx4 v[158:161], v176, s[18:19]
	global_load_dwordx4 v[162:165], v178, s[16:17]
	global_load_dwordx4 v[154:157], v[180:181], off
	ds_read_b128 v[82:85], v215 offset:24576
	ds_read_b128 v[86:89], v216 offset:24576
	ds_read_b128 v[222:225], v215 offset:28672
	ds_read_b128 v[226:229], v216 offset:28672
	v_add_u32_e32 v176, 0x2000, v176
	v_add_u32_e32 v178, 0x20000, v178
	s_mov_b64 s[20:21], 0x1000
	v_lshl_add_u64 v[180:181], v[180:181], 0, s[20:21]
	v_max_f32_e32 v0, v98, v99
	v_max3_f32 v0, v0, v100, v101
	v_max3_f32 v0, v0, v102, v103
	v_max3_f32 v0, v0, v104, v105
	v_max3_f32 v0, v0, v106, v107
	v_max3_f32 v0, v0, v108, v109
	v_max3_f32 v0, v0, v110, v111
	v_max3_f32 v0, v0, v112, v113
	v_max_f32_e32 v177, v177, v0
	v_mov_b32_e32 v0, v177
	v_mov_b32_e32 v221, 1.0
	s_nop 0
	v_permlane32_swap_b32_e32 v177, v0
	v_max_f32_e32 v177, v177, v0
	v_cmp_ge_f32_e32 vcc, s90, v177
	s_cmp_eq_u64 vcc, exec
	s_cbranch_scc0 .Lmla_h2_newmax
.Lmla_h2_cont:
	v_exp_f32_e32 v0, v114
	v_exp_f32_e32 v177, v115
	v_exp_f32_e32 v179, v116
	v_exp_f32_e32 v254, v117
	v_add_f32_e32 v219, v0, v177
	v_cvt_pk_fp8_f32 v246, v0, v177
	v_add_f32_e32 v219, v179, v219
	v_add_f32_e32 v219, v254, v219
	v_cvt_pk_fp8_f32 v246, v179, v254 op_sel:[0,0,1]
	s_waitcnt lgkmcnt(2)
	v_mfma_scale_f32_32x32x64_f8f6f4 v[82:97], v[82:89], v[146:153], v[230:245], v194, v193 op_sel_hi:[0,0,0]
	v_exp_f32_e32 v0, v118
	v_exp_f32_e32 v177, v119
	v_exp_f32_e32 v179, v120
	v_exp_f32_e32 v254, v121
	v_add_f32_e32 v219, v0, v219
	v_add_f32_e32 v219, v177, v219
	v_cvt_pk_fp8_f32 v247, v0, v177
	v_add_f32_e32 v219, v179, v219
	v_add_f32_e32 v219, v254, v219
	v_cvt_pk_fp8_f32 v247, v179, v254 op_sel:[0,0,1]
	ds_read_b128 v[114:117], v213 offset:24576
	ds_read_b128 v[118:121], v214 offset:24576
	s_waitcnt lgkmcnt(2)
	v_mfma_scale_f32_32x32x64_f8f6f4 v[66:81], v[222:229], v[146:153], v[230:245], v194, v193 op_sel_hi:[0,0,0]
	ds_read_b128 v[222:225], v213 offset:28672
	ds_read_b128 v[226:229], v214 offset:28672
	v_exp_f32_e32 v0, v122
	v_exp_f32_e32 v177, v123
	v_exp_f32_e32 v179, v124
	v_exp_f32_e32 v254, v125
	v_add_f32_e32 v219, v0, v219
	v_add_f32_e32 v219, v177, v219
	v_cvt_pk_fp8_f32 v248, v0, v177
	v_add_f32_e32 v219, v179, v219
	v_add_f32_e32 v219, v254, v219
	v_cvt_pk_fp8_f32 v248, v179, v254 op_sel:[0,0,1]
	v_exp_f32_e32 v0, v126
	v_exp_f32_e32 v177, v127
	v_exp_f32_e32 v179, v128
	v_exp_f32_e32 v254, v129
	v_add_f32_e32 v219, v0, v219
	v_add_f32_e32 v219, v177, v219
	v_cvt_pk_fp8_f32 v249, v0, v177
	v_add_f32_e32 v219, v179, v219
	v_add_f32_e32 v219, v254, v219
	v_cvt_pk_fp8_f32 v249, v179, v254 op_sel:[0,0,1]
	ds_read_b128 v[122:125], v185 offset:36864
	ds_read_b128 v[126:129], v186 offset:36864
	s_waitcnt lgkmcnt(4)
	v_mfma_scale_f32_32x32x64_f8f6f4 v[82:97], v[114:121], v[138:145], v[82:97], v194, v193 op_sel_hi:[0,0,0]
	v_exp_f32_e32 v0, v98
	v_exp_f32_e32 v177, v99
	v_exp_f32_e32 v179, v100
	v_exp_f32_e32 v254, v101
	v_add_f32_e32 v219, v0, v219
	v_add_f32_e32 v219, v177, v219
	v_cvt_pk_fp8_f32 v250, v0, v177
	v_add_f32_e32 v219, v179, v219
	v_add_f32_e32 v219, v254, v219
	v_cvt_pk_fp8_f32 v250, v179, v254 op_sel:[0,0,1]
	s_waitcnt lgkmcnt(2)
	v_mfma_scale_f32_32x32x64_f8f6f4 v[66:81], v[222:229], v[138:145], v[66:81], v194, v193 op_sel_hi:[0,0,0]
	ds_read_b128 v[222:225], v185 offset:38912
	ds_read_b128 v[226:229], v186 offset:38912
	v_exp_f32_e32 v0, v102
	v_exp_f32_e32 v177, v103
	v_exp_f32_e32 v179, v104
	v_exp_f32_e32 v254, v105
	v_add_f32_e32 v219, v0, v219
	v_add_f32_e32 v219, v177, v219
	v_cvt_pk_fp8_f32 v251, v0, v177
	v_add_f32_e32 v219, v179, v219
	v_add_f32_e32 v219, v254, v219
	v_cvt_pk_fp8_f32 v251, v179, v254 op_sel:[0,0,1]
	v_exp_f32_e32 v0, v106
	v_exp_f32_e32 v177, v107
	v_exp_f32_e32 v179, v108
	v_exp_f32_e32 v254, v109
	v_add_f32_e32 v219, v0, v219
	v_add_f32_e32 v219, v177, v219
	v_cvt_pk_fp8_f32 v252, v0, v177
	v_add_f32_e32 v219, v179, v219
	v_add_f32_e32 v219, v254, v219
	v_cvt_pk_fp8_f32 v252, v179, v254 op_sel:[0,0,1]
	s_waitcnt lgkmcnt(2)
; __device__ __forceinline__ void finishSM9(f32x16& p0, f32x16& p1, float alpha, float& l_reg, v8i32& p8) {
; #pragma unroll
;   for (int r = 0; r < 16; ++r) { p0[r] = __builtin_amdgcn_exp2f(p0[r]); p1[r] = __builtin_amdgcn_exp2f(p1[r]); }
;   float ps = 0;
; #pragma unroll
;   for (int r = 0; r < 16; ++r) ps += p0[r];
; #pragma unroll
;   for (int r = 0; r < 16; ++r) ps += p1[r];
;   { auto rr = __builtin_amdgcn_permlane32_swap(__float_as_uint(ps), __float_as_uint(ps), false, false);
;     ps = __uint_as_float(rr[0]) + __uint_as_float(rr[1]); }
;   l_reg = l_reg * alpha + ps;
; #pragma unroll
;   for (int g = 0; g < 4; ++g) {
;     int w = __builtin_amdgcn_cvt_pk_fp8_f32(p0[4 * g], p0[4 * g + 1], 0, false); p8[g] = __builtin_amdgcn_cvt_pk_fp8_f32(p0[4 * g + 2], p0[4 * g + 3], w, true);
;     int u = __builtin_amdgcn_cvt_pk_fp8_f32(p1[4 * g], p1[4 * g + 1], 0, false); p8[4 + g] = __builtin_amdgcn_cvt_pk_fp8_f32(p1[4 * g + 2], p1[4 * g + 3], u, true); }
; }
; __device__ __forceinline__ void pv8(f32x16* o, const char* Vt, const v8i32 p8, int r32, int hi) {
;   const int sw = (r32 >> 2) & 3, a0 = r32 * 64 + (((hi * 2) ^ sw) << 4), a1 = r32 * 64 + (((hi * 2 + 1) ^ sw) << 4);
; #pragma unroll
;   for (int d0 = 0; d0 < 4; ++d0) {
;     const v8i32 vf = cat8(*reinterpret_cast<const v4i32*>(Vt + d0 * 2048 + a0), *reinterpret_cast<const v4i32*>(Vt + d0 * 2048 + a1));
;     o[d0] = __builtin_amdgcn_mfma_scale_f32_32x32x64_f8f6f4(p8, vf, o[d0], 0, 0, 0, 127, 0, 127); }
; }
; __device__ __forceinline__ void qkt9(f32x16& p0, f32x16& p1, const char* Kn, const char* Kr, const v8i32* qf, const float init, int r32, int hi) {
; #pragma unroll
;   for (int r = 0; r < 16; ++r) { p0[r] = init; p1[r] = init; }
; #pragma unroll
;   for (int s = 0; s < 2; ++s) { const int c0 = s * 4 + hi * 2;
;     const v8i32 a0 = cat8(*reinterpret_cast<const v4i32*>(Kn + KN8SW(r32, c0)), *reinterpret_cast<const v4i32*>(Kn + KN8SW(r32, c0 + 1)));
;     const v8i32 a1 = cat8(*reinterpret_cast<const v4i32*>(Kn + 4096 + KN8SW(r32, c0)), *reinterpret_cast<const v4i32*>(Kn + 4096 + KN8SW(r32, c0 + 1)));
;     p0 = __builtin_amdgcn_mfma_scale_f32_32x32x64_f8f6f4(a0, qf[s], p0, 0, 0, 0, 127, 0, 124);
;     p1 = __builtin_amdgcn_mfma_scale_f32_32x32x64_f8f6f4(a1, qf[s], p1, 0, 0, 0, 127, 0, 124); }
;   { const int c0 = hi * 2;
	v_mfma_scale_f32_32x32x64_f8f6f4 v[82:97], v[122:129], v[130:137], v[82:97], v194, v193 op_sel_hi:[0,0,0]
	v_exp_f32_e32 v0, v110
	v_exp_f32_e32 v177, v111
	v_exp_f32_e32 v179, v112
	v_exp_f32_e32 v254, v113
	v_add_f32_e32 v219, v0, v219
	v_add_f32_e32 v219, v177, v219
	v_cvt_pk_fp8_f32 v253, v0, v177
	v_add_f32_e32 v219, v179, v219
	v_add_f32_e32 v219, v254, v219
	v_cvt_pk_fp8_f32 v253, v179, v254 op_sel:[0,0,1]
	ds_read_b128 v[122:125], v185 offset:0
	ds_read_b128 v[126:129], v186 offset:0
	ds_read_b128 v[114:117], v185 offset:2048
	ds_read_b128 v[118:121], v186 offset:2048
	ds_read_b128 v[106:109], v185 offset:4096
	ds_read_b128 v[110:113], v186 offset:4096
	ds_read_b128 v[98:101], v185 offset:6144
	ds_read_b128 v[102:105], v186 offset:6144
	s_waitcnt lgkmcnt(8)
	v_mfma_scale_f32_32x32x64_f8f6f4 v[66:81], v[222:229], v[130:137], v[66:81], v194, v193 op_sel_hi:[0,0,0]
	v_mov_b32_e32 v0, v219
	s_nop 1
	v_permlane32_swap_b32_e32 v219, v0
	v_add_f32_e32 v219, v219, v0
	v_fma_f32 v209, v209, v221, v219
	v_max_f32_e32 v177, v82, v83
	v_max3_f32 v177, v177, v84, v85
	v_max3_f32 v177, v177, v86, v87
	v_max3_f32 v177, v177, v88, v89
	v_max3_f32 v177, v177, v90, v91
	v_max3_f32 v177, v177, v92, v93
	v_max3_f32 v177, v177, v94, v95
	v_max3_f32 v177, v177, v96, v97
	s_waitcnt lgkmcnt(6)
	v_mfma_scale_f32_32x32x64_f8f6f4 v[50:65], v[246:253], v[122:129], v[50:65], v194, v194 op_sel_hi:[0,0,0]
	s_waitcnt lgkmcnt(4)
	v_mfma_scale_f32_32x32x64_f8f6f4 v[34:49], v[246:253], v[114:121], v[34:49], v194, v194 op_sel_hi:[0,0,0]
	s_waitcnt lgkmcnt(2)
	v_mfma_scale_f32_32x32x64_f8f6f4 v[18:33], v[246:253], v[106:113], v[18:33], v194, v194 op_sel_hi:[0,0,0]
	s_waitcnt vmcnt(0)
	ds_write_b128 v210, v[158:161] offset:43008
	ds_write_b128 v211, v[162:165] offset:51200
	ds_write_b128 v212, v[154:157] offset:59392
	s_waitcnt lgkmcnt(3)
	v_mfma_scale_f32_32x32x64_f8f6f4 v[2:17], v[246:253], v[98:105], v[2:17], v194, v194 op_sel_hi:[0,0,0]
	s_waitcnt lgkmcnt(0)
	s_barrier
	global_load_dwordx4 v[158:161], v176, s[18:19]
	global_load_dwordx4 v[162:165], v178, s[16:17]
	global_load_dwordx4 v[154:157], v[180:181], off
	ds_read_b128 v[114:117], v215 offset:51200
	ds_read_b128 v[118:121], v216 offset:51200
	ds_read_b128 v[222:225], v215 offset:55296
	ds_read_b128 v[226:229], v216 offset:55296
	v_add_u32_e32 v176, 0x2000, v176
	v_add_u32_e32 v178, 0x20000, v178
	s_mov_b64 s[20:21], 0x1000
	v_lshl_add_u64 v[180:181], v[180:181], 0, s[20:21]
	v_max_f32_e32 v0, v66, v67
	v_max3_f32 v0, v0, v68, v69
	v_max3_f32 v0, v0, v70, v71
	v_max3_f32 v0, v0, v72, v73
	v_max3_f32 v0, v0, v74, v75
	v_max3_f32 v0, v0, v76, v77
	v_max3_f32 v0, v0, v78, v79
	v_max3_f32 v0, v0, v80, v81
	v_max_f32_e32 v177, v177, v0
	v_mov_b32_e32 v0, v177
	v_mov_b32_e32 v218, 1.0
	s_nop 0
	v_permlane32_swap_b32_e32 v177, v0
	v_max_f32_e32 v177, v177, v0
	v_cmp_ge_f32_e32 vcc, s90, v177
	s_cmp_eq_u64 vcc, exec
	s_cbranch_scc0 .Lmla_h3_newmax
.Lmla_h3_cont:
	v_exp_f32_e32 v0, v82
	v_exp_f32_e32 v177, v83
	v_exp_f32_e32 v179, v84
	v_exp_f32_e32 v254, v85
	v_add_f32_e32 v219, v0, v177
	v_cvt_pk_fp8_f32 v246, v0, v177
	v_add_f32_e32 v219, v179, v219
	v_add_f32_e32 v219, v254, v219
	v_cvt_pk_fp8_f32 v246, v179, v254 op_sel:[0,0,1]
	s_waitcnt lgkmcnt(2)
	v_mfma_scale_f32_32x32x64_f8f6f4 v[114:129], v[114:121], v[146:153], v[230:245], v194, v193 op_sel_hi:[0,0,0]
	v_exp_f32_e32 v0, v86
	v_exp_f32_e32 v177, v87
	v_exp_f32_e32 v179, v88
	v_exp_f32_e32 v254, v89
	v_add_f32_e32 v219, v0, v219
	v_add_f32_e32 v219, v177, v219
	v_cvt_pk_fp8_f32 v247, v0, v177
	v_add_f32_e32 v219, v179, v219
	v_add_f32_e32 v219, v254, v219
	v_cvt_pk_fp8_f32 v247, v179, v254 op_sel:[0,0,1]
	ds_read_b128 v[82:85], v213 offset:51200
	ds_read_b128 v[86:89], v214 offset:51200
	s_waitcnt lgkmcnt(2)
	v_mfma_scale_f32_32x32x64_f8f6f4 v[98:113], v[222:229], v[146:153], v[230:245], v194, v193 op_sel_hi:[0,0,0]
	ds_read_b128 v[222:225], v213 offset:55296
	ds_read_b128 v[226:229], v214 offset:55296
	v_exp_f32_e32 v0, v90
	v_exp_f32_e32 v177, v91
	v_exp_f32_e32 v179, v92
	v_exp_f32_e32 v254, v93
	v_add_f32_e32 v219, v0, v219
	v_add_f32_e32 v219, v177, v219
	v_cvt_pk_fp8_f32 v248, v0, v177
	v_add_f32_e32 v219, v179, v219
	v_add_f32_e32 v219, v254, v219
	v_cvt_pk_fp8_f32 v248, v179, v254 op_sel:[0,0,1]
	v_exp_f32_e32 v0, v94
	v_exp_f32_e32 v177, v95
	v_exp_f32_e32 v179, v96
	v_exp_f32_e32 v254, v97
	v_add_f32_e32 v219, v0, v219
	v_add_f32_e32 v219, v177, v219
	v_cvt_pk_fp8_f32 v249, v0, v177
	v_add_f32_e32 v219, v179, v219
	v_add_f32_e32 v219, v254, v219
	v_cvt_pk_fp8_f32 v249, v179, v254 op_sel:[0,0,1]
	ds_read_b128 v[90:93], v185 offset:59392
	ds_read_b128 v[94:97], v186 offset:59392
	s_waitcnt lgkmcnt(4)
	v_mfma_scale_f32_32x32x64_f8f6f4 v[114:129], v[82:89], v[138:145], v[114:129], v194, v193 op_sel_hi:[0,0,0]
	v_exp_f32_e32 v0, v66
	v_exp_f32_e32 v177, v67
	v_exp_f32_e32 v179, v68
	v_exp_f32_e32 v254, v69
	v_add_f32_e32 v219, v0, v219
	v_add_f32_e32 v219, v177, v219
	v_cvt_pk_fp8_f32 v250, v0, v177
	v_add_f32_e32 v219, v179, v219
	v_add_f32_e32 v219, v254, v219
	v_cvt_pk_fp8_f32 v250, v179, v254 op_sel:[0,0,1]
	s_waitcnt lgkmcnt(2)
	v_mfma_scale_f32_32x32x64_f8f6f4 v[98:113], v[222:229], v[138:145], v[98:113], v194, v193 op_sel_hi:[0,0,0]
	ds_read_b128 v[222:225], v185 offset:61440
	ds_read_b128 v[226:229], v186 offset:61440
	v_exp_f32_e32 v0, v70
	v_exp_f32_e32 v177, v71
	v_exp_f32_e32 v179, v72
	v_exp_f32_e32 v254, v73
	v_add_f32_e32 v219, v0, v219
	v_add_f32_e32 v219, v177, v219
	v_cvt_pk_fp8_f32 v251, v0, v177
	v_add_f32_e32 v219, v179, v219
	v_add_f32_e32 v219, v254, v219
	v_cvt_pk_fp8_f32 v251, v179, v254 op_sel:[0,0,1]
	v_exp_f32_e32 v0, v74
	v_exp_f32_e32 v177, v75
	v_exp_f32_e32 v179, v76
	v_exp_f32_e32 v254, v77
	v_add_f32_e32 v219, v0, v219
	v_add_f32_e32 v219, v177, v219
	v_cvt_pk_fp8_f32 v252, v0, v177
	v_add_f32_e32 v219, v179, v219
	v_add_f32_e32 v219, v254, v219
	v_cvt_pk_fp8_f32 v252, v179, v254 op_sel:[0,0,1]
	s_waitcnt lgkmcnt(2)
; __device__ __forceinline__ void finishSM9(f32x16& p0, f32x16& p1, float alpha, float& l_reg, v8i32& p8) {
; #pragma unroll
;   for (int r = 0; r < 16; ++r) { p0[r] = __builtin_amdgcn_exp2f(p0[r]); p1[r] = __builtin_amdgcn_exp2f(p1[r]); }
;   float ps = 0;
; #pragma unroll
;   for (int r = 0; r < 16; ++r) ps += p0[r];
; #pragma unroll
;   for (int r = 0; r < 16; ++r) ps += p1[r];
;   { auto rr = __builtin_amdgcn_permlane32_swap(__float_as_uint(ps), __float_as_uint(ps), false, false);
;     ps = __uint_as_float(rr[0]) + __uint_as_float(rr[1]); }
;   l_reg = l_reg * alpha + ps;
; #pragma unroll
;   for (int g = 0; g < 4; ++g) {
;     int w = __builtin_amdgcn_cvt_pk_fp8_f32(p0[4 * g], p0[4 * g + 1], 0, false); p8[g] = __builtin_amdgcn_cvt_pk_fp8_f32(p0[4 * g + 2], p0[4 * g + 3], w, true);
;     int u = __builtin_amdgcn_cvt_pk_fp8_f32(p1[4 * g], p1[4 * g + 1], 0, false); p8[4 + g] = __builtin_amdgcn_cvt_pk_fp8_f32(p1[4 * g + 2], p1[4 * g + 3], u, true); }
; }
; __device__ __forceinline__ void pv8(f32x16* o, const char* Vt, const v8i32 p8, int r32, int hi) {
;   const int sw = (r32 >> 2) & 3, a0 = r32 * 64 + (((hi * 2) ^ sw) << 4), a1 = r32 * 64 + (((hi * 2 + 1) ^ sw) << 4);
; #pragma unroll
;   for (int d0 = 0; d0 < 4; ++d0) {
;     const v8i32 vf = cat8(*reinterpret_cast<const v4i32*>(Vt + d0 * 2048 + a0), *reinterpret_cast<const v4i32*>(Vt + d0 * 2048 + a1));
;     o[d0] = __builtin_amdgcn_mfma_scale_f32_32x32x64_f8f6f4(p8, vf, o[d0], 0, 0, 0, 127, 0, 127); }
; }
; __device__ __forceinline__ void qkt9(f32x16& p0, f32x16& p1, const char* Kn, const char* Kr, const v8i32* qf, const float init, int r32, int hi) {
; #pragma unroll
;   for (int r = 0; r < 16; ++r) { p0[r] = init; p1[r] = init; }
; #pragma unroll
;   for (int s = 0; s < 2; ++s) { const int c0 = s * 4 + hi * 2;
;     const v8i32 a0 = cat8(*reinterpret_cast<const v4i32*>(Kn + KN8SW(r32, c0)), *reinterpret_cast<const v4i32*>(Kn + KN8SW(r32, c0 + 1)));
;     const v8i32 a1 = cat8(*reinterpret_cast<const v4i32*>(Kn + 4096 + KN8SW(r32, c0)), *reinterpret_cast<const v4i32*>(Kn + 4096 + KN8SW(r32, c0 + 1)));
;     p0 = __builtin_amdgcn_mfma_scale_f32_32x32x64_f8f6f4(a0, qf[s], p0, 0, 0, 0, 127, 0, 124);
;     p1 = __builtin_amdgcn_mfma_scale_f32_32x32x64_f8f6f4(a1, qf[s], p1, 0, 0, 0, 127, 0, 124); }
;   { const int c0 = hi * 2;
	v_mfma_scale_f32_32x32x64_f8f6f4 v[114:129], v[90:97], v[130:137], v[114:129], v194, v193 op_sel_hi:[0,0,0]
	v_exp_f32_e32 v0, v78
	v_exp_f32_e32 v177, v79
	v_exp_f32_e32 v179, v80
	v_exp_f32_e32 v254, v81
	v_add_f32_e32 v219, v0, v219
	v_add_f32_e32 v219, v177, v219
	v_cvt_pk_fp8_f32 v253, v0, v177
	v_add_f32_e32 v219, v179, v219
	v_add_f32_e32 v219, v254, v219
	v_cvt_pk_fp8_f32 v253, v179, v254 op_sel:[0,0,1]
	ds_read_b128 v[90:93], v185 offset:8192
	ds_read_b128 v[94:97], v186 offset:8192
	ds_read_b128 v[82:85], v185 offset:10240
	ds_read_b128 v[86:89], v186 offset:10240
	ds_read_b128 v[74:77], v185 offset:12288
	ds_read_b128 v[78:81], v186 offset:12288
	ds_read_b128 v[66:69], v185 offset:14336
	ds_read_b128 v[70:73], v186 offset:14336
	s_waitcnt lgkmcnt(8)
	v_mfma_scale_f32_32x32x64_f8f6f4 v[98:113], v[222:229], v[130:137], v[98:113], v194, v193 op_sel_hi:[0,0,0]
	v_mov_b32_e32 v0, v219
	s_nop 1
	v_permlane32_swap_b32_e32 v219, v0
	v_add_f32_e32 v219, v219, v0
	v_fma_f32 v209, v209, v218, v219
	v_max_f32_e32 v177, v114, v115
	v_max3_f32 v177, v177, v116, v117
	v_max3_f32 v177, v177, v118, v119
	v_max3_f32 v177, v177, v120, v121
	v_max3_f32 v177, v177, v122, v123
	v_max3_f32 v177, v177, v124, v125
	v_max3_f32 v177, v177, v126, v127
	v_max3_f32 v177, v177, v128, v129
	s_waitcnt lgkmcnt(6)
	v_mfma_scale_f32_32x32x64_f8f6f4 v[50:65], v[246:253], v[90:97], v[50:65], v194, v194 op_sel_hi:[0,0,0]
	s_waitcnt lgkmcnt(4)
	v_mfma_scale_f32_32x32x64_f8f6f4 v[34:49], v[246:253], v[82:89], v[34:49], v194, v194 op_sel_hi:[0,0,0]
	s_waitcnt lgkmcnt(2)
	v_mfma_scale_f32_32x32x64_f8f6f4 v[18:33], v[246:253], v[74:81], v[18:33], v194, v194 op_sel_hi:[0,0,0]
	s_waitcnt vmcnt(0)
	ds_write_b128 v210, v[158:161]
	ds_write_b128 v211, v[162:165] offset:16384
	ds_write_b128 v212, v[154:157] offset:32768
	s_waitcnt lgkmcnt(3)
	v_mfma_scale_f32_32x32x64_f8f6f4 v[2:17], v[246:253], v[66:73], v[2:17], v194, v194 op_sel_hi:[0,0,0]
	s_waitcnt lgkmcnt(0)
	s_barrier
	global_load_dwordx4 v[158:161], v176, s[18:19]
	global_load_dwordx4 v[162:165], v178, s[16:17]
	global_load_dwordx4 v[154:157], v[180:181], off
	ds_read_b128 v[82:85], v215 offset:16384
	ds_read_b128 v[86:89], v216 offset:16384
	ds_read_b128 v[222:225], v215 offset:20480
	ds_read_b128 v[226:229], v216 offset:20480
	v_add_u32_e32 v176, 0x2000, v176
	v_add_u32_e32 v178, 0x20000, v178
	s_mov_b64 s[20:21], 0x1000
	v_lshl_add_u64 v[180:181], v[180:181], 0, s[20:21]
	v_max_f32_e32 v0, v98, v99
	v_max3_f32 v0, v0, v100, v101
	v_max3_f32 v0, v0, v102, v103
	v_max3_f32 v0, v0, v104, v105
	v_max3_f32 v0, v0, v106, v107
	v_max3_f32 v0, v0, v108, v109
	v_max3_f32 v0, v0, v110, v111
	v_max3_f32 v0, v0, v112, v113
	v_max_f32_e32 v177, v177, v0
	v_mov_b32_e32 v0, v177
	v_mov_b32_e32 v221, 1.0
	s_nop 0
	v_permlane32_swap_b32_e32 v177, v0
	v_max_f32_e32 v177, v177, v0
	v_cmp_ge_f32_e32 vcc, s90, v177
	s_cmp_eq_u64 vcc, exec
	s_cbranch_scc0 .Lmla_h4_newmax
.Lmla_h4_cont:
	v_exp_f32_e32 v0, v114
	v_exp_f32_e32 v177, v115
	v_exp_f32_e32 v179, v116
	v_exp_f32_e32 v254, v117
	v_add_f32_e32 v219, v0, v177
	v_cvt_pk_fp8_f32 v246, v0, v177
	v_add_f32_e32 v219, v179, v219
	v_add_f32_e32 v219, v254, v219
	v_cvt_pk_fp8_f32 v246, v179, v254 op_sel:[0,0,1]
	s_waitcnt lgkmcnt(2)
	v_mfma_scale_f32_32x32x64_f8f6f4 v[82:97], v[82:89], v[146:153], v[230:245], v194, v193 op_sel_hi:[0,0,0]
	v_exp_f32_e32 v0, v118
	v_exp_f32_e32 v177, v119
	v_exp_f32_e32 v179, v120
	v_exp_f32_e32 v254, v121
	v_add_f32_e32 v219, v0, v219
	v_add_f32_e32 v219, v177, v219
	v_cvt_pk_fp8_f32 v247, v0, v177
	v_add_f32_e32 v219, v179, v219
	v_add_f32_e32 v219, v254, v219
	v_cvt_pk_fp8_f32 v247, v179, v254 op_sel:[0,0,1]
	ds_read_b128 v[114:117], v213 offset:16384
	ds_read_b128 v[118:121], v214 offset:16384
	s_waitcnt lgkmcnt(2)
	v_mfma_scale_f32_32x32x64_f8f6f4 v[66:81], v[222:229], v[146:153], v[230:245], v194, v193 op_sel_hi:[0,0,0]
	ds_read_b128 v[222:225], v213 offset:20480
	ds_read_b128 v[226:229], v214 offset:20480
	v_exp_f32_e32 v0, v122
	v_exp_f32_e32 v177, v123
	v_exp_f32_e32 v179, v124
	v_exp_f32_e32 v254, v125
	v_add_f32_e32 v219, v0, v219
	v_add_f32_e32 v219, v177, v219
	v_cvt_pk_fp8_f32 v248, v0, v177
	v_add_f32_e32 v219, v179, v219
	v_add_f32_e32 v219, v254, v219
	v_cvt_pk_fp8_f32 v248, v179, v254 op_sel:[0,0,1]
	v_exp_f32_e32 v0, v126
	v_exp_f32_e32 v177, v127
	v_exp_f32_e32 v179, v128
	v_exp_f32_e32 v254, v129
	v_add_f32_e32 v219, v0, v219
	v_add_f32_e32 v219, v177, v219
	v_cvt_pk_fp8_f32 v249, v0, v177
	v_add_f32_e32 v219, v179, v219
	v_add_f32_e32 v219, v254, v219
	v_cvt_pk_fp8_f32 v249, v179, v254 op_sel:[0,0,1]
	ds_read_b128 v[122:125], v185 offset:32768
	ds_read_b128 v[126:129], v186 offset:32768
	s_waitcnt lgkmcnt(4)
	v_mfma_scale_f32_32x32x64_f8f6f4 v[82:97], v[114:121], v[138:145], v[82:97], v194, v193 op_sel_hi:[0,0,0]
	v_exp_f32_e32 v0, v98
	v_exp_f32_e32 v177, v99
	v_exp_f32_e32 v179, v100
	v_exp_f32_e32 v254, v101
	v_add_f32_e32 v219, v0, v219
	v_add_f32_e32 v219, v177, v219
	v_cvt_pk_fp8_f32 v250, v0, v177
	v_add_f32_e32 v219, v179, v219
	v_add_f32_e32 v219, v254, v219
	v_cvt_pk_fp8_f32 v250, v179, v254 op_sel:[0,0,1]
	s_waitcnt lgkmcnt(2)
	v_mfma_scale_f32_32x32x64_f8f6f4 v[66:81], v[222:229], v[138:145], v[66:81], v194, v193 op_sel_hi:[0,0,0]
	ds_read_b128 v[222:225], v185 offset:34816
	ds_read_b128 v[226:229], v186 offset:34816
	v_exp_f32_e32 v0, v102
	v_exp_f32_e32 v177, v103
	v_exp_f32_e32 v179, v104
	v_exp_f32_e32 v254, v105
	v_add_f32_e32 v219, v0, v219
	v_add_f32_e32 v219, v177, v219
	v_cvt_pk_fp8_f32 v251, v0, v177
	v_add_f32_e32 v219, v179, v219
	v_add_f32_e32 v219, v254, v219
	v_cvt_pk_fp8_f32 v251, v179, v254 op_sel:[0,0,1]
	v_exp_f32_e32 v0, v106
	v_exp_f32_e32 v177, v107
	v_exp_f32_e32 v179, v108
	v_exp_f32_e32 v254, v109
	v_add_f32_e32 v219, v0, v219
	v_add_f32_e32 v219, v177, v219
	v_cvt_pk_fp8_f32 v252, v0, v177
	v_add_f32_e32 v219, v179, v219
	v_add_f32_e32 v219, v254, v219
	v_cvt_pk_fp8_f32 v252, v179, v254 op_sel:[0,0,1]
	s_waitcnt lgkmcnt(2)
; __device__ __forceinline__ void finishSM9(f32x16& p0, f32x16& p1, float alpha, float& l_reg, v8i32& p8) {
; #pragma unroll
;   for (int r = 0; r < 16; ++r) { p0[r] = __builtin_amdgcn_exp2f(p0[r]); p1[r] = __builtin_amdgcn_exp2f(p1[r]); }
;   float ps = 0;
; #pragma unroll
;   for (int r = 0; r < 16; ++r) ps += p0[r];
; #pragma unroll
;   for (int r = 0; r < 16; ++r) ps += p1[r];
;   { auto rr = __builtin_amdgcn_permlane32_swap(__float_as_uint(ps), __float_as_uint(ps), false, false);
;     ps = __uint_as_float(rr[0]) + __uint_as_float(rr[1]); }
;   l_reg = l_reg * alpha + ps;
; #pragma unroll
;   for (int g = 0; g < 4; ++g) {
;     int w = __builtin_amdgcn_cvt_pk_fp8_f32(p0[4 * g], p0[4 * g + 1], 0, false); p8[g] = __builtin_amdgcn_cvt_pk_fp8_f32(p0[4 * g + 2], p0[4 * g + 3], w, true);
;     int u = __builtin_amdgcn_cvt_pk_fp8_f32(p1[4 * g], p1[4 * g + 1], 0, false); p8[4 + g] = __builtin_amdgcn_cvt_pk_fp8_f32(p1[4 * g + 2], p1[4 * g + 3], u, true); }
; }
; __device__ __forceinline__ void pv8(f32x16* o, const char* Vt, const v8i32 p8, int r32, int hi) {
;   const int sw = (r32 >> 2) & 3, a0 = r32 * 64 + (((hi * 2) ^ sw) << 4), a1 = r32 * 64 + (((hi * 2 + 1) ^ sw) << 4);
; #pragma unroll
;   for (int d0 = 0; d0 < 4; ++d0) {
;     const v8i32 vf = cat8(*reinterpret_cast<const v4i32*>(Vt + d0 * 2048 + a0), *reinterpret_cast<const v4i32*>(Vt + d0 * 2048 + a1));
;     o[d0] = __builtin_amdgcn_mfma_scale_f32_32x32x64_f8f6f4(p8, vf, o[d0], 0, 0, 0, 127, 0, 127); }
; }
; __device__ __forceinline__ void qkt9(f32x16& p0, f32x16& p1, const char* Kn, const char* Kr, const v8i32* qf, const float init, int r32, int hi) {
; #pragma unroll
;   for (int r = 0; r < 16; ++r) { p0[r] = init; p1[r] = init; }
; #pragma unroll
;   for (int s = 0; s < 2; ++s) { const int c0 = s * 4 + hi * 2;
;     const v8i32 a0 = cat8(*reinterpret_cast<const v4i32*>(Kn + KN8SW(r32, c0)), *reinterpret_cast<const v4i32*>(Kn + KN8SW(r32, c0 + 1)));
;     const v8i32 a1 = cat8(*reinterpret_cast<const v4i32*>(Kn + 4096 + KN8SW(r32, c0)), *reinterpret_cast<const v4i32*>(Kn + 4096 + KN8SW(r32, c0 + 1)));
;     p0 = __builtin_amdgcn_mfma_scale_f32_32x32x64_f8f6f4(a0, qf[s], p0, 0, 0, 0, 127, 0, 124);
;     p1 = __builtin_amdgcn_mfma_scale_f32_32x32x64_f8f6f4(a1, qf[s], p1, 0, 0, 0, 127, 0, 124); }
;   { const int c0 = hi * 2;
	v_mfma_scale_f32_32x32x64_f8f6f4 v[82:97], v[122:129], v[130:137], v[82:97], v194, v193 op_sel_hi:[0,0,0]
	v_exp_f32_e32 v0, v110
	v_exp_f32_e32 v177, v111
	v_exp_f32_e32 v179, v112
	v_exp_f32_e32 v254, v113
	v_add_f32_e32 v219, v0, v219
	v_add_f32_e32 v219, v177, v219
	v_cvt_pk_fp8_f32 v253, v0, v177
	v_add_f32_e32 v219, v179, v219
	v_add_f32_e32 v219, v254, v219
	v_cvt_pk_fp8_f32 v253, v179, v254 op_sel:[0,0,1]
	ds_read_b128 v[122:125], v185 offset:43008
	ds_read_b128 v[126:129], v186 offset:43008
	ds_read_b128 v[114:117], v185 offset:45056
	ds_read_b128 v[118:121], v186 offset:45056
	ds_read_b128 v[106:109], v185 offset:47104
	ds_read_b128 v[110:113], v186 offset:47104
	ds_read_b128 v[98:101], v185 offset:49152
	ds_read_b128 v[102:105], v186 offset:49152
	s_waitcnt lgkmcnt(8)
	v_mfma_scale_f32_32x32x64_f8f6f4 v[66:81], v[222:229], v[130:137], v[66:81], v194, v193 op_sel_hi:[0,0,0]
	v_mov_b32_e32 v0, v219
	s_nop 1
	v_permlane32_swap_b32_e32 v219, v0
	v_add_f32_e32 v219, v219, v0
	v_fma_f32 v209, v209, v221, v219
	v_max_f32_e32 v177, v82, v83
	v_max3_f32 v177, v177, v84, v85
	v_max3_f32 v177, v177, v86, v87
	v_max3_f32 v177, v177, v88, v89
	v_max3_f32 v177, v177, v90, v91
	v_max3_f32 v177, v177, v92, v93
	v_max3_f32 v177, v177, v94, v95
	v_max3_f32 v177, v177, v96, v97
	s_waitcnt lgkmcnt(6)
	v_mfma_scale_f32_32x32x64_f8f6f4 v[50:65], v[246:253], v[122:129], v[50:65], v194, v194 op_sel_hi:[0,0,0]
	s_waitcnt lgkmcnt(4)
	v_mfma_scale_f32_32x32x64_f8f6f4 v[34:49], v[246:253], v[114:121], v[34:49], v194, v194 op_sel_hi:[0,0,0]
	s_waitcnt lgkmcnt(2)
	v_mfma_scale_f32_32x32x64_f8f6f4 v[18:33], v[246:253], v[106:113], v[18:33], v194, v194 op_sel_hi:[0,0,0]
	s_waitcnt vmcnt(0)
	ds_write_b128 v210, v[158:161] offset:8192
	ds_write_b128 v211, v[162:165] offset:24576
	ds_write_b128 v212, v[154:157] offset:36864
	s_waitcnt lgkmcnt(3)
	v_mfma_scale_f32_32x32x64_f8f6f4 v[2:17], v[246:253], v[98:105], v[2:17], v194, v194 op_sel_hi:[0,0,0]
	s_waitcnt lgkmcnt(0)
	s_barrier
	global_load_dwordx4 v[158:161], v176, s[18:19]
	global_load_dwordx4 v[162:165], v178, s[16:17]
	global_load_dwordx4 v[154:157], v[180:181], off
	ds_read_b128 v[114:117], v215 offset:24576
	ds_read_b128 v[118:121], v216 offset:24576
	ds_read_b128 v[222:225], v215 offset:28672
	ds_read_b128 v[226:229], v216 offset:28672
	v_add_u32_e32 v176, 0x2000, v176
	v_add_u32_e32 v178, 0x20000, v178
	s_mov_b64 s[20:21], 0x1000
	v_lshl_add_u64 v[180:181], v[180:181], 0, s[20:21]
	v_max_f32_e32 v0, v66, v67
	v_max3_f32 v0, v0, v68, v69
	v_max3_f32 v0, v0, v70, v71
	v_max3_f32 v0, v0, v72, v73
	v_max3_f32 v0, v0, v74, v75
	v_max3_f32 v0, v0, v76, v77
	v_max3_f32 v0, v0, v78, v79
	v_max3_f32 v0, v0, v80, v81
	v_max_f32_e32 v177, v177, v0
	v_mov_b32_e32 v0, v177
	v_mov_b32_e32 v218, 1.0
	s_nop 0
	v_permlane32_swap_b32_e32 v177, v0
	v_max_f32_e32 v177, v177, v0
	v_cmp_ge_f32_e32 vcc, s90, v177
	s_cmp_eq_u64 vcc, exec
	s_cbranch_scc0 .Lmla_h5_newmax
.Lmla_h5_cont:
	s_add_i32 s30, s30, 1
	s_cmpk_lt_u32 s30, 42
	s_cbranch_scc1 .LBB0_1321
	v_exp_f32_e32 v0, v82
	v_exp_f32_e32 v177, v83
	v_exp_f32_e32 v179, v84
	v_exp_f32_e32 v254, v85
	v_add_f32_e32 v219, v0, v177
	v_cvt_pk_fp8_f32 v246, v0, v177
	v_add_f32_e32 v219, v179, v219
	v_add_f32_e32 v219, v254, v219
	v_cvt_pk_fp8_f32 v246, v179, v254 op_sel:[0,0,1]
	s_waitcnt lgkmcnt(2)
	v_mfma_scale_f32_32x32x64_f8f6f4 v[114:129], v[114:121], v[146:153], v[230:245], v194, v193 op_sel_hi:[0,0,0]
	v_exp_f32_e32 v0, v86
	v_exp_f32_e32 v177, v87
	v_exp_f32_e32 v179, v88
	v_exp_f32_e32 v254, v89
	v_add_f32_e32 v219, v0, v219
	v_add_f32_e32 v219, v177, v219
	v_cvt_pk_fp8_f32 v247, v0, v177
	v_add_f32_e32 v219, v179, v219
	v_add_f32_e32 v219, v254, v219
	v_cvt_pk_fp8_f32 v247, v179, v254 op_sel:[0,0,1]
	ds_read_b128 v[82:85], v213 offset:24576
	ds_read_b128 v[86:89], v214 offset:24576
	s_waitcnt lgkmcnt(2)
	v_mfma_scale_f32_32x32x64_f8f6f4 v[98:113], v[222:229], v[146:153], v[230:245], v194, v193 op_sel_hi:[0,0,0]
	ds_read_b128 v[222:225], v213 offset:28672
	ds_read_b128 v[226:229], v214 offset:28672
	v_exp_f32_e32 v0, v90
	v_exp_f32_e32 v177, v91
	v_exp_f32_e32 v179, v92
	v_exp_f32_e32 v254, v93
	v_add_f32_e32 v219, v0, v219
	v_add_f32_e32 v219, v177, v219
	v_cvt_pk_fp8_f32 v248, v0, v177
	v_add_f32_e32 v219, v179, v219
	v_add_f32_e32 v219, v254, v219
	v_cvt_pk_fp8_f32 v248, v179, v254 op_sel:[0,0,1]
	v_exp_f32_e32 v0, v94
	v_exp_f32_e32 v177, v95
	v_exp_f32_e32 v179, v96
	v_exp_f32_e32 v254, v97
	v_add_f32_e32 v219, v0, v219
	v_add_f32_e32 v219, v177, v219
	v_cvt_pk_fp8_f32 v249, v0, v177
	v_add_f32_e32 v219, v179, v219
	v_add_f32_e32 v219, v254, v219
	v_cvt_pk_fp8_f32 v249, v179, v254 op_sel:[0,0,1]
	ds_read_b128 v[90:93], v185 offset:36864
	ds_read_b128 v[94:97], v186 offset:36864
	s_waitcnt lgkmcnt(4)
	v_mfma_scale_f32_32x32x64_f8f6f4 v[114:129], v[82:89], v[138:145], v[114:129], v194, v193 op_sel_hi:[0,0,0]
	v_exp_f32_e32 v0, v66
	v_exp_f32_e32 v177, v67
	v_exp_f32_e32 v179, v68
	v_exp_f32_e32 v254, v69
	v_add_f32_e32 v219, v0, v219
	v_add_f32_e32 v219, v177, v219
	v_cvt_pk_fp8_f32 v250, v0, v177
	v_add_f32_e32 v219, v179, v219
	v_add_f32_e32 v219, v254, v219
	v_cvt_pk_fp8_f32 v250, v179, v254 op_sel:[0,0,1]
	s_waitcnt lgkmcnt(2)
	v_mfma_scale_f32_32x32x64_f8f6f4 v[98:113], v[222:229], v[138:145], v[98:113], v194, v193 op_sel_hi:[0,0,0]
	ds_read_b128 v[222:225], v185 offset:38912
	ds_read_b128 v[226:229], v186 offset:38912
	v_exp_f32_e32 v0, v70
	v_exp_f32_e32 v177, v71
	v_exp_f32_e32 v179, v72
	v_exp_f32_e32 v254, v73
	v_add_f32_e32 v219, v0, v219
	v_add_f32_e32 v219, v177, v219
	v_cvt_pk_fp8_f32 v251, v0, v177
	v_add_f32_e32 v219, v179, v219
	v_add_f32_e32 v219, v254, v219
	v_cvt_pk_fp8_f32 v251, v179, v254 op_sel:[0,0,1]
	v_exp_f32_e32 v0, v74
	v_exp_f32_e32 v177, v75
	v_exp_f32_e32 v179, v76
	v_exp_f32_e32 v254, v77
	v_add_f32_e32 v219, v0, v219
	v_add_f32_e32 v219, v177, v219
	v_cvt_pk_fp8_f32 v252, v0, v177
	v_add_f32_e32 v219, v179, v219
	v_add_f32_e32 v219, v254, v219
	v_cvt_pk_fp8_f32 v252, v179, v254 op_sel:[0,0,1]
	s_waitcnt lgkmcnt(2)
; __device__ __forceinline__ void finishSM9(f32x16& p0, f32x16& p1, float alpha, float& l_reg, v8i32& p8) {
; #pragma unroll
;   for (int r = 0; r < 16; ++r) { p0[r] = __builtin_amdgcn_exp2f(p0[r]); p1[r] = __builtin_amdgcn_exp2f(p1[r]); }
;   float ps = 0;
; #pragma unroll
;   for (int r = 0; r < 16; ++r) ps += p0[r];
; #pragma unroll
;   for (int r = 0; r < 16; ++r) ps += p1[r];
;   { auto rr = __builtin_amdgcn_permlane32_swap(__float_as_uint(ps), __float_as_uint(ps), false, false);
;     ps = __uint_as_float(rr[0]) + __uint_as_float(rr[1]); }
;   l_reg = l_reg * alpha + ps;
; #pragma unroll
;   for (int g = 0; g < 4; ++g) {
;     int w = __builtin_amdgcn_cvt_pk_fp8_f32(p0[4 * g], p0[4 * g + 1], 0, false); p8[g] = __builtin_amdgcn_cvt_pk_fp8_f32(p0[4 * g + 2], p0[4 * g + 3], w, true);
;     int u = __builtin_amdgcn_cvt_pk_fp8_f32(p1[4 * g], p1[4 * g + 1], 0, false); p8[4 + g] = __builtin_amdgcn_cvt_pk_fp8_f32(p1[4 * g + 2], p1[4 * g + 3], u, true); }
; }
; __device__ __forceinline__ void pv8(f32x16* o, const char* Vt, const v8i32 p8, int r32, int hi) {
;   const int sw = (r32 >> 2) & 3, a0 = r32 * 64 + (((hi * 2) ^ sw) << 4), a1 = r32 * 64 + (((hi * 2 + 1) ^ sw) << 4);
; #pragma unroll
;   for (int d0 = 0; d0 < 4; ++d0) {
;     const v8i32 vf = cat8(*reinterpret_cast<const v4i32*>(Vt + d0 * 2048 + a0), *reinterpret_cast<const v4i32*>(Vt + d0 * 2048 + a1));
;     o[d0] = __builtin_amdgcn_mfma_scale_f32_32x32x64_f8f6f4(p8, vf, o[d0], 0, 0, 0, 127, 0, 127); }
; }
; __device__ __forceinline__ void qkt9(f32x16& p0, f32x16& p1, const char* Kn, const char* Kr, const v8i32* qf, const float init, int r32, int hi) {
; #pragma unroll
;   for (int r = 0; r < 16; ++r) { p0[r] = init; p1[r] = init; }
; #pragma unroll
;   for (int s = 0; s < 2; ++s) { const int c0 = s * 4 + hi * 2;
;     const v8i32 a0 = cat8(*reinterpret_cast<const v4i32*>(Kn + KN8SW(r32, c0)), *reinterpret_cast<const v4i32*>(Kn + KN8SW(r32, c0 + 1)));
;     const v8i32 a1 = cat8(*reinterpret_cast<const v4i32*>(Kn + 4096 + KN8SW(r32, c0)), *reinterpret_cast<const v4i32*>(Kn + 4096 + KN8SW(r32, c0 + 1)));
;     p0 = __builtin_amdgcn_mfma_scale_f32_32x32x64_f8f6f4(a0, qf[s], p0, 0, 0, 0, 127, 0, 124);
;     p1 = __builtin_amdgcn_mfma_scale_f32_32x32x64_f8f6f4(a1, qf[s], p1, 0, 0, 0, 127, 0, 124); }
;   { const int c0 = hi * 2;
	v_mfma_scale_f32_32x32x64_f8f6f4 v[114:129], v[90:97], v[130:137], v[114:129], v194, v193 op_sel_hi:[0,0,0]
	v_exp_f32_e32 v0, v78
	v_exp_f32_e32 v177, v79
	v_exp_f32_e32 v179, v80
	v_exp_f32_e32 v254, v81
	v_add_f32_e32 v219, v0, v219
	v_add_f32_e32 v219, v177, v219
	v_cvt_pk_fp8_f32 v253, v0, v177
	v_add_f32_e32 v219, v179, v219
	v_add_f32_e32 v219, v254, v219
	v_cvt_pk_fp8_f32 v253, v179, v254 op_sel:[0,0,1]
	ds_read_b128 v[90:93], v185 offset:0
	ds_read_b128 v[94:97], v186 offset:0
	ds_read_b128 v[82:85], v185 offset:2048
	ds_read_b128 v[86:89], v186 offset:2048
	ds_read_b128 v[74:77], v185 offset:4096
	ds_read_b128 v[78:81], v186 offset:4096
	ds_read_b128 v[66:69], v185 offset:6144
	ds_read_b128 v[70:73], v186 offset:6144
	s_waitcnt lgkmcnt(8)
	v_mfma_scale_f32_32x32x64_f8f6f4 v[98:113], v[222:229], v[130:137], v[98:113], v194, v193 op_sel_hi:[0,0,0]
	v_mov_b32_e32 v0, v219
	s_nop 1
	v_permlane32_swap_b32_e32 v219, v0
	v_add_f32_e32 v219, v219, v0
	v_fma_f32 v209, v209, v218, v219
	v_max_f32_e32 v177, v114, v115
	v_max3_f32 v177, v177, v116, v117
	v_max3_f32 v177, v177, v118, v119
	v_max3_f32 v177, v177, v120, v121
	v_max3_f32 v177, v177, v122, v123
	v_max3_f32 v177, v177, v124, v125
	v_max3_f32 v177, v177, v126, v127
	v_max3_f32 v177, v177, v128, v129
	s_waitcnt lgkmcnt(6)
	v_mfma_scale_f32_32x32x64_f8f6f4 v[50:65], v[246:253], v[90:97], v[50:65], v194, v194 op_sel_hi:[0,0,0]
	s_waitcnt lgkmcnt(4)
	v_mfma_scale_f32_32x32x64_f8f6f4 v[34:49], v[246:253], v[82:89], v[34:49], v194, v194 op_sel_hi:[0,0,0]
	s_waitcnt lgkmcnt(2)
	v_mfma_scale_f32_32x32x64_f8f6f4 v[18:33], v[246:253], v[74:81], v[18:33], v194, v194 op_sel_hi:[0,0,0]
	s_waitcnt vmcnt(0)
	ds_write_b128 v210, v[158:161] offset:43008
	ds_write_b128 v211, v[162:165] offset:51200
	ds_write_b128 v212, v[154:157] offset:59392
	s_waitcnt lgkmcnt(3)
	v_mfma_scale_f32_32x32x64_f8f6f4 v[2:17], v[246:253], v[66:73], v[2:17], v194, v194 op_sel_hi:[0,0,0]
	s_waitcnt lgkmcnt(0)
	s_barrier
	global_load_dwordx4 v[158:161], v176, s[18:19]
	global_load_dwordx4 v[162:165], v178, s[16:17]
	global_load_dwordx4 v[154:157], v[180:181], off
	ds_read_b128 v[82:85], v215 offset:51200
	ds_read_b128 v[86:89], v216 offset:51200
	ds_read_b128 v[222:225], v215 offset:55296
	ds_read_b128 v[226:229], v216 offset:55296
	v_add_u32_e32 v176, 0x2000, v176
	v_add_u32_e32 v178, 0x20000, v178
	s_mov_b64 s[20:21], 0x1000
	v_lshl_add_u64 v[180:181], v[180:181], 0, s[20:21]
	v_max_f32_e32 v0, v98, v99
	v_max3_f32 v0, v0, v100, v101
	v_max3_f32 v0, v0, v102, v103
	v_max3_f32 v0, v0, v104, v105
	v_max3_f32 v0, v0, v106, v107
	v_max3_f32 v0, v0, v108, v109
	v_max3_f32 v0, v0, v110, v111
	v_max3_f32 v0, v0, v112, v113
	v_max_f32_e32 v177, v177, v0
	v_mov_b32_e32 v0, v177
	v_mov_b32_e32 v221, 1.0
	s_nop 0
	v_permlane32_swap_b32_e32 v177, v0
	v_max_f32_e32 v177, v177, v0
	v_cmp_ge_f32_e32 vcc, s90, v177
	s_cmp_eq_u64 vcc, exec
	s_cbranch_scc0 .Lmla_p0_newmax
; __device__ __forceinline__ void finishSM9(f32x16& p0, f32x16& p1, float alpha, float& l_reg, v8i32& p8) {
; #pragma unroll
;   for (int r = 0; r < 16; ++r) { p0[r] = __builtin_amdgcn_exp2f(p0[r]); p1[r] = __builtin_amdgcn_exp2f(p1[r]); }
;   float ps = 0;
; #pragma unroll
;   for (int r = 0; r < 16; ++r) ps += p0[r];
; #pragma unroll
;   for (int r = 0; r < 16; ++r) ps += p1[r];
;   { auto rr = __builtin_amdgcn_permlane32_swap(__float_as_uint(ps), __float_as_uint(ps), false, false);
;     ps = __uint_as_float(rr[0]) + __uint_as_float(rr[1]); }
;   l_reg = l_reg * alpha + ps;
; #pragma unroll
;   for (int g = 0; g < 4; ++g) {
;     int w = __builtin_amdgcn_cvt_pk_fp8_f32(p0[4 * g], p0[4 * g + 1], 0, false); p8[g] = __builtin_amdgcn_cvt_pk_fp8_f32(p0[4 * g + 2], p0[4 * g + 3], w, true);
;     int u = __builtin_amdgcn_cvt_pk_fp8_f32(p1[4 * g], p1[4 * g + 1], 0, false); p8[4 + g] = __builtin_amdgcn_cvt_pk_fp8_f32(p1[4 * g + 2], p1[4 * g + 3], u, true); }
; }
; __device__ __forceinline__ void pv8(f32x16* o, const char* Vt, const v8i32 p8, int r32, int hi) {
;   const int sw = (r32 >> 2) & 3, a0 = r32 * 64 + (((hi * 2) ^ sw) << 4), a1 = r32 * 64 + (((hi * 2 + 1) ^ sw) << 4);
; #pragma unroll
;   for (int d0 = 0; d0 < 4; ++d0) {
;     const v8i32 vf = cat8(*reinterpret_cast<const v4i32*>(Vt + d0 * 2048 + a0), *reinterpret_cast<const v4i32*>(Vt + d0 * 2048 + a1));
;     o[d0] = __builtin_amdgcn_mfma_scale_f32_32x32x64_f8f6f4(p8, vf, o[d0], 0, 0, 0, 127, 0, 127); }
; }
; __device__ __forceinline__ void qkt9(f32x16& p0, f32x16& p1, const char* Kn, const char* Kr, const v8i32* qf, const float init, int r32, int hi) {
; #pragma unroll
;   for (int r = 0; r < 16; ++r) { p0[r] = init; p1[r] = init; }
; #pragma unroll
;   for (int s = 0; s < 2; ++s) { const int c0 = s * 4 + hi * 2;
;     const v8i32 a0 = cat8(*reinterpret_cast<const v4i32*>(Kn + KN8SW(r32, c0)), *reinterpret_cast<const v4i32*>(Kn + KN8SW(r32, c0 + 1)));
;     const v8i32 a1 = cat8(*reinterpret_cast<const v4i32*>(Kn + 4096 + KN8SW(r32, c0)), *reinterpret_cast<const v4i32*>(Kn + 4096 + KN8SW(r32, c0 + 1)));
;     p0 = __builtin_amdgcn_mfma_scale_f32_32x32x64_f8f6f4(a0, qf[s], p0, 0, 0, 0, 127, 0, 124);
;     p1 = __builtin_amdgcn_mfma_scale_f32_32x32x64_f8f6f4(a1, qf[s], p1, 0, 0, 0, 127, 0, 124); }
;   { const int c0 = hi * 2;
.Lmla_p0_cont:
	v_exp_f32_e32 v0, v114
	v_exp_f32_e32 v177, v115
	v_exp_f32_e32 v179, v116
	v_exp_f32_e32 v254, v117
	v_add_f32_e32 v219, v0, v177
	v_cvt_pk_fp8_f32 v246, v0, v177
	v_add_f32_e32 v219, v179, v219
	v_add_f32_e32 v219, v254, v219
	v_cvt_pk_fp8_f32 v246, v179, v254 op_sel:[0,0,1]
	s_waitcnt lgkmcnt(2)
	v_mfma_scale_f32_32x32x64_f8f6f4 v[82:97], v[82:89], v[146:153], v[230:245], v194, v193 op_sel_hi:[0,0,0]
	v_exp_f32_e32 v0, v118
	v_exp_f32_e32 v177, v119
	v_exp_f32_e32 v179, v120
	v_exp_f32_e32 v254, v121
	v_add_f32_e32 v219, v0, v219
	v_add_f32_e32 v219, v177, v219
	v_cvt_pk_fp8_f32 v247, v0, v177
	v_add_f32_e32 v219, v179, v219
	v_add_f32_e32 v219, v254, v219
	v_cvt_pk_fp8_f32 v247, v179, v254 op_sel:[0,0,1]
	ds_read_b128 v[114:117], v213 offset:51200
	ds_read_b128 v[118:121], v214 offset:51200
	s_waitcnt lgkmcnt(2)
	v_mfma_scale_f32_32x32x64_f8f6f4 v[66:81], v[222:229], v[146:153], v[230:245], v194, v193 op_sel_hi:[0,0,0]
	ds_read_b128 v[222:225], v213 offset:55296
	ds_read_b128 v[226:229], v214 offset:55296
	v_exp_f32_e32 v0, v122
	v_exp_f32_e32 v177, v123
	v_exp_f32_e32 v179, v124
	v_exp_f32_e32 v254, v125
	v_add_f32_e32 v219, v0, v219
	v_add_f32_e32 v219, v177, v219
	v_cvt_pk_fp8_f32 v248, v0, v177
	v_add_f32_e32 v219, v179, v219
	v_add_f32_e32 v219, v254, v219
	v_cvt_pk_fp8_f32 v248, v179, v254 op_sel:[0,0,1]
	v_exp_f32_e32 v0, v126
	v_exp_f32_e32 v177, v127
	v_exp_f32_e32 v179, v128
	v_exp_f32_e32 v254, v129
	v_add_f32_e32 v219, v0, v219
	v_add_f32_e32 v219, v177, v219
	v_cvt_pk_fp8_f32 v249, v0, v177
	v_add_f32_e32 v219, v179, v219
	v_add_f32_e32 v219, v254, v219
	v_cvt_pk_fp8_f32 v249, v179, v254 op_sel:[0,0,1]
	ds_read_b128 v[122:125], v185 offset:59392
	ds_read_b128 v[126:129], v186 offset:59392
	s_waitcnt lgkmcnt(4)
	v_mfma_scale_f32_32x32x64_f8f6f4 v[82:97], v[114:121], v[138:145], v[82:97], v194, v193 op_sel_hi:[0,0,0]
	v_exp_f32_e32 v0, v98
	v_exp_f32_e32 v177, v99
	v_exp_f32_e32 v179, v100
	v_exp_f32_e32 v254, v101
	v_add_f32_e32 v219, v0, v219
	v_add_f32_e32 v219, v177, v219
	v_cvt_pk_fp8_f32 v250, v0, v177
	v_add_f32_e32 v219, v179, v219
	v_add_f32_e32 v219, v254, v219
	v_cvt_pk_fp8_f32 v250, v179, v254 op_sel:[0,0,1]
	s_waitcnt lgkmcnt(2)
	v_mfma_scale_f32_32x32x64_f8f6f4 v[66:81], v[222:229], v[138:145], v[66:81], v194, v193 op_sel_hi:[0,0,0]
	ds_read_b128 v[222:225], v185 offset:61440
	ds_read_b128 v[226:229], v186 offset:61440
	v_exp_f32_e32 v0, v102
	v_exp_f32_e32 v177, v103
	v_exp_f32_e32 v179, v104
	v_exp_f32_e32 v254, v105
	v_add_f32_e32 v219, v0, v219
	v_add_f32_e32 v219, v177, v219
	v_cvt_pk_fp8_f32 v251, v0, v177
	v_add_f32_e32 v219, v179, v219
	v_add_f32_e32 v219, v254, v219
	v_cvt_pk_fp8_f32 v251, v179, v254 op_sel:[0,0,1]
	v_exp_f32_e32 v0, v106
	v_exp_f32_e32 v177, v107
	v_exp_f32_e32 v179, v108
	v_exp_f32_e32 v254, v109
	v_add_f32_e32 v219, v0, v219
	v_add_f32_e32 v219, v177, v219
	v_cvt_pk_fp8_f32 v252, v0, v177
	v_add_f32_e32 v219, v179, v219
	v_add_f32_e32 v219, v254, v219
	v_cvt_pk_fp8_f32 v252, v179, v254 op_sel:[0,0,1]
	s_waitcnt lgkmcnt(2)
	v_mfma_scale_f32_32x32x64_f8f6f4 v[82:97], v[122:129], v[130:137], v[82:97], v194, v193 op_sel_hi:[0,0,0]
	v_exp_f32_e32 v0, v110
	v_exp_f32_e32 v177, v111
	v_exp_f32_e32 v179, v112
	v_exp_f32_e32 v254, v113
	v_add_f32_e32 v219, v0, v219
	v_add_f32_e32 v219, v177, v219
	v_cvt_pk_fp8_f32 v253, v0, v177
	v_add_f32_e32 v219, v179, v219
	v_add_f32_e32 v219, v254, v219
	v_cvt_pk_fp8_f32 v253, v179, v254 op_sel:[0,0,1]
	ds_read_b128 v[122:125], v185 offset:8192
	ds_read_b128 v[126:129], v186 offset:8192
	ds_read_b128 v[114:117], v185 offset:10240
	ds_read_b128 v[118:121], v186 offset:10240
	ds_read_b128 v[106:109], v185 offset:12288
	ds_read_b128 v[110:113], v186 offset:12288
	ds_read_b128 v[98:101], v185 offset:14336
	ds_read_b128 v[102:105], v186 offset:14336
	s_waitcnt lgkmcnt(8)
	v_mfma_scale_f32_32x32x64_f8f6f4 v[66:81], v[222:229], v[130:137], v[66:81], v194, v193 op_sel_hi:[0,0,0]
	v_mov_b32_e32 v0, v219
	s_nop 1
	v_permlane32_swap_b32_e32 v219, v0
	v_add_f32_e32 v219, v219, v0
	v_fma_f32 v209, v209, v221, v219
	v_max_f32_e32 v177, v82, v83
	v_max3_f32 v177, v177, v84, v85
	v_max3_f32 v177, v177, v86, v87
	v_max3_f32 v177, v177, v88, v89
	v_max3_f32 v177, v177, v90, v91
	v_max3_f32 v177, v177, v92, v93
	v_max3_f32 v177, v177, v94, v95
	v_max3_f32 v177, v177, v96, v97
	s_waitcnt lgkmcnt(6)
	v_mfma_scale_f32_32x32x64_f8f6f4 v[50:65], v[246:253], v[122:129], v[50:65], v194, v194 op_sel_hi:[0,0,0]
	s_waitcnt lgkmcnt(4)
	v_mfma_scale_f32_32x32x64_f8f6f4 v[34:49], v[246:253], v[114:121], v[34:49], v194, v194 op_sel_hi:[0,0,0]
	s_waitcnt lgkmcnt(2)
	v_mfma_scale_f32_32x32x64_f8f6f4 v[18:33], v[246:253], v[106:113], v[18:33], v194, v194 op_sel_hi:[0,0,0]
	s_waitcnt vmcnt(0)
	ds_write_b128 v210, v[158:161]
	ds_write_b128 v211, v[162:165] offset:16384
	ds_write_b128 v212, v[154:157] offset:32768
	s_waitcnt lgkmcnt(3)
	v_mfma_scale_f32_32x32x64_f8f6f4 v[2:17], v[246:253], v[98:105], v[2:17], v194, v194 op_sel_hi:[0,0,0]
	s_waitcnt lgkmcnt(0)
	s_barrier
	v_max_f32_e32 v0, v66, v67
	v_max3_f32 v0, v0, v68, v69
	v_max3_f32 v0, v0, v70, v71
	v_max3_f32 v0, v0, v72, v73
	v_max3_f32 v0, v0, v74, v75
	v_max3_f32 v0, v0, v76, v77
	v_max3_f32 v0, v0, v78, v79
	v_max3_f32 v0, v0, v80, v81
	v_max_f32_e32 v177, v177, v0
	v_mov_b32_e32 v0, v177
	v_mov_b32_e32 v218, 1.0
	s_nop 0
	v_permlane32_swap_b32_e32 v177, v0
	v_max_f32_e32 v177, v177, v0
	v_cmp_ge_f32_e32 vcc, s90, v177
	s_cmp_eq_u64 vcc, exec
	s_cbranch_scc0 .Lmla_p1_newmax

; __device__ __forceinline__ void finishSM9(f32x16& p0, f32x16& p1, float alpha, float& l_reg, v8i32& p8) {
; #pragma unroll
;   for (int r = 0; r < 16; ++r) { p0[r] = __builtin_amdgcn_exp2f(p0[r]); p1[r] = __builtin_amdgcn_exp2f(p1[r]); }
;   float ps = 0;
; #pragma unroll
;   for (int r = 0; r < 16; ++r) ps += p0[r];
; #pragma unroll
;   for (int r = 0; r < 16; ++r) ps += p1[r];
;   { auto rr = __builtin_amdgcn_permlane32_swap(__float_as_uint(ps), __float_as_uint(ps), false, false);
;     ps = __uint_as_float(rr[0]) + __uint_as_float(rr[1]); }
;   l_reg = l_reg * alpha + ps;
; #pragma unroll
;   for (int g = 0; g < 4; ++g) {
;     int w = __builtin_amdgcn_cvt_pk_fp8_f32(p0[4 * g], p0[4 * g + 1], 0, false); p8[g] = __builtin_amdgcn_cvt_pk_fp8_f32(p0[4 * g + 2], p0[4 * g + 3], w, true);
;     int u = __builtin_amdgcn_cvt_pk_fp8_f32(p1[4 * g], p1[4 * g + 1], 0, false); p8[4 + g] = __builtin_amdgcn_cvt_pk_fp8_f32(p1[4 * g + 2], p1[4 * g + 3], u, true); }
; }
; __device__ __forceinline__ void pv8(f32x16* o, const char* Vt, const v8i32 p8, int r32, int hi) {
;   const int sw = (r32 >> 2) & 3, a0 = r32 * 64 + (((hi * 2) ^ sw) << 4), a1 = r32 * 64 + (((hi * 2 + 1) ^ sw) << 4);
; #pragma unroll
;   for (int d0 = 0; d0 < 4; ++d0) {
;     const v8i32 vf = cat8(*reinterpret_cast<const v4i32*>(Vt + d0 * 2048 + a0), *reinterpret_cast<const v4i32*>(Vt + d0 * 2048 + a1));
;     o[d0] = __builtin_amdgcn_mfma_scale_f32_32x32x64_f8f6f4(p8, vf, o[d0], 0, 0, 0, 127, 0, 127); }
; }
; __device__ __forceinline__ void qkt9(f32x16& p0, f32x16& p1, const char* Kn, const char* Kr, const v8i32* qf, const float init, int r32, int hi) {
; #pragma unroll
;   for (int r = 0; r < 16; ++r) { p0[r] = init; p1[r] = init; }
; #pragma unroll
;   for (int s = 0; s < 2; ++s) { const int c0 = s * 4 + hi * 2;
;     const v8i32 a0 = cat8(*reinterpret_cast<const v4i32*>(Kn + KN8SW(r32, c0)), *reinterpret_cast<const v4i32*>(Kn + KN8SW(r32, c0 + 1)));
;     const v8i32 a1 = cat8(*reinterpret_cast<const v4i32*>(Kn + 4096 + KN8SW(r32, c0)), *reinterpret_cast<const v4i32*>(Kn + 4096 + KN8SW(r32, c0 + 1)));
;     p0 = __builtin_amdgcn_mfma_scale_f32_32x32x64_f8f6f4(a0, qf[s], p0, 0, 0, 0, 127, 0, 124);
;     p1 = __builtin_amdgcn_mfma_scale_f32_32x32x64_f8f6f4(a1, qf[s], p1, 0, 0, 0, 127, 0, 124); }
;   { const int c0 = hi * 2;
.Lmla_stag_entry:
	global_load_dwordx4 v[158:161], v176, s[18:19]
	global_load_dwordx4 v[162:165], v178, s[16:17]
	s_nop 1
	v_add_u32_e32 v176, 0x2000, v176
	v_add_u32_e32 v178, 0x20000, v178
	ds_read_b128 v[114:117], v215 offset:24576
	ds_read_b128 v[118:121], v216 offset:24576
	ds_read_b128 v[222:225], v215 offset:28672
	ds_read_b128 v[226:229], v216 offset:28672
.Lmla_stag_loop:
	v_exp_f32_e32 v0, v82
	v_exp_f32_e32 v177, v83
	v_exp_f32_e32 v179, v84
	v_exp_f32_e32 v254, v85
	v_add_f32_e32 v219, v0, v177
	v_cvt_pk_fp8_f32 v246, v0, v177
	v_add_f32_e32 v219, v179, v219
	v_add_f32_e32 v219, v254, v219
	v_cvt_pk_fp8_f32 v246, v179, v254 op_sel:[0,0,1]
	s_waitcnt lgkmcnt(2)
	v_mfma_scale_f32_32x32x64_f8f6f4 v[114:129], v[114:121], v[146:153], v[230:245], v194, v193 op_sel_hi:[0,0,0]
	v_exp_f32_e32 v0, v86
	v_exp_f32_e32 v177, v87
	v_exp_f32_e32 v179, v88
	v_exp_f32_e32 v254, v89
	v_add_f32_e32 v219, v0, v219
	v_add_f32_e32 v219, v177, v219
	v_cvt_pk_fp8_f32 v247, v0, v177
	v_add_f32_e32 v219, v179, v219
	v_add_f32_e32 v219, v254, v219
	v_cvt_pk_fp8_f32 v247, v179, v254 op_sel:[0,0,1]
	ds_read_b128 v[82:85], v213 offset:24576
	ds_read_b128 v[86:89], v214 offset:24576
	s_waitcnt lgkmcnt(2)
	v_mfma_scale_f32_32x32x64_f8f6f4 v[98:113], v[222:229], v[146:153], v[230:245], v194, v193 op_sel_hi:[0,0,0]
	ds_read_b128 v[222:225], v213 offset:28672
	ds_read_b128 v[226:229], v214 offset:28672
	v_exp_f32_e32 v0, v90
	v_exp_f32_e32 v177, v91
	v_exp_f32_e32 v179, v92
	v_exp_f32_e32 v254, v93
	v_add_f32_e32 v219, v0, v219
	v_add_f32_e32 v219, v177, v219
	v_cvt_pk_fp8_f32 v248, v0, v177
	v_add_f32_e32 v219, v179, v219
	v_add_f32_e32 v219, v254, v219
	v_cvt_pk_fp8_f32 v248, v179, v254 op_sel:[0,0,1]
	v_exp_f32_e32 v0, v94
	v_exp_f32_e32 v177, v95
	v_exp_f32_e32 v179, v96
	v_exp_f32_e32 v254, v97
	v_add_f32_e32 v219, v0, v219
	v_add_f32_e32 v219, v177, v219
	v_cvt_pk_fp8_f32 v249, v0, v177
	v_add_f32_e32 v219, v179, v219
	v_add_f32_e32 v219, v254, v219
	v_cvt_pk_fp8_f32 v249, v179, v254 op_sel:[0,0,1]
	ds_read_b128 v[90:93], v185 offset:36864
	ds_read_b128 v[94:97], v186 offset:36864
	s_waitcnt lgkmcnt(4)
	v_mfma_scale_f32_32x32x64_f8f6f4 v[114:129], v[82:89], v[138:145], v[114:129], v194, v193 op_sel_hi:[0,0,0]
	v_exp_f32_e32 v0, v66
	v_exp_f32_e32 v177, v67
	v_exp_f32_e32 v179, v68
	v_exp_f32_e32 v254, v69
	v_add_f32_e32 v219, v0, v219
	v_add_f32_e32 v219, v177, v219
	v_cvt_pk_fp8_f32 v250, v0, v177
	v_add_f32_e32 v219, v179, v219
	v_add_f32_e32 v219, v254, v219
	v_cvt_pk_fp8_f32 v250, v179, v254 op_sel:[0,0,1]
	s_waitcnt lgkmcnt(2)
	v_mfma_scale_f32_32x32x64_f8f6f4 v[98:113], v[222:229], v[138:145], v[98:113], v194, v193 op_sel_hi:[0,0,0]
	ds_read_b128 v[222:225], v185 offset:38912
	ds_read_b128 v[226:229], v186 offset:38912
	v_exp_f32_e32 v0, v70
	v_exp_f32_e32 v177, v71
	v_exp_f32_e32 v179, v72
	v_exp_f32_e32 v254, v73
	v_add_f32_e32 v219, v0, v219
	v_add_f32_e32 v219, v177, v219
	v_cvt_pk_fp8_f32 v251, v0, v177
	v_add_f32_e32 v219, v179, v219
	v_add_f32_e32 v219, v254, v219
	v_cvt_pk_fp8_f32 v251, v179, v254 op_sel:[0,0,1]
	v_exp_f32_e32 v0, v74
	v_exp_f32_e32 v177, v75
	v_exp_f32_e32 v179, v76
	v_exp_f32_e32 v254, v77
	v_add_f32_e32 v219, v0, v219
	v_add_f32_e32 v219, v177, v219
	v_cvt_pk_fp8_f32 v252, v0, v177
	v_add_f32_e32 v219, v179, v219
	v_add_f32_e32 v219, v254, v219
	v_cvt_pk_fp8_f32 v252, v179, v254 op_sel:[0,0,1]
	s_waitcnt lgkmcnt(2)
	v_mfma_scale_f32_32x32x64_f8f6f4 v[114:129], v[90:97], v[130:137], v[114:129], v194, v193 op_sel_hi:[0,0,0]
	v_exp_f32_e32 v0, v78
	v_exp_f32_e32 v177, v79
	v_exp_f32_e32 v179, v80
	v_exp_f32_e32 v254, v81
	v_add_f32_e32 v219, v0, v219
	v_add_f32_e32 v219, v177, v219
	v_cvt_pk_fp8_f32 v253, v0, v177
	v_add_f32_e32 v219, v179, v219
	v_add_f32_e32 v219, v254, v219
	v_cvt_pk_fp8_f32 v253, v179, v254 op_sel:[0,0,1]
	ds_read_b128 v[90:93], v185 offset:0
	ds_read_b128 v[94:97], v186 offset:0
	ds_read_b128 v[82:85], v185 offset:2048
	ds_read_b128 v[86:89], v186 offset:2048
	ds_read_b128 v[74:77], v185 offset:4096
	ds_read_b128 v[78:81], v186 offset:4096
	ds_read_b128 v[66:69], v185 offset:6144
	ds_read_b128 v[70:73], v186 offset:6144
	s_waitcnt lgkmcnt(8)
	v_mfma_scale_f32_32x32x64_f8f6f4 v[98:113], v[222:229], v[130:137], v[98:113], v194, v193 op_sel_hi:[0,0,0]
	v_mov_b32_e32 v0, v219
	s_nop 1
	v_permlane32_swap_b32_e32 v219, v0
	v_add_f32_e32 v219, v219, v0
	v_fma_f32 v209, v209, v218, v219
	v_max_f32_e32 v177, v114, v115
	v_max3_f32 v177, v177, v116, v117
	v_max3_f32 v177, v177, v118, v119
	v_max3_f32 v177, v177, v120, v121
	v_max3_f32 v177, v177, v122, v123
	v_max3_f32 v177, v177, v124, v125
	v_max3_f32 v177, v177, v126, v127
	v_max3_f32 v177, v177, v128, v129
	s_waitcnt lgkmcnt(6)
	v_mfma_scale_f32_32x32x64_f8f6f4 v[50:65], v[246:253], v[90:97], v[50:65], v194, v194 op_sel_hi:[0,0,0]
	s_waitcnt vmcnt(0)
	ds_write_b128 v210, v[158:161] offset:43008
	ds_write_b128 v211, v[162:165] offset:51200
	s_waitcnt lgkmcnt(6)
	v_mfma_scale_f32_32x32x64_f8f6f4 v[34:49], v[246:253], v[82:89], v[34:49], v194, v194 op_sel_hi:[0,0,0]
	s_waitcnt lgkmcnt(0)
	s_barrier
	global_load_dwordx4 v[158:161], v176, s[18:19]
	global_load_dwordx4 v[162:165], v178, s[16:17]
	v_add_u32_e32 v176, 0x2000, v176
	v_add_u32_e32 v178, 0x20000, v178
	s_waitcnt lgkmcnt(2)
	v_mfma_scale_f32_32x32x64_f8f6f4 v[18:33], v[246:253], v[74:81], v[18:33], v194, v194 op_sel_hi:[0,0,0]
	s_waitcnt lgkmcnt(0)
	v_mfma_scale_f32_32x32x64_f8f6f4 v[2:17], v[246:253], v[66:73], v[2:17], v194, v194 op_sel_hi:[0,0,0]
	ds_read_b128 v[82:85], v215 offset:51200
	ds_read_b128 v[86:89], v216 offset:51200
	ds_read_b128 v[222:225], v215 offset:55296
	ds_read_b128 v[226:229], v216 offset:55296
	v_max_f32_e32 v0, v98, v99
	v_max3_f32 v0, v0, v100, v101
	v_max3_f32 v0, v0, v102, v103
	v_max3_f32 v0, v0, v104, v105
	v_max3_f32 v0, v0, v106, v107
	v_max3_f32 v0, v0, v108, v109
	v_max3_f32 v0, v0, v110, v111
	v_max3_f32 v0, v0, v112, v113
	v_max_f32_e32 v177, v177, v0
	v_mov_b32_e32 v0, v177
	v_mov_b32_e32 v221, 1.0
	s_nop 0
	v_permlane32_swap_b32_e32 v177, v0
	v_max_f32_e32 v177, v177, v0
	v_cmp_ge_f32_e32 vcc, s90, v177
	s_cmp_eq_u64 vcc, exec
	s_cbranch_scc0 .Lmla_s0_newmax
; __device__ __forceinline__ void finishSM9(f32x16& p0, f32x16& p1, float alpha, float& l_reg, v8i32& p8) {
; #pragma unroll
;   for (int r = 0; r < 16; ++r) { p0[r] = __builtin_amdgcn_exp2f(p0[r]); p1[r] = __builtin_amdgcn_exp2f(p1[r]); }
;   float ps = 0;
; #pragma unroll
;   for (int r = 0; r < 16; ++r) ps += p0[r];
; #pragma unroll
;   for (int r = 0; r < 16; ++r) ps += p1[r];
;   { auto rr = __builtin_amdgcn_permlane32_swap(__float_as_uint(ps), __float_as_uint(ps), false, false);
;     ps = __uint_as_float(rr[0]) + __uint_as_float(rr[1]); }
;   l_reg = l_reg * alpha + ps;
; #pragma unroll
;   for (int g = 0; g < 4; ++g) {
;     int w = __builtin_amdgcn_cvt_pk_fp8_f32(p0[4 * g], p0[4 * g + 1], 0, false); p8[g] = __builtin_amdgcn_cvt_pk_fp8_f32(p0[4 * g + 2], p0[4 * g + 3], w, true);
;     int u = __builtin_amdgcn_cvt_pk_fp8_f32(p1[4 * g], p1[4 * g + 1], 0, false); p8[4 + g] = __builtin_amdgcn_cvt_pk_fp8_f32(p1[4 * g + 2], p1[4 * g + 3], u, true); }
; }
; __device__ __forceinline__ void pv8(f32x16* o, const char* Vt, const v8i32 p8, int r32, int hi) {
;   const int sw = (r32 >> 2) & 3, a0 = r32 * 64 + (((hi * 2) ^ sw) << 4), a1 = r32 * 64 + (((hi * 2 + 1) ^ sw) << 4);
; #pragma unroll
;   for (int d0 = 0; d0 < 4; ++d0) {
;     const v8i32 vf = cat8(*reinterpret_cast<const v4i32*>(Vt + d0 * 2048 + a0), *reinterpret_cast<const v4i32*>(Vt + d0 * 2048 + a1));
;     o[d0] = __builtin_amdgcn_mfma_scale_f32_32x32x64_f8f6f4(p8, vf, o[d0], 0, 0, 0, 127, 0, 127); }
; }
; __device__ __forceinline__ void qkt9(f32x16& p0, f32x16& p1, const char* Kn, const char* Kr, const v8i32* qf, const float init, int r32, int hi) {
; #pragma unroll
;   for (int r = 0; r < 16; ++r) { p0[r] = init; p1[r] = init; }
; #pragma unroll
;   for (int s = 0; s < 2; ++s) { const int c0 = s * 4 + hi * 2;
;     const v8i32 a0 = cat8(*reinterpret_cast<const v4i32*>(Kn + KN8SW(r32, c0)), *reinterpret_cast<const v4i32*>(Kn + KN8SW(r32, c0 + 1)));
;     const v8i32 a1 = cat8(*reinterpret_cast<const v4i32*>(Kn + 4096 + KN8SW(r32, c0)), *reinterpret_cast<const v4i32*>(Kn + 4096 + KN8SW(r32, c0 + 1)));
;     p0 = __builtin_amdgcn_mfma_scale_f32_32x32x64_f8f6f4(a0, qf[s], p0, 0, 0, 0, 127, 0, 124);
;     p1 = __builtin_amdgcn_mfma_scale_f32_32x32x64_f8f6f4(a1, qf[s], p1, 0, 0, 0, 127, 0, 124); }
;   { const int c0 = hi * 2;
.Lmla_s0_cont:
	v_exp_f32_e32 v0, v114
	v_exp_f32_e32 v177, v115
	v_exp_f32_e32 v179, v116
	v_exp_f32_e32 v254, v117
	v_add_f32_e32 v219, v0, v177
	v_cvt_pk_fp8_f32 v246, v0, v177
	v_add_f32_e32 v219, v179, v219
	v_add_f32_e32 v219, v254, v219
	v_cvt_pk_fp8_f32 v246, v179, v254 op_sel:[0,0,1]
	s_waitcnt lgkmcnt(2)
	v_mfma_scale_f32_32x32x64_f8f6f4 v[82:97], v[82:89], v[146:153], v[230:245], v194, v193 op_sel_hi:[0,0,0]
	v_exp_f32_e32 v0, v118
	v_exp_f32_e32 v177, v119
	v_exp_f32_e32 v179, v120
	v_exp_f32_e32 v254, v121
	v_add_f32_e32 v219, v0, v219
	v_add_f32_e32 v219, v177, v219
	v_cvt_pk_fp8_f32 v247, v0, v177
	v_add_f32_e32 v219, v179, v219
	v_add_f32_e32 v219, v254, v219
	v_cvt_pk_fp8_f32 v247, v179, v254 op_sel:[0,0,1]
	ds_read_b128 v[114:117], v213 offset:51200
	ds_read_b128 v[118:121], v214 offset:51200
	s_waitcnt lgkmcnt(2)
	v_mfma_scale_f32_32x32x64_f8f6f4 v[66:81], v[222:229], v[146:153], v[230:245], v194, v193 op_sel_hi:[0,0,0]
	ds_read_b128 v[222:225], v213 offset:55296
	ds_read_b128 v[226:229], v214 offset:55296
	v_exp_f32_e32 v0, v122
	v_exp_f32_e32 v177, v123
	v_exp_f32_e32 v179, v124
	v_exp_f32_e32 v254, v125
	v_add_f32_e32 v219, v0, v219
	v_add_f32_e32 v219, v177, v219
	v_cvt_pk_fp8_f32 v248, v0, v177
	v_add_f32_e32 v219, v179, v219
	v_add_f32_e32 v219, v254, v219
	v_cvt_pk_fp8_f32 v248, v179, v254 op_sel:[0,0,1]
	v_exp_f32_e32 v0, v126
	v_exp_f32_e32 v177, v127
	v_exp_f32_e32 v179, v128
	v_exp_f32_e32 v254, v129
	v_add_f32_e32 v219, v0, v219
	v_add_f32_e32 v219, v177, v219
	v_cvt_pk_fp8_f32 v249, v0, v177
	v_add_f32_e32 v219, v179, v219
	v_add_f32_e32 v219, v254, v219
	v_cvt_pk_fp8_f32 v249, v179, v254 op_sel:[0,0,1]
	ds_read_b128 v[122:125], v185 offset:59392
	ds_read_b128 v[126:129], v186 offset:59392
	s_waitcnt lgkmcnt(4)
	v_mfma_scale_f32_32x32x64_f8f6f4 v[82:97], v[114:121], v[138:145], v[82:97], v194, v193 op_sel_hi:[0,0,0]
	v_exp_f32_e32 v0, v98
	v_exp_f32_e32 v177, v99
	v_exp_f32_e32 v179, v100
	v_exp_f32_e32 v254, v101
	v_add_f32_e32 v219, v0, v219
	v_add_f32_e32 v219, v177, v219
	v_cvt_pk_fp8_f32 v250, v0, v177
	v_add_f32_e32 v219, v179, v219
	v_add_f32_e32 v219, v254, v219
	v_cvt_pk_fp8_f32 v250, v179, v254 op_sel:[0,0,1]
	s_waitcnt lgkmcnt(2)
	v_mfma_scale_f32_32x32x64_f8f6f4 v[66:81], v[222:229], v[138:145], v[66:81], v194, v193 op_sel_hi:[0,0,0]
	ds_read_b128 v[222:225], v185 offset:61440
	ds_read_b128 v[226:229], v186 offset:61440
	v_exp_f32_e32 v0, v102
	v_exp_f32_e32 v177, v103
	v_exp_f32_e32 v179, v104
	v_exp_f32_e32 v254, v105
	v_add_f32_e32 v219, v0, v219
	v_add_f32_e32 v219, v177, v219
	v_cvt_pk_fp8_f32 v251, v0, v177
	v_add_f32_e32 v219, v179, v219
	v_add_f32_e32 v219, v254, v219
	v_cvt_pk_fp8_f32 v251, v179, v254 op_sel:[0,0,1]
	v_exp_f32_e32 v0, v106
	v_exp_f32_e32 v177, v107
	v_exp_f32_e32 v179, v108
	v_exp_f32_e32 v254, v109
	v_add_f32_e32 v219, v0, v219
	v_add_f32_e32 v219, v177, v219
	v_cvt_pk_fp8_f32 v252, v0, v177
	v_add_f32_e32 v219, v179, v219
	v_add_f32_e32 v219, v254, v219
	v_cvt_pk_fp8_f32 v252, v179, v254 op_sel:[0,0,1]
	s_waitcnt lgkmcnt(2)
	v_mfma_scale_f32_32x32x64_f8f6f4 v[82:97], v[122:129], v[130:137], v[82:97], v194, v193 op_sel_hi:[0,0,0]
	v_exp_f32_e32 v0, v110
	v_exp_f32_e32 v177, v111
	v_exp_f32_e32 v179, v112
	v_exp_f32_e32 v254, v113
	v_add_f32_e32 v219, v0, v219
	v_add_f32_e32 v219, v177, v219
	v_cvt_pk_fp8_f32 v253, v0, v177
	v_add_f32_e32 v219, v179, v219
	v_add_f32_e32 v219, v254, v219
	v_cvt_pk_fp8_f32 v253, v179, v254 op_sel:[0,0,1]
	ds_read_b128 v[122:125], v185 offset:8192
	ds_read_b128 v[126:129], v186 offset:8192
	ds_read_b128 v[114:117], v185 offset:10240
	ds_read_b128 v[118:121], v186 offset:10240
	ds_read_b128 v[106:109], v185 offset:12288
	ds_read_b128 v[110:113], v186 offset:12288
	ds_read_b128 v[98:101], v185 offset:14336
	ds_read_b128 v[102:105], v186 offset:14336
	s_waitcnt lgkmcnt(8)
	v_mfma_scale_f32_32x32x64_f8f6f4 v[66:81], v[222:229], v[130:137], v[66:81], v194, v193 op_sel_hi:[0,0,0]
	v_mov_b32_e32 v0, v219
	s_nop 1
	v_permlane32_swap_b32_e32 v219, v0
	v_add_f32_e32 v219, v219, v0
	v_fma_f32 v209, v209, v221, v219
	v_max_f32_e32 v177, v82, v83
	v_max3_f32 v177, v177, v84, v85
	v_max3_f32 v177, v177, v86, v87
	v_max3_f32 v177, v177, v88, v89
	v_max3_f32 v177, v177, v90, v91
	v_max3_f32 v177, v177, v92, v93
	v_max3_f32 v177, v177, v94, v95
	v_max3_f32 v177, v177, v96, v97
	s_waitcnt lgkmcnt(6)
	v_mfma_scale_f32_32x32x64_f8f6f4 v[50:65], v[246:253], v[122:129], v[50:65], v194, v194 op_sel_hi:[0,0,0]
	s_waitcnt vmcnt(0)
	ds_write_b128 v210, v[158:161]
	ds_write_b128 v211, v[162:165] offset:16384
	s_waitcnt lgkmcnt(6)
	v_mfma_scale_f32_32x32x64_f8f6f4 v[34:49], v[246:253], v[114:121], v[34:49], v194, v194 op_sel_hi:[0,0,0]
	s_waitcnt lgkmcnt(0)
	s_barrier
	global_load_dwordx4 v[158:161], v176, s[18:19]
	global_load_dwordx4 v[162:165], v178, s[16:17]
	v_add_u32_e32 v176, 0x2000, v176
	v_add_u32_e32 v178, 0x20000, v178
	s_waitcnt lgkmcnt(2)
	v_mfma_scale_f32_32x32x64_f8f6f4 v[18:33], v[246:253], v[106:113], v[18:33], v194, v194 op_sel_hi:[0,0,0]
	s_waitcnt lgkmcnt(0)
	v_mfma_scale_f32_32x32x64_f8f6f4 v[2:17], v[246:253], v[98:105], v[2:17], v194, v194 op_sel_hi:[0,0,0]
	ds_read_b128 v[114:117], v215 offset:16384
	ds_read_b128 v[118:121], v216 offset:16384
	ds_read_b128 v[222:225], v215 offset:20480
	ds_read_b128 v[226:229], v216 offset:20480
	v_max_f32_e32 v0, v66, v67
	v_max3_f32 v0, v0, v68, v69
	v_max3_f32 v0, v0, v70, v71
	v_max3_f32 v0, v0, v72, v73
	v_max3_f32 v0, v0, v74, v75
	v_max3_f32 v0, v0, v76, v77
	v_max3_f32 v0, v0, v78, v79
	v_max3_f32 v0, v0, v80, v81
	v_max_f32_e32 v177, v177, v0
	v_mov_b32_e32 v0, v177
	v_mov_b32_e32 v218, 1.0
	s_nop 0
	v_permlane32_swap_b32_e32 v177, v0
	v_max_f32_e32 v177, v177, v0
	v_cmp_ge_f32_e32 vcc, s90, v177
	s_cmp_eq_u64 vcc, exec
	s_cbranch_scc0 .Lmla_s1_newmax
; __device__ __forceinline__ void finishSM9(f32x16& p0, f32x16& p1, float alpha, float& l_reg, v8i32& p8) {
; #pragma unroll
;   for (int r = 0; r < 16; ++r) { p0[r] = __builtin_amdgcn_exp2f(p0[r]); p1[r] = __builtin_amdgcn_exp2f(p1[r]); }
;   float ps = 0;
; #pragma unroll
;   for (int r = 0; r < 16; ++r) ps += p0[r];
; #pragma unroll
;   for (int r = 0; r < 16; ++r) ps += p1[r];
;   { auto rr = __builtin_amdgcn_permlane32_swap(__float_as_uint(ps), __float_as_uint(ps), false, false);
;     ps = __uint_as_float(rr[0]) + __uint_as_float(rr[1]); }
;   l_reg = l_reg * alpha + ps;
; #pragma unroll
;   for (int g = 0; g < 4; ++g) {
;     int w = __builtin_amdgcn_cvt_pk_fp8_f32(p0[4 * g], p0[4 * g + 1], 0, false); p8[g] = __builtin_amdgcn_cvt_pk_fp8_f32(p0[4 * g + 2], p0[4 * g + 3], w, true);
;     int u = __builtin_amdgcn_cvt_pk_fp8_f32(p1[4 * g], p1[4 * g + 1], 0, false); p8[4 + g] = __builtin_amdgcn_cvt_pk_fp8_f32(p1[4 * g + 2], p1[4 * g + 3], u, true); }
; }
; __device__ __forceinline__ void pv8(f32x16* o, const char* Vt, const v8i32 p8, int r32, int hi) {
;   const int sw = (r32 >> 2) & 3, a0 = r32 * 64 + (((hi * 2) ^ sw) << 4), a1 = r32 * 64 + (((hi * 2 + 1) ^ sw) << 4);
; #pragma unroll
;   for (int d0 = 0; d0 < 4; ++d0) {
;     const v8i32 vf = cat8(*reinterpret_cast<const v4i32*>(Vt + d0 * 2048 + a0), *reinterpret_cast<const v4i32*>(Vt + d0 * 2048 + a1));
;     o[d0] = __builtin_amdgcn_mfma_scale_f32_32x32x64_f8f6f4(p8, vf, o[d0], 0, 0, 0, 127, 0, 127); }
; }
; __device__ __forceinline__ void qkt9(f32x16& p0, f32x16& p1, const char* Kn, const char* Kr, const v8i32* qf, const float init, int r32, int hi) {
; #pragma unroll
;   for (int r = 0; r < 16; ++r) { p0[r] = init; p1[r] = init; }
; #pragma unroll
;   for (int s = 0; s < 2; ++s) { const int c0 = s * 4 + hi * 2;
;     const v8i32 a0 = cat8(*reinterpret_cast<const v4i32*>(Kn + KN8SW(r32, c0)), *reinterpret_cast<const v4i32*>(Kn + KN8SW(r32, c0 + 1)));
;     const v8i32 a1 = cat8(*reinterpret_cast<const v4i32*>(Kn + 4096 + KN8SW(r32, c0)), *reinterpret_cast<const v4i32*>(Kn + 4096 + KN8SW(r32, c0 + 1)));
;     p0 = __builtin_amdgcn_mfma_scale_f32_32x32x64_f8f6f4(a0, qf[s], p0, 0, 0, 0, 127, 0, 124);
;     p1 = __builtin_amdgcn_mfma_scale_f32_32x32x64_f8f6f4(a1, qf[s], p1, 0, 0, 0, 127, 0, 124); }
;   { const int c0 = hi * 2;
.Lmla_s1_cont:
	v_exp_f32_e32 v0, v82
	v_exp_f32_e32 v177, v83
	v_exp_f32_e32 v179, v84
	v_exp_f32_e32 v254, v85
	v_add_f32_e32 v219, v0, v177
	v_cvt_pk_fp8_f32 v246, v0, v177
	v_add_f32_e32 v219, v179, v219
	v_add_f32_e32 v219, v254, v219
	v_cvt_pk_fp8_f32 v246, v179, v254 op_sel:[0,0,1]
	s_waitcnt lgkmcnt(2)
	v_mfma_scale_f32_32x32x64_f8f6f4 v[114:129], v[114:121], v[146:153], v[230:245], v194, v193 op_sel_hi:[0,0,0]
	v_exp_f32_e32 v0, v86
	v_exp_f32_e32 v177, v87
	v_exp_f32_e32 v179, v88
	v_exp_f32_e32 v254, v89
	v_add_f32_e32 v219, v0, v219
	v_add_f32_e32 v219, v177, v219
	v_cvt_pk_fp8_f32 v247, v0, v177
	v_add_f32_e32 v219, v179, v219
	v_add_f32_e32 v219, v254, v219
	v_cvt_pk_fp8_f32 v247, v179, v254 op_sel:[0,0,1]
	ds_read_b128 v[82:85], v213 offset:16384
	ds_read_b128 v[86:89], v214 offset:16384
	s_waitcnt lgkmcnt(2)
	v_mfma_scale_f32_32x32x64_f8f6f4 v[98:113], v[222:229], v[146:153], v[230:245], v194, v193 op_sel_hi:[0,0,0]
	ds_read_b128 v[222:225], v213 offset:20480
	ds_read_b128 v[226:229], v214 offset:20480
	v_exp_f32_e32 v0, v90
	v_exp_f32_e32 v177, v91
	v_exp_f32_e32 v179, v92
	v_exp_f32_e32 v254, v93
	v_add_f32_e32 v219, v0, v219
	v_add_f32_e32 v219, v177, v219
	v_cvt_pk_fp8_f32 v248, v0, v177
	v_add_f32_e32 v219, v179, v219
	v_add_f32_e32 v219, v254, v219
	v_cvt_pk_fp8_f32 v248, v179, v254 op_sel:[0,0,1]
	v_exp_f32_e32 v0, v94
	v_exp_f32_e32 v177, v95
	v_exp_f32_e32 v179, v96
	v_exp_f32_e32 v254, v97
	v_add_f32_e32 v219, v0, v219
	v_add_f32_e32 v219, v177, v219
	v_cvt_pk_fp8_f32 v249, v0, v177
	v_add_f32_e32 v219, v179, v219
	v_add_f32_e32 v219, v254, v219
	v_cvt_pk_fp8_f32 v249, v179, v254 op_sel:[0,0,1]
	ds_read_b128 v[90:93], v185 offset:32768
	ds_read_b128 v[94:97], v186 offset:32768
	s_waitcnt lgkmcnt(4)
	v_mfma_scale_f32_32x32x64_f8f6f4 v[114:129], v[82:89], v[138:145], v[114:129], v194, v193 op_sel_hi:[0,0,0]
	v_exp_f32_e32 v0, v66
	v_exp_f32_e32 v177, v67
	v_exp_f32_e32 v179, v68
	v_exp_f32_e32 v254, v69
	v_add_f32_e32 v219, v0, v219
	v_add_f32_e32 v219, v177, v219
	v_cvt_pk_fp8_f32 v250, v0, v177
	v_add_f32_e32 v219, v179, v219
	v_add_f32_e32 v219, v254, v219
	v_cvt_pk_fp8_f32 v250, v179, v254 op_sel:[0,0,1]
	s_waitcnt lgkmcnt(2)
	v_mfma_scale_f32_32x32x64_f8f6f4 v[98:113], v[222:229], v[138:145], v[98:113], v194, v193 op_sel_hi:[0,0,0]
	ds_read_b128 v[222:225], v185 offset:34816
	ds_read_b128 v[226:229], v186 offset:34816
	v_exp_f32_e32 v0, v70
	v_exp_f32_e32 v177, v71
	v_exp_f32_e32 v179, v72
	v_exp_f32_e32 v254, v73
	v_add_f32_e32 v219, v0, v219
	v_add_f32_e32 v219, v177, v219
	v_cvt_pk_fp8_f32 v251, v0, v177
	v_add_f32_e32 v219, v179, v219
	v_add_f32_e32 v219, v254, v219
	v_cvt_pk_fp8_f32 v251, v179, v254 op_sel:[0,0,1]
	v_exp_f32_e32 v0, v74
	v_exp_f32_e32 v177, v75
	v_exp_f32_e32 v179, v76
	v_exp_f32_e32 v254, v77
	v_add_f32_e32 v219, v0, v219
	v_add_f32_e32 v219, v177, v219
	v_cvt_pk_fp8_f32 v252, v0, v177
	v_add_f32_e32 v219, v179, v219
	v_add_f32_e32 v219, v254, v219
	v_cvt_pk_fp8_f32 v252, v179, v254 op_sel:[0,0,1]
	s_waitcnt lgkmcnt(2)
	v_mfma_scale_f32_32x32x64_f8f6f4 v[114:129], v[90:97], v[130:137], v[114:129], v194, v193 op_sel_hi:[0,0,0]
	v_exp_f32_e32 v0, v78
	v_exp_f32_e32 v177, v79
	v_exp_f32_e32 v179, v80
	v_exp_f32_e32 v254, v81
	v_add_f32_e32 v219, v0, v219
	v_add_f32_e32 v219, v177, v219
	v_cvt_pk_fp8_f32 v253, v0, v177
	v_add_f32_e32 v219, v179, v219
	v_add_f32_e32 v219, v254, v219
	v_cvt_pk_fp8_f32 v253, v179, v254 op_sel:[0,0,1]
	ds_read_b128 v[90:93], v185 offset:43008
	ds_read_b128 v[94:97], v186 offset:43008
	ds_read_b128 v[82:85], v185 offset:45056
	ds_read_b128 v[86:89], v186 offset:45056
	ds_read_b128 v[74:77], v185 offset:47104
	ds_read_b128 v[78:81], v186 offset:47104
	ds_read_b128 v[66:69], v185 offset:49152
	ds_read_b128 v[70:73], v186 offset:49152
	s_waitcnt lgkmcnt(8)
	v_mfma_scale_f32_32x32x64_f8f6f4 v[98:113], v[222:229], v[130:137], v[98:113], v194, v193 op_sel_hi:[0,0,0]
	v_mov_b32_e32 v0, v219
	s_nop 1
	v_permlane32_swap_b32_e32 v219, v0
	v_add_f32_e32 v219, v219, v0
	v_fma_f32 v209, v209, v218, v219
	v_max_f32_e32 v177, v114, v115
	v_max3_f32 v177, v177, v116, v117
	v_max3_f32 v177, v177, v118, v119
	v_max3_f32 v177, v177, v120, v121
	v_max3_f32 v177, v177, v122, v123
	v_max3_f32 v177, v177, v124, v125
	v_max3_f32 v177, v177, v126, v127
	v_max3_f32 v177, v177, v128, v129
	s_waitcnt lgkmcnt(6)
	v_mfma_scale_f32_32x32x64_f8f6f4 v[50:65], v[246:253], v[90:97], v[50:65], v194, v194 op_sel_hi:[0,0,0]
	s_waitcnt vmcnt(0)
	ds_write_b128 v210, v[158:161] offset:8192
	ds_write_b128 v211, v[162:165] offset:24576
	s_waitcnt lgkmcnt(6)
	v_mfma_scale_f32_32x32x64_f8f6f4 v[34:49], v[246:253], v[82:89], v[34:49], v194, v194 op_sel_hi:[0,0,0]
	s_waitcnt lgkmcnt(0)
	s_barrier
	global_load_dwordx4 v[158:161], v176, s[18:19]
	global_load_dwordx4 v[162:165], v178, s[16:17]
	v_add_u32_e32 v176, 0x2000, v176
	v_add_u32_e32 v178, 0x20000, v178
	s_waitcnt lgkmcnt(2)
	v_mfma_scale_f32_32x32x64_f8f6f4 v[18:33], v[246:253], v[74:81], v[18:33], v194, v194 op_sel_hi:[0,0,0]
	s_waitcnt lgkmcnt(0)
	v_mfma_scale_f32_32x32x64_f8f6f4 v[2:17], v[246:253], v[66:73], v[2:17], v194, v194 op_sel_hi:[0,0,0]
	ds_read_b128 v[82:85], v215 offset:24576
	ds_read_b128 v[86:89], v216 offset:24576
	ds_read_b128 v[222:225], v215 offset:28672
	ds_read_b128 v[226:229], v216 offset:28672
	v_max_f32_e32 v0, v98, v99
	v_max3_f32 v0, v0, v100, v101
	v_max3_f32 v0, v0, v102, v103
	v_max3_f32 v0, v0, v104, v105
	v_max3_f32 v0, v0, v106, v107
	v_max3_f32 v0, v0, v108, v109
	v_max3_f32 v0, v0, v110, v111
	v_max3_f32 v0, v0, v112, v113
	v_max_f32_e32 v177, v177, v0
	v_mov_b32_e32 v0, v177
	v_mov_b32_e32 v221, 1.0
	s_nop 0
	v_permlane32_swap_b32_e32 v177, v0
	v_max_f32_e32 v177, v177, v0
	v_cmp_ge_f32_e32 vcc, s90, v177
	s_cmp_eq_u64 vcc, exec
	s_cbranch_scc0 .Lmla_s2_newmax
; __device__ __forceinline__ void finishSM9(f32x16& p0, f32x16& p1, float alpha, float& l_reg, v8i32& p8) {
; #pragma unroll
;   for (int r = 0; r < 16; ++r) { p0[r] = __builtin_amdgcn_exp2f(p0[r]); p1[r] = __builtin_amdgcn_exp2f(p1[r]); }
;   float ps = 0;
; #pragma unroll
;   for (int r = 0; r < 16; ++r) ps += p0[r];
; #pragma unroll
;   for (int r = 0; r < 16; ++r) ps += p1[r];
;   { auto rr = __builtin_amdgcn_permlane32_swap(__float_as_uint(ps), __float_as_uint(ps), false, false);
;     ps = __uint_as_float(rr[0]) + __uint_as_float(rr[1]); }
;   l_reg = l_reg * alpha + ps;
; #pragma unroll
;   for (int g = 0; g < 4; ++g) {
;     int w = __builtin_amdgcn_cvt_pk_fp8_f32(p0[4 * g], p0[4 * g + 1], 0, false); p8[g] = __builtin_amdgcn_cvt_pk_fp8_f32(p0[4 * g + 2], p0[4 * g + 3], w, true);
;     int u = __builtin_amdgcn_cvt_pk_fp8_f32(p1[4 * g], p1[4 * g + 1], 0, false); p8[4 + g] = __builtin_amdgcn_cvt_pk_fp8_f32(p1[4 * g + 2], p1[4 * g + 3], u, true); }
; }
; __device__ __forceinline__ void pv8(f32x16* o, const char* Vt, const v8i32 p8, int r32, int hi) {
;   const int sw = (r32 >> 2) & 3, a0 = r32 * 64 + (((hi * 2) ^ sw) << 4), a1 = r32 * 64 + (((hi * 2 + 1) ^ sw) << 4);
; #pragma unroll
;   for (int d0 = 0; d0 < 4; ++d0) {
;     const v8i32 vf = cat8(*reinterpret_cast<const v4i32*>(Vt + d0 * 2048 + a0), *reinterpret_cast<const v4i32*>(Vt + d0 * 2048 + a1));
;     o[d0] = __builtin_amdgcn_mfma_scale_f32_32x32x64_f8f6f4(p8, vf, o[d0], 0, 0, 0, 127, 0, 127); }
; }
; __device__ __forceinline__ void qkt9(f32x16& p0, f32x16& p1, const char* Kn, const char* Kr, const v8i32* qf, const float init, int r32, int hi) {
; #pragma unroll
;   for (int r = 0; r < 16; ++r) { p0[r] = init; p1[r] = init; }
; #pragma unroll
;   for (int s = 0; s < 2; ++s) { const int c0 = s * 4 + hi * 2;
;     const v8i32 a0 = cat8(*reinterpret_cast<const v4i32*>(Kn + KN8SW(r32, c0)), *reinterpret_cast<const v4i32*>(Kn + KN8SW(r32, c0 + 1)));
;     const v8i32 a1 = cat8(*reinterpret_cast<const v4i32*>(Kn + 4096 + KN8SW(r32, c0)), *reinterpret_cast<const v4i32*>(Kn + 4096 + KN8SW(r32, c0 + 1)));
;     p0 = __builtin_amdgcn_mfma_scale_f32_32x32x64_f8f6f4(a0, qf[s], p0, 0, 0, 0, 127, 0, 124);
;     p1 = __builtin_amdgcn_mfma_scale_f32_32x32x64_f8f6f4(a1, qf[s], p1, 0, 0, 0, 127, 0, 124); }
;   { const int c0 = hi * 2;
.Lmla_s2_cont:
	v_exp_f32_e32 v0, v114
	v_exp_f32_e32 v177, v115
	v_exp_f32_e32 v179, v116
	v_exp_f32_e32 v254, v117
	v_add_f32_e32 v219, v0, v177
	v_cvt_pk_fp8_f32 v246, v0, v177
	v_add_f32_e32 v219, v179, v219
	v_add_f32_e32 v219, v254, v219
	v_cvt_pk_fp8_f32 v246, v179, v254 op_sel:[0,0,1]
	s_waitcnt lgkmcnt(2)
	v_mfma_scale_f32_32x32x64_f8f6f4 v[82:97], v[82:89], v[146:153], v[230:245], v194, v193 op_sel_hi:[0,0,0]
	v_exp_f32_e32 v0, v118
	v_exp_f32_e32 v177, v119
	v_exp_f32_e32 v179, v120
	v_exp_f32_e32 v254, v121
	v_add_f32_e32 v219, v0, v219
	v_add_f32_e32 v219, v177, v219
	v_cvt_pk_fp8_f32 v247, v0, v177
	v_add_f32_e32 v219, v179, v219
	v_add_f32_e32 v219, v254, v219
	v_cvt_pk_fp8_f32 v247, v179, v254 op_sel:[0,0,1]
	ds_read_b128 v[114:117], v213 offset:24576
	ds_read_b128 v[118:121], v214 offset:24576
	s_waitcnt lgkmcnt(2)
	v_mfma_scale_f32_32x32x64_f8f6f4 v[66:81], v[222:229], v[146:153], v[230:245], v194, v193 op_sel_hi:[0,0,0]
	ds_read_b128 v[222:225], v213 offset:28672
	ds_read_b128 v[226:229], v214 offset:28672
	v_exp_f32_e32 v0, v122
	v_exp_f32_e32 v177, v123
	v_exp_f32_e32 v179, v124
	v_exp_f32_e32 v254, v125
	v_add_f32_e32 v219, v0, v219
	v_add_f32_e32 v219, v177, v219
	v_cvt_pk_fp8_f32 v248, v0, v177
	v_add_f32_e32 v219, v179, v219
	v_add_f32_e32 v219, v254, v219
	v_cvt_pk_fp8_f32 v248, v179, v254 op_sel:[0,0,1]
	v_exp_f32_e32 v0, v126
	v_exp_f32_e32 v177, v127
	v_exp_f32_e32 v179, v128
	v_exp_f32_e32 v254, v129
	v_add_f32_e32 v219, v0, v219
	v_add_f32_e32 v219, v177, v219
	v_cvt_pk_fp8_f32 v249, v0, v177
	v_add_f32_e32 v219, v179, v219
	v_add_f32_e32 v219, v254, v219
	v_cvt_pk_fp8_f32 v249, v179, v254 op_sel:[0,0,1]
	ds_read_b128 v[122:125], v185 offset:36864
	ds_read_b128 v[126:129], v186 offset:36864
	s_waitcnt lgkmcnt(4)
	v_mfma_scale_f32_32x32x64_f8f6f4 v[82:97], v[114:121], v[138:145], v[82:97], v194, v193 op_sel_hi:[0,0,0]
	v_exp_f32_e32 v0, v98
	v_exp_f32_e32 v177, v99
	v_exp_f32_e32 v179, v100
	v_exp_f32_e32 v254, v101
	v_add_f32_e32 v219, v0, v219
	v_add_f32_e32 v219, v177, v219
	v_cvt_pk_fp8_f32 v250, v0, v177
	v_add_f32_e32 v219, v179, v219
	v_add_f32_e32 v219, v254, v219
	v_cvt_pk_fp8_f32 v250, v179, v254 op_sel:[0,0,1]
	s_waitcnt lgkmcnt(2)
	v_mfma_scale_f32_32x32x64_f8f6f4 v[66:81], v[222:229], v[138:145], v[66:81], v194, v193 op_sel_hi:[0,0,0]
	ds_read_b128 v[222:225], v185 offset:38912
	ds_read_b128 v[226:229], v186 offset:38912
	v_exp_f32_e32 v0, v102
	v_exp_f32_e32 v177, v103
	v_exp_f32_e32 v179, v104
	v_exp_f32_e32 v254, v105
	v_add_f32_e32 v219, v0, v219
	v_add_f32_e32 v219, v177, v219
	v_cvt_pk_fp8_f32 v251, v0, v177
	v_add_f32_e32 v219, v179, v219
	v_add_f32_e32 v219, v254, v219
	v_cvt_pk_fp8_f32 v251, v179, v254 op_sel:[0,0,1]
	v_exp_f32_e32 v0, v106
	v_exp_f32_e32 v177, v107
	v_exp_f32_e32 v179, v108
	v_exp_f32_e32 v254, v109
	v_add_f32_e32 v219, v0, v219
	v_add_f32_e32 v219, v177, v219
	v_cvt_pk_fp8_f32 v252, v0, v177
	v_add_f32_e32 v219, v179, v219
	v_add_f32_e32 v219, v254, v219
	v_cvt_pk_fp8_f32 v252, v179, v254 op_sel:[0,0,1]
	s_waitcnt lgkmcnt(2)
	v_mfma_scale_f32_32x32x64_f8f6f4 v[82:97], v[122:129], v[130:137], v[82:97], v194, v193 op_sel_hi:[0,0,0]
	v_exp_f32_e32 v0, v110
	v_exp_f32_e32 v177, v111
	v_exp_f32_e32 v179, v112
	v_exp_f32_e32 v254, v113
	v_add_f32_e32 v219, v0, v219
	v_add_f32_e32 v219, v177, v219
	v_cvt_pk_fp8_f32 v253, v0, v177
	v_add_f32_e32 v219, v179, v219
	v_add_f32_e32 v219, v254, v219
	v_cvt_pk_fp8_f32 v253, v179, v254 op_sel:[0,0,1]
	ds_read_b128 v[122:125], v185 offset:0
	ds_read_b128 v[126:129], v186 offset:0
	ds_read_b128 v[114:117], v185 offset:2048
	ds_read_b128 v[118:121], v186 offset:2048
	ds_read_b128 v[106:109], v185 offset:4096
	ds_read_b128 v[110:113], v186 offset:4096
	ds_read_b128 v[98:101], v185 offset:6144
	ds_read_b128 v[102:105], v186 offset:6144
	s_waitcnt lgkmcnt(8)
	v_mfma_scale_f32_32x32x64_f8f6f4 v[66:81], v[222:229], v[130:137], v[66:81], v194, v193 op_sel_hi:[0,0,0]
	v_mov_b32_e32 v0, v219
	s_nop 1
	v_permlane32_swap_b32_e32 v219, v0
	v_add_f32_e32 v219, v219, v0
	v_fma_f32 v209, v209, v221, v219
	v_max_f32_e32 v177, v82, v83
	v_max3_f32 v177, v177, v84, v85
	v_max3_f32 v177, v177, v86, v87
	v_max3_f32 v177, v177, v88, v89
	v_max3_f32 v177, v177, v90, v91
	v_max3_f32 v177, v177, v92, v93
	v_max3_f32 v177, v177, v94, v95
	v_max3_f32 v177, v177, v96, v97
	s_waitcnt lgkmcnt(6)
	v_mfma_scale_f32_32x32x64_f8f6f4 v[50:65], v[246:253], v[122:129], v[50:65], v194, v194 op_sel_hi:[0,0,0]
	s_waitcnt vmcnt(0)
	ds_write_b128 v210, v[158:161] offset:43008
	ds_write_b128 v211, v[162:165] offset:51200
	s_waitcnt lgkmcnt(6)
	v_mfma_scale_f32_32x32x64_f8f6f4 v[34:49], v[246:253], v[114:121], v[34:49], v194, v194 op_sel_hi:[0,0,0]
	s_waitcnt lgkmcnt(0)
	s_barrier
	global_load_dwordx4 v[158:161], v176, s[18:19]
	global_load_dwordx4 v[162:165], v178, s[16:17]
	v_add_u32_e32 v176, 0x2000, v176
	v_add_u32_e32 v178, 0x20000, v178
	s_waitcnt lgkmcnt(2)
	v_mfma_scale_f32_32x32x64_f8f6f4 v[18:33], v[246:253], v[106:113], v[18:33], v194, v194 op_sel_hi:[0,0,0]
	s_waitcnt lgkmcnt(0)
	v_mfma_scale_f32_32x32x64_f8f6f4 v[2:17], v[246:253], v[98:105], v[2:17], v194, v194 op_sel_hi:[0,0,0]
	ds_read_b128 v[114:117], v215 offset:51200
	ds_read_b128 v[118:121], v216 offset:51200
	ds_read_b128 v[222:225], v215 offset:55296
	ds_read_b128 v[226:229], v216 offset:55296
	v_max_f32_e32 v0, v66, v67
	v_max3_f32 v0, v0, v68, v69
	v_max3_f32 v0, v0, v70, v71
	v_max3_f32 v0, v0, v72, v73
	v_max3_f32 v0, v0, v74, v75
	v_max3_f32 v0, v0, v76, v77
	v_max3_f32 v0, v0, v78, v79
	v_max3_f32 v0, v0, v80, v81
	v_max_f32_e32 v177, v177, v0
	v_mov_b32_e32 v0, v177
	v_mov_b32_e32 v218, 1.0
	s_nop 0
	v_permlane32_swap_b32_e32 v177, v0
	v_max_f32_e32 v177, v177, v0
	v_cmp_ge_f32_e32 vcc, s90, v177
	s_cmp_eq_u64 vcc, exec
	s_cbranch_scc0 .Lmla_s3_newmax
; __device__ __forceinline__ void finishSM9(f32x16& p0, f32x16& p1, float alpha, float& l_reg, v8i32& p8) {
; #pragma unroll
;   for (int r = 0; r < 16; ++r) { p0[r] = __builtin_amdgcn_exp2f(p0[r]); p1[r] = __builtin_amdgcn_exp2f(p1[r]); }
;   float ps = 0;
; #pragma unroll
;   for (int r = 0; r < 16; ++r) ps += p0[r];
; #pragma unroll
;   for (int r = 0; r < 16; ++r) ps += p1[r];
;   { auto rr = __builtin_amdgcn_permlane32_swap(__float_as_uint(ps), __float_as_uint(ps), false, false);
;     ps = __uint_as_float(rr[0]) + __uint_as_float(rr[1]); }
;   l_reg = l_reg * alpha + ps;
; #pragma unroll
;   for (int g = 0; g < 4; ++g) {
;     int w = __builtin_amdgcn_cvt_pk_fp8_f32(p0[4 * g], p0[4 * g + 1], 0, false); p8[g] = __builtin_amdgcn_cvt_pk_fp8_f32(p0[4 * g + 2], p0[4 * g + 3], w, true);
;     int u = __builtin_amdgcn_cvt_pk_fp8_f32(p1[4 * g], p1[4 * g + 1], 0, false); p8[4 + g] = __builtin_amdgcn_cvt_pk_fp8_f32(p1[4 * g + 2], p1[4 * g + 3], u, true); }
; }
; __device__ __forceinline__ void pv8(f32x16* o, const char* Vt, const v8i32 p8, int r32, int hi) {
;   const int sw = (r32 >> 2) & 3, a0 = r32 * 64 + (((hi * 2) ^ sw) << 4), a1 = r32 * 64 + (((hi * 2 + 1) ^ sw) << 4);
; #pragma unroll
;   for (int d0 = 0; d0 < 4; ++d0) {
;     const v8i32 vf = cat8(*reinterpret_cast<const v4i32*>(Vt + d0 * 2048 + a0), *reinterpret_cast<const v4i32*>(Vt + d0 * 2048 + a1));
;     o[d0] = __builtin_amdgcn_mfma_scale_f32_32x32x64_f8f6f4(p8, vf, o[d0], 0, 0, 0, 127, 0, 127); }
; }
; __device__ __forceinline__ void qkt9(f32x16& p0, f32x16& p1, const char* Kn, const char* Kr, const v8i32* qf, const float init, int r32, int hi) {
; #pragma unroll
;   for (int r = 0; r < 16; ++r) { p0[r] = init; p1[r] = init; }
; #pragma unroll
;   for (int s = 0; s < 2; ++s) { const int c0 = s * 4 + hi * 2;
;     const v8i32 a0 = cat8(*reinterpret_cast<const v4i32*>(Kn + KN8SW(r32, c0)), *reinterpret_cast<const v4i32*>(Kn + KN8SW(r32, c0 + 1)));
;     const v8i32 a1 = cat8(*reinterpret_cast<const v4i32*>(Kn + 4096 + KN8SW(r32, c0)), *reinterpret_cast<const v4i32*>(Kn + 4096 + KN8SW(r32, c0 + 1)));
;     p0 = __builtin_amdgcn_mfma_scale_f32_32x32x64_f8f6f4(a0, qf[s], p0, 0, 0, 0, 127, 0, 124);
;     p1 = __builtin_amdgcn_mfma_scale_f32_32x32x64_f8f6f4(a1, qf[s], p1, 0, 0, 0, 127, 0, 124); }
;   { const int c0 = hi * 2;
.Lmla_s3_cont:
	v_exp_f32_e32 v0, v82
	v_exp_f32_e32 v177, v83
	v_exp_f32_e32 v179, v84
	v_exp_f32_e32 v254, v85
	v_add_f32_e32 v219, v0, v177
	v_cvt_pk_fp8_f32 v246, v0, v177
	v_add_f32_e32 v219, v179, v219
	v_add_f32_e32 v219, v254, v219
	v_cvt_pk_fp8_f32 v246, v179, v254 op_sel:[0,0,1]
	s_waitcnt lgkmcnt(2)
	v_mfma_scale_f32_32x32x64_f8f6f4 v[114:129], v[114:121], v[146:153], v[230:245], v194, v193 op_sel_hi:[0,0,0]
	v_exp_f32_e32 v0, v86
	v_exp_f32_e32 v177, v87
	v_exp_f32_e32 v179, v88
	v_exp_f32_e32 v254, v89
	v_add_f32_e32 v219, v0, v219
	v_add_f32_e32 v219, v177, v219
	v_cvt_pk_fp8_f32 v247, v0, v177
	v_add_f32_e32 v219, v179, v219
	v_add_f32_e32 v219, v254, v219
	v_cvt_pk_fp8_f32 v247, v179, v254 op_sel:[0,0,1]
	ds_read_b128 v[82:85], v213 offset:51200
	ds_read_b128 v[86:89], v214 offset:51200
	s_waitcnt lgkmcnt(2)
	v_mfma_scale_f32_32x32x64_f8f6f4 v[98:113], v[222:229], v[146:153], v[230:245], v194, v193 op_sel_hi:[0,0,0]
	ds_read_b128 v[222:225], v213 offset:55296
	ds_read_b128 v[226:229], v214 offset:55296
	v_exp_f32_e32 v0, v90
	v_exp_f32_e32 v177, v91
	v_exp_f32_e32 v179, v92
	v_exp_f32_e32 v254, v93
	v_add_f32_e32 v219, v0, v219
	v_add_f32_e32 v219, v177, v219
	v_cvt_pk_fp8_f32 v248, v0, v177
	v_add_f32_e32 v219, v179, v219
	v_add_f32_e32 v219, v254, v219
	v_cvt_pk_fp8_f32 v248, v179, v254 op_sel:[0,0,1]
	v_exp_f32_e32 v0, v94
	v_exp_f32_e32 v177, v95
	v_exp_f32_e32 v179, v96
	v_exp_f32_e32 v254, v97
	v_add_f32_e32 v219, v0, v219
	v_add_f32_e32 v219, v177, v219
	v_cvt_pk_fp8_f32 v249, v0, v177
	v_add_f32_e32 v219, v179, v219
	v_add_f32_e32 v219, v254, v219
	v_cvt_pk_fp8_f32 v249, v179, v254 op_sel:[0,0,1]
	ds_read_b128 v[90:93], v185 offset:59392
	ds_read_b128 v[94:97], v186 offset:59392
	s_waitcnt lgkmcnt(4)
	v_mfma_scale_f32_32x32x64_f8f6f4 v[114:129], v[82:89], v[138:145], v[114:129], v194, v193 op_sel_hi:[0,0,0]
	v_exp_f32_e32 v0, v66
	v_exp_f32_e32 v177, v67
	v_exp_f32_e32 v179, v68
	v_exp_f32_e32 v254, v69
	v_add_f32_e32 v219, v0, v219
	v_add_f32_e32 v219, v177, v219
	v_cvt_pk_fp8_f32 v250, v0, v177
	v_add_f32_e32 v219, v179, v219
	v_add_f32_e32 v219, v254, v219
	v_cvt_pk_fp8_f32 v250, v179, v254 op_sel:[0,0,1]
	s_waitcnt lgkmcnt(2)
	v_mfma_scale_f32_32x32x64_f8f6f4 v[98:113], v[222:229], v[138:145], v[98:113], v194, v193 op_sel_hi:[0,0,0]
	ds_read_b128 v[222:225], v185 offset:61440
	ds_read_b128 v[226:229], v186 offset:61440
	v_exp_f32_e32 v0, v70
	v_exp_f32_e32 v177, v71
	v_exp_f32_e32 v179, v72
	v_exp_f32_e32 v254, v73
	v_add_f32_e32 v219, v0, v219
	v_add_f32_e32 v219, v177, v219
	v_cvt_pk_fp8_f32 v251, v0, v177
	v_add_f32_e32 v219, v179, v219
	v_add_f32_e32 v219, v254, v219
	v_cvt_pk_fp8_f32 v251, v179, v254 op_sel:[0,0,1]
	v_exp_f32_e32 v0, v74
	v_exp_f32_e32 v177, v75
	v_exp_f32_e32 v179, v76
	v_exp_f32_e32 v254, v77
	v_add_f32_e32 v219, v0, v219
	v_add_f32_e32 v219, v177, v219
	v_cvt_pk_fp8_f32 v252, v0, v177
	v_add_f32_e32 v219, v179, v219
	v_add_f32_e32 v219, v254, v219
	v_cvt_pk_fp8_f32 v252, v179, v254 op_sel:[0,0,1]
	s_waitcnt lgkmcnt(2)
	v_mfma_scale_f32_32x32x64_f8f6f4 v[114:129], v[90:97], v[130:137], v[114:129], v194, v193 op_sel_hi:[0,0,0]
	v_exp_f32_e32 v0, v78
	v_exp_f32_e32 v177, v79
	v_exp_f32_e32 v179, v80
	v_exp_f32_e32 v254, v81
	v_add_f32_e32 v219, v0, v219
	v_add_f32_e32 v219, v177, v219
	v_cvt_pk_fp8_f32 v253, v0, v177
	v_add_f32_e32 v219, v179, v219
	v_add_f32_e32 v219, v254, v219
	v_cvt_pk_fp8_f32 v253, v179, v254 op_sel:[0,0,1]
	ds_read_b128 v[90:93], v185 offset:8192
	ds_read_b128 v[94:97], v186 offset:8192
	ds_read_b128 v[82:85], v185 offset:10240
	ds_read_b128 v[86:89], v186 offset:10240
	ds_read_b128 v[74:77], v185 offset:12288
	ds_read_b128 v[78:81], v186 offset:12288
	ds_read_b128 v[66:69], v185 offset:14336
	ds_read_b128 v[70:73], v186 offset:14336
	s_waitcnt lgkmcnt(8)
	v_mfma_scale_f32_32x32x64_f8f6f4 v[98:113], v[222:229], v[130:137], v[98:113], v194, v193 op_sel_hi:[0,0,0]
	v_mov_b32_e32 v0, v219
	s_nop 1
	v_permlane32_swap_b32_e32 v219, v0
	v_add_f32_e32 v219, v219, v0
	v_fma_f32 v209, v209, v218, v219
	v_max_f32_e32 v177, v114, v115
	v_max3_f32 v177, v177, v116, v117
	v_max3_f32 v177, v177, v118, v119
	v_max3_f32 v177, v177, v120, v121
	v_max3_f32 v177, v177, v122, v123
	v_max3_f32 v177, v177, v124, v125
	v_max3_f32 v177, v177, v126, v127
	v_max3_f32 v177, v177, v128, v129
	s_waitcnt lgkmcnt(6)
	v_mfma_scale_f32_32x32x64_f8f6f4 v[50:65], v[246:253], v[90:97], v[50:65], v194, v194 op_sel_hi:[0,0,0]
	s_waitcnt vmcnt(0)
	ds_write_b128 v210, v[158:161]
	ds_write_b128 v211, v[162:165] offset:16384
	s_waitcnt lgkmcnt(6)
	v_mfma_scale_f32_32x32x64_f8f6f4 v[34:49], v[246:253], v[82:89], v[34:49], v194, v194 op_sel_hi:[0,0,0]
	s_waitcnt lgkmcnt(0)
	s_barrier
	global_load_dwordx4 v[158:161], v176, s[18:19]
	global_load_dwordx4 v[162:165], v178, s[16:17]
	v_add_u32_e32 v176, 0x2000, v176
	v_add_u32_e32 v178, 0x20000, v178
	s_waitcnt lgkmcnt(2)
	v_mfma_scale_f32_32x32x64_f8f6f4 v[18:33], v[246:253], v[74:81], v[18:33], v194, v194 op_sel_hi:[0,0,0]
	s_waitcnt lgkmcnt(0)
	v_mfma_scale_f32_32x32x64_f8f6f4 v[2:17], v[246:253], v[66:73], v[2:17], v194, v194 op_sel_hi:[0,0,0]
	ds_read_b128 v[82:85], v215 offset:16384
	ds_read_b128 v[86:89], v216 offset:16384
	ds_read_b128 v[222:225], v215 offset:20480
	ds_read_b128 v[226:229], v216 offset:20480
	v_max_f32_e32 v0, v98, v99
	v_max3_f32 v0, v0, v100, v101
	v_max3_f32 v0, v0, v102, v103
	v_max3_f32 v0, v0, v104, v105
	v_max3_f32 v0, v0, v106, v107
	v_max3_f32 v0, v0, v108, v109
	v_max3_f32 v0, v0, v110, v111
	v_max3_f32 v0, v0, v112, v113
	v_max_f32_e32 v177, v177, v0
	v_mov_b32_e32 v0, v177
	v_mov_b32_e32 v221, 1.0
	s_nop 0
	v_permlane32_swap_b32_e32 v177, v0
	v_max_f32_e32 v177, v177, v0
	v_cmp_ge_f32_e32 vcc, s90, v177
	s_cmp_eq_u64 vcc, exec
	s_cbranch_scc0 .Lmla_s4_newmax
; __device__ __forceinline__ void finishSM9(f32x16& p0, f32x16& p1, float alpha, float& l_reg, v8i32& p8) {
; #pragma unroll
;   for (int r = 0; r < 16; ++r) { p0[r] = __builtin_amdgcn_exp2f(p0[r]); p1[r] = __builtin_amdgcn_exp2f(p1[r]); }
;   float ps = 0;
; #pragma unroll
;   for (int r = 0; r < 16; ++r) ps += p0[r];
; #pragma unroll
;   for (int r = 0; r < 16; ++r) ps += p1[r];
;   { auto rr = __builtin_amdgcn_permlane32_swap(__float_as_uint(ps), __float_as_uint(ps), false, false);
;     ps = __uint_as_float(rr[0]) + __uint_as_float(rr[1]); }
;   l_reg = l_reg * alpha + ps;
; #pragma unroll
;   for (int g = 0; g < 4; ++g) {
;     int w = __builtin_amdgcn_cvt_pk_fp8_f32(p0[4 * g], p0[4 * g + 1], 0, false); p8[g] = __builtin_amdgcn_cvt_pk_fp8_f32(p0[4 * g + 2], p0[4 * g + 3], w, true);
;     int u = __builtin_amdgcn_cvt_pk_fp8_f32(p1[4 * g], p1[4 * g + 1], 0, false); p8[4 + g] = __builtin_amdgcn_cvt_pk_fp8_f32(p1[4 * g + 2], p1[4 * g + 3], u, true); }
; }
; __device__ __forceinline__ void pv8(f32x16* o, const char* Vt, const v8i32 p8, int r32, int hi) {
;   const int sw = (r32 >> 2) & 3, a0 = r32 * 64 + (((hi * 2) ^ sw) << 4), a1 = r32 * 64 + (((hi * 2 + 1) ^ sw) << 4);
; #pragma unroll
;   for (int d0 = 0; d0 < 4; ++d0) {
;     const v8i32 vf = cat8(*reinterpret_cast<const v4i32*>(Vt + d0 * 2048 + a0), *reinterpret_cast<const v4i32*>(Vt + d0 * 2048 + a1));
;     o[d0] = __builtin_amdgcn_mfma_scale_f32_32x32x64_f8f6f4(p8, vf, o[d0], 0, 0, 0, 127, 0, 127); }
; }
; __device__ __forceinline__ void qkt9(f32x16& p0, f32x16& p1, const char* Kn, const char* Kr, const v8i32* qf, const float init, int r32, int hi) {
; #pragma unroll
;   for (int r = 0; r < 16; ++r) { p0[r] = init; p1[r] = init; }
; #pragma unroll
;   for (int s = 0; s < 2; ++s) { const int c0 = s * 4 + hi * 2;
;     const v8i32 a0 = cat8(*reinterpret_cast<const v4i32*>(Kn + KN8SW(r32, c0)), *reinterpret_cast<const v4i32*>(Kn + KN8SW(r32, c0 + 1)));
;     const v8i32 a1 = cat8(*reinterpret_cast<const v4i32*>(Kn + 4096 + KN8SW(r32, c0)), *reinterpret_cast<const v4i32*>(Kn + 4096 + KN8SW(r32, c0 + 1)));
;     p0 = __builtin_amdgcn_mfma_scale_f32_32x32x64_f8f6f4(a0, qf[s], p0, 0, 0, 0, 127, 0, 124);
;     p1 = __builtin_amdgcn_mfma_scale_f32_32x32x64_f8f6f4(a1, qf[s], p1, 0, 0, 0, 127, 0, 124); }
;   { const int c0 = hi * 2;
.Lmla_s4_cont:
	v_exp_f32_e32 v0, v114
	v_exp_f32_e32 v177, v115
	v_exp_f32_e32 v179, v116
	v_exp_f32_e32 v254, v117
	v_add_f32_e32 v219, v0, v177
	v_cvt_pk_fp8_f32 v246, v0, v177
	v_add_f32_e32 v219, v179, v219
	v_add_f32_e32 v219, v254, v219
	v_cvt_pk_fp8_f32 v246, v179, v254 op_sel:[0,0,1]
	s_waitcnt lgkmcnt(2)
	v_mfma_scale_f32_32x32x64_f8f6f4 v[82:97], v[82:89], v[146:153], v[230:245], v194, v193 op_sel_hi:[0,0,0]
	v_exp_f32_e32 v0, v118
	v_exp_f32_e32 v177, v119
	v_exp_f32_e32 v179, v120
	v_exp_f32_e32 v254, v121
	v_add_f32_e32 v219, v0, v219
	v_add_f32_e32 v219, v177, v219
	v_cvt_pk_fp8_f32 v247, v0, v177
	v_add_f32_e32 v219, v179, v219
	v_add_f32_e32 v219, v254, v219
	v_cvt_pk_fp8_f32 v247, v179, v254 op_sel:[0,0,1]
	ds_read_b128 v[114:117], v213 offset:16384
	ds_read_b128 v[118:121], v214 offset:16384
	s_waitcnt lgkmcnt(2)
	v_mfma_scale_f32_32x32x64_f8f6f4 v[66:81], v[222:229], v[146:153], v[230:245], v194, v193 op_sel_hi:[0,0,0]
	ds_read_b128 v[222:225], v213 offset:20480
	ds_read_b128 v[226:229], v214 offset:20480
	v_exp_f32_e32 v0, v122
	v_exp_f32_e32 v177, v123
	v_exp_f32_e32 v179, v124
	v_exp_f32_e32 v254, v125
	v_add_f32_e32 v219, v0, v219
	v_add_f32_e32 v219, v177, v219
	v_cvt_pk_fp8_f32 v248, v0, v177
	v_add_f32_e32 v219, v179, v219
	v_add_f32_e32 v219, v254, v219
	v_cvt_pk_fp8_f32 v248, v179, v254 op_sel:[0,0,1]
	v_exp_f32_e32 v0, v126
	v_exp_f32_e32 v177, v127
	v_exp_f32_e32 v179, v128
	v_exp_f32_e32 v254, v129
	v_add_f32_e32 v219, v0, v219
	v_add_f32_e32 v219, v177, v219
	v_cvt_pk_fp8_f32 v249, v0, v177
	v_add_f32_e32 v219, v179, v219
	v_add_f32_e32 v219, v254, v219
	v_cvt_pk_fp8_f32 v249, v179, v254 op_sel:[0,0,1]
	ds_read_b128 v[122:125], v185 offset:32768
	ds_read_b128 v[126:129], v186 offset:32768
	s_waitcnt lgkmcnt(4)
	v_mfma_scale_f32_32x32x64_f8f6f4 v[82:97], v[114:121], v[138:145], v[82:97], v194, v193 op_sel_hi:[0,0,0]
	v_exp_f32_e32 v0, v98
	v_exp_f32_e32 v177, v99
	v_exp_f32_e32 v179, v100
	v_exp_f32_e32 v254, v101
	v_add_f32_e32 v219, v0, v219
	v_add_f32_e32 v219, v177, v219
	v_cvt_pk_fp8_f32 v250, v0, v177
	v_add_f32_e32 v219, v179, v219
	v_add_f32_e32 v219, v254, v219
	v_cvt_pk_fp8_f32 v250, v179, v254 op_sel:[0,0,1]
	s_waitcnt lgkmcnt(2)
	v_mfma_scale_f32_32x32x64_f8f6f4 v[66:81], v[222:229], v[138:145], v[66:81], v194, v193 op_sel_hi:[0,0,0]
	ds_read_b128 v[222:225], v185 offset:34816
	ds_read_b128 v[226:229], v186 offset:34816
	v_exp_f32_e32 v0, v102
	v_exp_f32_e32 v177, v103
	v_exp_f32_e32 v179, v104
	v_exp_f32_e32 v254, v105
	v_add_f32_e32 v219, v0, v219
	v_add_f32_e32 v219, v177, v219
	v_cvt_pk_fp8_f32 v251, v0, v177
	v_add_f32_e32 v219, v179, v219
	v_add_f32_e32 v219, v254, v219
	v_cvt_pk_fp8_f32 v251, v179, v254 op_sel:[0,0,1]
	v_exp_f32_e32 v0, v106
	v_exp_f32_e32 v177, v107
	v_exp_f32_e32 v179, v108
	v_exp_f32_e32 v254, v109
	v_add_f32_e32 v219, v0, v219
	v_add_f32_e32 v219, v177, v219
	v_cvt_pk_fp8_f32 v252, v0, v177
	v_add_f32_e32 v219, v179, v219
	v_add_f32_e32 v219, v254, v219
	v_cvt_pk_fp8_f32 v252, v179, v254 op_sel:[0,0,1]
	s_waitcnt lgkmcnt(2)
	v_mfma_scale_f32_32x32x64_f8f6f4 v[82:97], v[122:129], v[130:137], v[82:97], v194, v193 op_sel_hi:[0,0,0]
	v_exp_f32_e32 v0, v110
	v_exp_f32_e32 v177, v111
	v_exp_f32_e32 v179, v112
	v_exp_f32_e32 v254, v113
	v_add_f32_e32 v219, v0, v219
	v_add_f32_e32 v219, v177, v219
	v_cvt_pk_fp8_f32 v253, v0, v177
	v_add_f32_e32 v219, v179, v219
	v_add_f32_e32 v219, v254, v219
	v_cvt_pk_fp8_f32 v253, v179, v254 op_sel:[0,0,1]
	ds_read_b128 v[122:125], v185 offset:43008
	ds_read_b128 v[126:129], v186 offset:43008
	ds_read_b128 v[114:117], v185 offset:45056
	ds_read_b128 v[118:121], v186 offset:45056
	ds_read_b128 v[106:109], v185 offset:47104
	ds_read_b128 v[110:113], v186 offset:47104
	ds_read_b128 v[98:101], v185 offset:49152
	ds_read_b128 v[102:105], v186 offset:49152
	s_waitcnt lgkmcnt(8)
	v_mfma_scale_f32_32x32x64_f8f6f4 v[66:81], v[222:229], v[130:137], v[66:81], v194, v193 op_sel_hi:[0,0,0]
	v_mov_b32_e32 v0, v219
	s_nop 1
	v_permlane32_swap_b32_e32 v219, v0
	v_add_f32_e32 v219, v219, v0
	v_fma_f32 v209, v209, v221, v219
	v_max_f32_e32 v177, v82, v83
	v_max3_f32 v177, v177, v84, v85
	v_max3_f32 v177, v177, v86, v87
	v_max3_f32 v177, v177, v88, v89
	v_max3_f32 v177, v177, v90, v91
	v_max3_f32 v177, v177, v92, v93
	v_max3_f32 v177, v177, v94, v95
	v_max3_f32 v177, v177, v96, v97
	s_waitcnt lgkmcnt(6)
	v_mfma_scale_f32_32x32x64_f8f6f4 v[50:65], v[246:253], v[122:129], v[50:65], v194, v194 op_sel_hi:[0,0,0]
	s_waitcnt vmcnt(0)
	ds_write_b128 v210, v[158:161] offset:8192
	ds_write_b128 v211, v[162:165] offset:24576
	s_waitcnt lgkmcnt(6)
	v_mfma_scale_f32_32x32x64_f8f6f4 v[34:49], v[246:253], v[114:121], v[34:49], v194, v194 op_sel_hi:[0,0,0]
	s_waitcnt lgkmcnt(0)
	s_barrier
	global_load_dwordx4 v[158:161], v176, s[18:19]
	global_load_dwordx4 v[162:165], v178, s[16:17]
	v_add_u32_e32 v176, 0x2000, v176
	v_add_u32_e32 v178, 0x20000, v178
	s_waitcnt lgkmcnt(2)
	v_mfma_scale_f32_32x32x64_f8f6f4 v[18:33], v[246:253], v[106:113], v[18:33], v194, v194 op_sel_hi:[0,0,0]
	s_waitcnt lgkmcnt(0)
	v_mfma_scale_f32_32x32x64_f8f6f4 v[2:17], v[246:253], v[98:105], v[2:17], v194, v194 op_sel_hi:[0,0,0]
	ds_read_b128 v[114:117], v215 offset:24576
	ds_read_b128 v[118:121], v216 offset:24576
	ds_read_b128 v[222:225], v215 offset:28672
	ds_read_b128 v[226:229], v216 offset:28672
	v_max_f32_e32 v0, v66, v67
	v_max3_f32 v0, v0, v68, v69
	v_max3_f32 v0, v0, v70, v71
	v_max3_f32 v0, v0, v72, v73
	v_max3_f32 v0, v0, v74, v75
	v_max3_f32 v0, v0, v76, v77
	v_max3_f32 v0, v0, v78, v79
	v_max3_f32 v0, v0, v80, v81
	v_max_f32_e32 v177, v177, v0
	v_mov_b32_e32 v0, v177
	v_mov_b32_e32 v218, 1.0
	s_nop 0
	v_permlane32_swap_b32_e32 v177, v0
	v_max_f32_e32 v177, v177, v0
	v_cmp_ge_f32_e32 vcc, s90, v177
	s_cmp_eq_u64 vcc, exec
	s_cbranch_scc0 .Lmla_s5_newmax
; __device__ __forceinline__ void finishSM9(f32x16& p0, f32x16& p1, float alpha, float& l_reg, v8i32& p8) {
; #pragma unroll
;   for (int r = 0; r < 16; ++r) { p0[r] = __builtin_amdgcn_exp2f(p0[r]); p1[r] = __builtin_amdgcn_exp2f(p1[r]); }
;   float ps = 0;
; #pragma unroll
;   for (int r = 0; r < 16; ++r) ps += p0[r];
; #pragma unroll
;   for (int r = 0; r < 16; ++r) ps += p1[r];
;   { auto rr = __builtin_amdgcn_permlane32_swap(__float_as_uint(ps), __float_as_uint(ps), false, false);
;     ps = __uint_as_float(rr[0]) + __uint_as_float(rr[1]); }
;   l_reg = l_reg * alpha + ps;
; #pragma unroll
;   for (int g = 0; g < 4; ++g) {
;     int w = __builtin_amdgcn_cvt_pk_fp8_f32(p0[4 * g], p0[4 * g + 1], 0, false); p8[g] = __builtin_amdgcn_cvt_pk_fp8_f32(p0[4 * g + 2], p0[4 * g + 3], w, true);
;     int u = __builtin_amdgcn_cvt_pk_fp8_f32(p1[4 * g], p1[4 * g + 1], 0, false); p8[4 + g] = __builtin_amdgcn_cvt_pk_fp8_f32(p1[4 * g + 2], p1[4 * g + 3], u, true); }
; }
; __device__ __forceinline__ void pv8(f32x16* o, const char* Vt, const v8i32 p8, int r32, int hi) {
;   const int sw = (r32 >> 2) & 3, a0 = r32 * 64 + (((hi * 2) ^ sw) << 4), a1 = r32 * 64 + (((hi * 2 + 1) ^ sw) << 4);
; #pragma unroll
;   for (int d0 = 0; d0 < 4; ++d0) {
;     const v8i32 vf = cat8(*reinterpret_cast<const v4i32*>(Vt + d0 * 2048 + a0), *reinterpret_cast<const v4i32*>(Vt + d0 * 2048 + a1));
;     o[d0] = __builtin_amdgcn_mfma_scale_f32_32x32x64_f8f6f4(p8, vf, o[d0], 0, 0, 0, 127, 0, 127); }
; }
; __device__ __forceinline__ void qkt9(f32x16& p0, f32x16& p1, const char* Kn, const char* Kr, const v8i32* qf, const float init, int r32, int hi) {
; #pragma unroll
;   for (int r = 0; r < 16; ++r) { p0[r] = init; p1[r] = init; }
; #pragma unroll
;   for (int s = 0; s < 2; ++s) { const int c0 = s * 4 + hi * 2;
;     const v8i32 a0 = cat8(*reinterpret_cast<const v4i32*>(Kn + KN8SW(r32, c0)), *reinterpret_cast<const v4i32*>(Kn + KN8SW(r32, c0 + 1)));
;     const v8i32 a1 = cat8(*reinterpret_cast<const v4i32*>(Kn + 4096 + KN8SW(r32, c0)), *reinterpret_cast<const v4i32*>(Kn + 4096 + KN8SW(r32, c0 + 1)));
;     p0 = __builtin_amdgcn_mfma_scale_f32_32x32x64_f8f6f4(a0, qf[s], p0, 0, 0, 0, 127, 0, 124);
;     p1 = __builtin_amdgcn_mfma_scale_f32_32x32x64_f8f6f4(a1, qf[s], p1, 0, 0, 0, 127, 0, 124); }
;   { const int c0 = hi * 2;
.Lmla_s5_cont:
	s_add_i32 s30, s30, 1
	s_cmpk_lt_u32 s30, 42
	s_cbranch_scc1 .Lmla_stag_loop
	v_exp_f32_e32 v0, v82
	v_exp_f32_e32 v177, v83
	v_exp_f32_e32 v179, v84
	v_exp_f32_e32 v254, v85
	v_add_f32_e32 v219, v0, v177
	v_cvt_pk_fp8_f32 v246, v0, v177
	v_add_f32_e32 v219, v179, v219
	v_add_f32_e32 v219, v254, v219
	v_cvt_pk_fp8_f32 v246, v179, v254 op_sel:[0,0,1]
	s_waitcnt lgkmcnt(2)
	v_mfma_scale_f32_32x32x64_f8f6f4 v[114:129], v[114:121], v[146:153], v[230:245], v194, v193 op_sel_hi:[0,0,0]
	v_exp_f32_e32 v0, v86
	v_exp_f32_e32 v177, v87
	v_exp_f32_e32 v179, v88
	v_exp_f32_e32 v254, v89
	v_add_f32_e32 v219, v0, v219
	v_add_f32_e32 v219, v177, v219
	v_cvt_pk_fp8_f32 v247, v0, v177
	v_add_f32_e32 v219, v179, v219
	v_add_f32_e32 v219, v254, v219
	v_cvt_pk_fp8_f32 v247, v179, v254 op_sel:[0,0,1]
	ds_read_b128 v[82:85], v213 offset:24576
	ds_read_b128 v[86:89], v214 offset:24576
	s_waitcnt lgkmcnt(2)
	v_mfma_scale_f32_32x32x64_f8f6f4 v[98:113], v[222:229], v[146:153], v[230:245], v194, v193 op_sel_hi:[0,0,0]
	ds_read_b128 v[222:225], v213 offset:28672
	ds_read_b128 v[226:229], v214 offset:28672
	v_exp_f32_e32 v0, v90
	v_exp_f32_e32 v177, v91
	v_exp_f32_e32 v179, v92
	v_exp_f32_e32 v254, v93
	v_add_f32_e32 v219, v0, v219
	v_add_f32_e32 v219, v177, v219
	v_cvt_pk_fp8_f32 v248, v0, v177
	v_add_f32_e32 v219, v179, v219
	v_add_f32_e32 v219, v254, v219
	v_cvt_pk_fp8_f32 v248, v179, v254 op_sel:[0,0,1]
	v_exp_f32_e32 v0, v94
	v_exp_f32_e32 v177, v95
	v_exp_f32_e32 v179, v96
	v_exp_f32_e32 v254, v97
	v_add_f32_e32 v219, v0, v219
	v_add_f32_e32 v219, v177, v219
	v_cvt_pk_fp8_f32 v249, v0, v177
	v_add_f32_e32 v219, v179, v219
	v_add_f32_e32 v219, v254, v219
	v_cvt_pk_fp8_f32 v249, v179, v254 op_sel:[0,0,1]
	ds_read_b128 v[90:93], v185 offset:36864
	ds_read_b128 v[94:97], v186 offset:36864
	s_waitcnt lgkmcnt(4)
	v_mfma_scale_f32_32x32x64_f8f6f4 v[114:129], v[82:89], v[138:145], v[114:129], v194, v193 op_sel_hi:[0,0,0]
	v_exp_f32_e32 v0, v66
	v_exp_f32_e32 v177, v67
	v_exp_f32_e32 v179, v68
	v_exp_f32_e32 v254, v69
	v_add_f32_e32 v219, v0, v219
	v_add_f32_e32 v219, v177, v219
	v_cvt_pk_fp8_f32 v250, v0, v177
	v_add_f32_e32 v219, v179, v219
	v_add_f32_e32 v219, v254, v219
	v_cvt_pk_fp8_f32 v250, v179, v254 op_sel:[0,0,1]
	s_waitcnt lgkmcnt(2)
	v_mfma_scale_f32_32x32x64_f8f6f4 v[98:113], v[222:229], v[138:145], v[98:113], v194, v193 op_sel_hi:[0,0,0]
	ds_read_b128 v[222:225], v185 offset:38912
	ds_read_b128 v[226:229], v186 offset:38912
	v_exp_f32_e32 v0, v70
	v_exp_f32_e32 v177, v71
	v_exp_f32_e32 v179, v72
	v_exp_f32_e32 v254, v73
	v_add_f32_e32 v219, v0, v219
	v_add_f32_e32 v219, v177, v219
	v_cvt_pk_fp8_f32 v251, v0, v177
	v_add_f32_e32 v219, v179, v219
	v_add_f32_e32 v219, v254, v219
	v_cvt_pk_fp8_f32 v251, v179, v254 op_sel:[0,0,1]
	v_exp_f32_e32 v0, v74
	v_exp_f32_e32 v177, v75
	v_exp_f32_e32 v179, v76
	v_exp_f32_e32 v254, v77
	v_add_f32_e32 v219, v0, v219
	v_add_f32_e32 v219, v177, v219
	v_cvt_pk_fp8_f32 v252, v0, v177
	v_add_f32_e32 v219, v179, v219
	v_add_f32_e32 v219, v254, v219
	v_cvt_pk_fp8_f32 v252, v179, v254 op_sel:[0,0,1]
	s_waitcnt lgkmcnt(2)
	v_mfma_scale_f32_32x32x64_f8f6f4 v[114:129], v[90:97], v[130:137], v[114:129], v194, v193 op_sel_hi:[0,0,0]
	v_exp_f32_e32 v0, v78
	v_exp_f32_e32 v177, v79
	v_exp_f32_e32 v179, v80
	v_exp_f32_e32 v254, v81
	v_add_f32_e32 v219, v0, v219
	v_add_f32_e32 v219, v177, v219
	v_cvt_pk_fp8_f32 v253, v0, v177
	v_add_f32_e32 v219, v179, v219
	v_add_f32_e32 v219, v254, v219
	v_cvt_pk_fp8_f32 v253, v179, v254 op_sel:[0,0,1]
	ds_read_b128 v[90:93], v185 offset:0
	ds_read_b128 v[94:97], v186 offset:0
	ds_read_b128 v[82:85], v185 offset:2048
	ds_read_b128 v[86:89], v186 offset:2048
	ds_read_b128 v[74:77], v185 offset:4096
	ds_read_b128 v[78:81], v186 offset:4096
	ds_read_b128 v[66:69], v185 offset:6144
	ds_read_b128 v[70:73], v186 offset:6144
	s_waitcnt lgkmcnt(8)
	v_mfma_scale_f32_32x32x64_f8f6f4 v[98:113], v[222:229], v[130:137], v[98:113], v194, v193 op_sel_hi:[0,0,0]
	v_mov_b32_e32 v0, v219
	s_nop 1
	v_permlane32_swap_b32_e32 v219, v0
	v_add_f32_e32 v219, v219, v0
	v_fma_f32 v209, v209, v218, v219
	v_max_f32_e32 v177, v114, v115
	v_max3_f32 v177, v177, v116, v117
	v_max3_f32 v177, v177, v118, v119
	v_max3_f32 v177, v177, v120, v121
	v_max3_f32 v177, v177, v122, v123
	v_max3_f32 v177, v177, v124, v125
	v_max3_f32 v177, v177, v126, v127
	v_max3_f32 v177, v177, v128, v129
	s_waitcnt lgkmcnt(6)
	v_mfma_scale_f32_32x32x64_f8f6f4 v[50:65], v[246:253], v[90:97], v[50:65], v194, v194 op_sel_hi:[0,0,0]
	s_waitcnt vmcnt(0)
	ds_write_b128 v210, v[158:161] offset:43008
	ds_write_b128 v211, v[162:165] offset:51200
	s_waitcnt lgkmcnt(6)
	v_mfma_scale_f32_32x32x64_f8f6f4 v[34:49], v[246:253], v[82:89], v[34:49], v194, v194 op_sel_hi:[0,0,0]
	s_waitcnt lgkmcnt(0)
	s_barrier
	global_load_dwordx4 v[158:161], v176, s[18:19]
	global_load_dwordx4 v[162:165], v178, s[16:17]
	v_add_u32_e32 v176, 0x2000, v176
	v_add_u32_e32 v178, 0x20000, v178
	s_waitcnt lgkmcnt(2)
	v_mfma_scale_f32_32x32x64_f8f6f4 v[18:33], v[246:253], v[74:81], v[18:33], v194, v194 op_sel_hi:[0,0,0]
	s_waitcnt lgkmcnt(0)
	v_mfma_scale_f32_32x32x64_f8f6f4 v[2:17], v[246:253], v[66:73], v[2:17], v194, v194 op_sel_hi:[0,0,0]
	ds_read_b128 v[82:85], v215 offset:51200
	ds_read_b128 v[86:89], v216 offset:51200
	ds_read_b128 v[222:225], v215 offset:55296
	ds_read_b128 v[226:229], v216 offset:55296
	v_max_f32_e32 v0, v98, v99
	v_max3_f32 v0, v0, v100, v101
	v_max3_f32 v0, v0, v102, v103
	v_max3_f32 v0, v0, v104, v105
	v_max3_f32 v0, v0, v106, v107
	v_max3_f32 v0, v0, v108, v109
	v_max3_f32 v0, v0, v110, v111
	v_max3_f32 v0, v0, v112, v113
	v_max_f32_e32 v177, v177, v0
	v_mov_b32_e32 v0, v177
	v_mov_b32_e32 v221, 1.0
	s_nop 0
	v_permlane32_swap_b32_e32 v177, v0
	v_max_f32_e32 v177, v177, v0
	v_cmp_ge_f32_e32 vcc, s90, v177
	s_cmp_eq_u64 vcc, exec
	s_cbranch_scc0 .Lmla_q0_newmax
; __device__ __forceinline__ void finishSM9(f32x16& p0, f32x16& p1, float alpha, float& l_reg, v8i32& p8) {
; #pragma unroll
;   for (int r = 0; r < 16; ++r) { p0[r] = __builtin_amdgcn_exp2f(p0[r]); p1[r] = __builtin_amdgcn_exp2f(p1[r]); }
;   float ps = 0;
; #pragma unroll
;   for (int r = 0; r < 16; ++r) ps += p0[r];
; #pragma unroll
;   for (int r = 0; r < 16; ++r) ps += p1[r];
;   { auto rr = __builtin_amdgcn_permlane32_swap(__float_as_uint(ps), __float_as_uint(ps), false, false);
;     ps = __uint_as_float(rr[0]) + __uint_as_float(rr[1]); }
;   l_reg = l_reg * alpha + ps;
; #pragma unroll
;   for (int g = 0; g < 4; ++g) {
;     int w = __builtin_amdgcn_cvt_pk_fp8_f32(p0[4 * g], p0[4 * g + 1], 0, false); p8[g] = __builtin_amdgcn_cvt_pk_fp8_f32(p0[4 * g + 2], p0[4 * g + 3], w, true);
;     int u = __builtin_amdgcn_cvt_pk_fp8_f32(p1[4 * g], p1[4 * g + 1], 0, false); p8[4 + g] = __builtin_amdgcn_cvt_pk_fp8_f32(p1[4 * g + 2], p1[4 * g + 3], u, true); }
; }
; __device__ __forceinline__ void pv8(f32x16* o, const char* Vt, const v8i32 p8, int r32, int hi) {
;   const int sw = (r32 >> 2) & 3, a0 = r32 * 64 + (((hi * 2) ^ sw) << 4), a1 = r32 * 64 + (((hi * 2 + 1) ^ sw) << 4);
; #pragma unroll
;   for (int d0 = 0; d0 < 4; ++d0) {
;     const v8i32 vf = cat8(*reinterpret_cast<const v4i32*>(Vt + d0 * 2048 + a0), *reinterpret_cast<const v4i32*>(Vt + d0 * 2048 + a1));
;     o[d0] = __builtin_amdgcn_mfma_scale_f32_32x32x64_f8f6f4(p8, vf, o[d0], 0, 0, 0, 127, 0, 127); }
; }
; __device__ __forceinline__ void qkt9(f32x16& p0, f32x16& p1, const char* Kn, const char* Kr, const v8i32* qf, const float init, int r32, int hi) {
; #pragma unroll
;   for (int r = 0; r < 16; ++r) { p0[r] = init; p1[r] = init; }
; #pragma unroll
;   for (int s = 0; s < 2; ++s) { const int c0 = s * 4 + hi * 2;
;     const v8i32 a0 = cat8(*reinterpret_cast<const v4i32*>(Kn + KN8SW(r32, c0)), *reinterpret_cast<const v4i32*>(Kn + KN8SW(r32, c0 + 1)));
;     const v8i32 a1 = cat8(*reinterpret_cast<const v4i32*>(Kn + 4096 + KN8SW(r32, c0)), *reinterpret_cast<const v4i32*>(Kn + 4096 + KN8SW(r32, c0 + 1)));
;     p0 = __builtin_amdgcn_mfma_scale_f32_32x32x64_f8f6f4(a0, qf[s], p0, 0, 0, 0, 127, 0, 124);
;     p1 = __builtin_amdgcn_mfma_scale_f32_32x32x64_f8f6f4(a1, qf[s], p1, 0, 0, 0, 127, 0, 124); }
;   { const int c0 = hi * 2;
.Lmla_q0_cont:
	v_exp_f32_e32 v0, v114
	v_exp_f32_e32 v177, v115
	v_exp_f32_e32 v179, v116
	v_exp_f32_e32 v254, v117
	v_add_f32_e32 v219, v0, v177
	v_cvt_pk_fp8_f32 v246, v0, v177
	v_add_f32_e32 v219, v179, v219
	v_add_f32_e32 v219, v254, v219
	v_cvt_pk_fp8_f32 v246, v179, v254 op_sel:[0,0,1]
	s_waitcnt lgkmcnt(2)
	v_mfma_scale_f32_32x32x64_f8f6f4 v[82:97], v[82:89], v[146:153], v[230:245], v194, v193 op_sel_hi:[0,0,0]
	v_exp_f32_e32 v0, v118
	v_exp_f32_e32 v177, v119
	v_exp_f32_e32 v179, v120
	v_exp_f32_e32 v254, v121
	v_add_f32_e32 v219, v0, v219
	v_add_f32_e32 v219, v177, v219
	v_cvt_pk_fp8_f32 v247, v0, v177
	v_add_f32_e32 v219, v179, v219
	v_add_f32_e32 v219, v254, v219
	v_cvt_pk_fp8_f32 v247, v179, v254 op_sel:[0,0,1]
	ds_read_b128 v[114:117], v213 offset:51200
	ds_read_b128 v[118:121], v214 offset:51200
	s_waitcnt lgkmcnt(2)
	v_mfma_scale_f32_32x32x64_f8f6f4 v[66:81], v[222:229], v[146:153], v[230:245], v194, v193 op_sel_hi:[0,0,0]
	ds_read_b128 v[222:225], v213 offset:55296
	ds_read_b128 v[226:229], v214 offset:55296
	v_exp_f32_e32 v0, v122
	v_exp_f32_e32 v177, v123
	v_exp_f32_e32 v179, v124
	v_exp_f32_e32 v254, v125
	v_add_f32_e32 v219, v0, v219
	v_add_f32_e32 v219, v177, v219
	v_cvt_pk_fp8_f32 v248, v0, v177
	v_add_f32_e32 v219, v179, v219
	v_add_f32_e32 v219, v254, v219
	v_cvt_pk_fp8_f32 v248, v179, v254 op_sel:[0,0,1]
	v_exp_f32_e32 v0, v126
	v_exp_f32_e32 v177, v127
	v_exp_f32_e32 v179, v128
	v_exp_f32_e32 v254, v129
	v_add_f32_e32 v219, v0, v219
	v_add_f32_e32 v219, v177, v219
	v_cvt_pk_fp8_f32 v249, v0, v177
	v_add_f32_e32 v219, v179, v219
	v_add_f32_e32 v219, v254, v219
	v_cvt_pk_fp8_f32 v249, v179, v254 op_sel:[0,0,1]
	ds_read_b128 v[122:125], v185 offset:59392
	ds_read_b128 v[126:129], v186 offset:59392
	s_waitcnt lgkmcnt(4)
	v_mfma_scale_f32_32x32x64_f8f6f4 v[82:97], v[114:121], v[138:145], v[82:97], v194, v193 op_sel_hi:[0,0,0]
	v_exp_f32_e32 v0, v98
	v_exp_f32_e32 v177, v99
	v_exp_f32_e32 v179, v100
	v_exp_f32_e32 v254, v101
	v_add_f32_e32 v219, v0, v219
	v_add_f32_e32 v219, v177, v219
	v_cvt_pk_fp8_f32 v250, v0, v177
	v_add_f32_e32 v219, v179, v219
	v_add_f32_e32 v219, v254, v219
	v_cvt_pk_fp8_f32 v250, v179, v254 op_sel:[0,0,1]
	s_waitcnt lgkmcnt(2)
	v_mfma_scale_f32_32x32x64_f8f6f4 v[66:81], v[222:229], v[138:145], v[66:81], v194, v193 op_sel_hi:[0,0,0]
	ds_read_b128 v[222:225], v185 offset:61440
	ds_read_b128 v[226:229], v186 offset:61440
	v_exp_f32_e32 v0, v102
	v_exp_f32_e32 v177, v103
	v_exp_f32_e32 v179, v104
	v_exp_f32_e32 v254, v105
	v_add_f32_e32 v219, v0, v219
	v_add_f32_e32 v219, v177, v219
	v_cvt_pk_fp8_f32 v251, v0, v177
	v_add_f32_e32 v219, v179, v219
	v_add_f32_e32 v219, v254, v219
	v_cvt_pk_fp8_f32 v251, v179, v254 op_sel:[0,0,1]
	v_exp_f32_e32 v0, v106
	v_exp_f32_e32 v177, v107
	v_exp_f32_e32 v179, v108
	v_exp_f32_e32 v254, v109
	v_add_f32_e32 v219, v0, v219
	v_add_f32_e32 v219, v177, v219
	v_cvt_pk_fp8_f32 v252, v0, v177
	v_add_f32_e32 v219, v179, v219
	v_add_f32_e32 v219, v254, v219
	v_cvt_pk_fp8_f32 v252, v179, v254 op_sel:[0,0,1]
	s_waitcnt lgkmcnt(2)
	v_mfma_scale_f32_32x32x64_f8f6f4 v[82:97], v[122:129], v[130:137], v[82:97], v194, v193 op_sel_hi:[0,0,0]
	v_exp_f32_e32 v0, v110
	v_exp_f32_e32 v177, v111
	v_exp_f32_e32 v179, v112
	v_exp_f32_e32 v254, v113
	v_add_f32_e32 v219, v0, v219
	v_add_f32_e32 v219, v177, v219
	v_cvt_pk_fp8_f32 v253, v0, v177
	v_add_f32_e32 v219, v179, v219
	v_add_f32_e32 v219, v254, v219
	v_cvt_pk_fp8_f32 v253, v179, v254 op_sel:[0,0,1]
	ds_read_b128 v[122:125], v185 offset:8192
	ds_read_b128 v[126:129], v186 offset:8192
	ds_read_b128 v[114:117], v185 offset:10240
	ds_read_b128 v[118:121], v186 offset:10240
	ds_read_b128 v[106:109], v185 offset:12288
	ds_read_b128 v[110:113], v186 offset:12288
	ds_read_b128 v[98:101], v185 offset:14336
	ds_read_b128 v[102:105], v186 offset:14336
	s_waitcnt lgkmcnt(8)
	v_mfma_scale_f32_32x32x64_f8f6f4 v[66:81], v[222:229], v[130:137], v[66:81], v194, v193 op_sel_hi:[0,0,0]
	v_mov_b32_e32 v0, v219
	s_nop 1
	v_permlane32_swap_b32_e32 v219, v0
	v_add_f32_e32 v219, v219, v0
	v_fma_f32 v209, v209, v221, v219
	v_max_f32_e32 v177, v82, v83
	v_max3_f32 v177, v177, v84, v85
	v_max3_f32 v177, v177, v86, v87
	v_max3_f32 v177, v177, v88, v89
	v_max3_f32 v177, v177, v90, v91
	v_max3_f32 v177, v177, v92, v93
	v_max3_f32 v177, v177, v94, v95
	v_max3_f32 v177, v177, v96, v97
	s_waitcnt lgkmcnt(6)
	v_mfma_scale_f32_32x32x64_f8f6f4 v[50:65], v[246:253], v[122:129], v[50:65], v194, v194 op_sel_hi:[0,0,0]
	s_waitcnt vmcnt(0)
	ds_write_b128 v210, v[158:161]
	ds_write_b128 v211, v[162:165] offset:16384
	s_waitcnt lgkmcnt(6)
	v_mfma_scale_f32_32x32x64_f8f6f4 v[34:49], v[246:253], v[114:121], v[34:49], v194, v194 op_sel_hi:[0,0,0]
	s_waitcnt lgkmcnt(0)
	s_barrier
	s_waitcnt lgkmcnt(2)
	v_mfma_scale_f32_32x32x64_f8f6f4 v[18:33], v[246:253], v[106:113], v[18:33], v194, v194 op_sel_hi:[0,0,0]
	s_waitcnt lgkmcnt(0)
	v_mfma_scale_f32_32x32x64_f8f6f4 v[2:17], v[246:253], v[98:105], v[2:17], v194, v194 op_sel_hi:[0,0,0]
	v_max_f32_e32 v0, v66, v67
	v_max3_f32 v0, v0, v68, v69
	v_max3_f32 v0, v0, v70, v71
	v_max3_f32 v0, v0, v72, v73
	v_max3_f32 v0, v0, v74, v75
	v_max3_f32 v0, v0, v76, v77
	v_max3_f32 v0, v0, v78, v79
	v_max3_f32 v0, v0, v80, v81
	v_max_f32_e32 v177, v177, v0
	v_mov_b32_e32 v0, v177
	v_mov_b32_e32 v218, 1.0
	s_nop 0
	v_permlane32_swap_b32_e32 v177, v0
	v_max_f32_e32 v177, v177, v0
	v_cmp_ge_f32_e32 vcc, s90, v177
	s_cmp_eq_u64 vcc, exec
	s_cbranch_scc0 .Lmla_q1_newmax
